# f32->bf16 conversions in epilogues: integer RNE sequence (bfe+add3+perm) replaced by v_cvt_pk_bf16_f32 (same rounding) in inproj, mix and phase0 code
# speedup vs baseline: 1.0181x; 1.0098x over previous
.LBB0_34:
	s_andn2_b64 vcc, exec, s[24:25]
	s_cbranch_vccnz .LBB0_36
	s_add_i32 s22, s90, 0xffffef00
	s_lshr_b32 s22, s22, 4
	s_lshl_b64 s[24:25], s[22:23], 18
	s_add_u32 s27, s38, s24
	s_addc_u32 s29, s39, s25
	s_lshl_b64 s[24:25], s[22:23], 17
	s_add_u32 s24, s30, s24
	s_addc_u32 s25, s31, s25
	s_lshl_b32 s26, s90, 6
	s_lshl_b32 s22, s90, 4
	s_and_b32 s26, s26, 0xc0
	s_and_b32 s22, s22, 0xc0
	s_lshl_b32 s28, s26, 2
	s_add_u32 s28, s27, s28
	s_addc_u32 s29, s29, 0
	v_mov_b32_e32 v25, v11
	v_or_b32_e32 v2, s22, v128
	v_lshl_add_u64 v[42:43], s[28:29], 0, v[24:25]
	v_lshlrev_b32_e32 v10, 10, v2
	v_lshl_add_u64 v[2:3], v[42:43], 0, v[10:11]
	v_add_lshl_u32 v10, s22, v34, 10
	v_lshl_add_u64 v[6:7], v[42:43], 0, v[10:11]
	global_load_dwordx4 v[2:5], v[2:3], off nt
	s_nop 0
	global_load_dwordx4 v[6:9], v[6:7], off nt
	v_add_lshl_u32 v10, s22, v35, 10
	v_lshl_add_u64 v[38:39], v[42:43], 0, v[10:11]
	global_load_dwordx4 v[38:41], v[38:39], off nt
	v_add_lshl_u32 v10, s22, v36, 10
	v_lshl_add_u64 v[42:43], v[42:43], 0, v[10:11]
	global_load_dwordx4 v[42:45], v[42:43], off nt
	v_add_u32_e32 v25, v12, v33
	v_add_u32_e32 v48, 0x800, v37
	v_add_u32_e32 v49, 0x400, v37
	v_add_u32_e32 v50, 0xc00, v37
	v_add_u32_e32 v51, 0x1040, v25
	v_add_u32_e32 v52, 0x1048, v25
	v_add_u32_e32 v53, 0x2080, v25
	v_add_u32_e32 v54, 0x2088, v25
	v_add_u32_e32 v55, 0x30c0, v25
	v_add_u32_e32 v56, 0x30c8, v25
	v_add_lshl_u32 v10, s26, v154, 9
	s_lshl_b32 s22, s22, 1
	v_lshl_add_u64 v[46:47], s[24:25], 0, v[10:11]
	v_lshlrev_b32_e32 v10, 1, v14
	v_lshl_add_u64 v[46:47], v[46:47], 0, s[22:23]
	s_waitcnt vmcnt(3)
	ds_write2_b32 v25, v2, v3 offset1:1
	ds_write2_b32 v25, v4, v5 offset0:2 offset1:3
	s_waitcnt vmcnt(2)
	ds_write2_b32 v51, v6, v7 offset1:1
	ds_write2_b32 v52, v8, v9 offset1:1
	s_waitcnt vmcnt(1)
	ds_write2_b32 v53, v38, v39 offset1:1
	ds_write2_b32 v54, v40, v41 offset1:1
	s_waitcnt vmcnt(0)
	ds_write2_b32 v55, v42, v43 offset1:1
	ds_write2_b32 v56, v44, v45 offset1:1
	s_waitcnt lgkmcnt(0)
	s_barrier
	ds_read2_b32 v[2:3], v37 offset1:65
	ds_read2_b32 v[4:5], v48 offset0:8 offset1:73
	ds_read2_b32 v[6:7], v37 offset0:130 offset1:195
	ds_read2_b32 v[8:9], v49 offset0:134 offset1:199
	ds_read2_b32 v[38:39], v48 offset0:138 offset1:203
	ds_read2_b32 v[40:41], v49 offset0:4 offset1:69
	ds_read2_b32 v[42:43], v50 offset0:12 offset1:77
	ds_read2_b32 v[44:45], v50 offset0:142 offset1:207
	s_waitcnt lgkmcnt(4)
	s_waitcnt lgkmcnt(2)
	v_bfe_u32 v49, v41, 16, 1
	v_bfe_u32 v50, v40, 16, 1
	v_bfe_u32 v51, v7, 16, 1
	v_bfe_u32 v52, v6, 16, 1
	v_bfe_u32 v53, v3, 16, 1
	v_bfe_u32 v54, v2, 16, 1
	s_waitcnt lgkmcnt(0)
	v_bfe_u32 v61, v5, 16, 1
	v_bfe_u32 v62, v4, 16, 1
	v_add3_u32 v2, v2, v54, s33
	v_add3_u32 v53, v3, v53, s33
	v_add3_u32 v3, v6, v52, s33
	v_add3_u32 v6, v7, v51, s33
	v_add3_u32 v7, v40, v50, s33
	v_add3_u32 v40, v41, v49, s33
	v_add3_u32 v25, v4, v62, s33
	v_add3_u32 v41, v5, v61, s33
	v_cvt_pk_bf16_f32 v5, v8, v9
	v_perm_b32 v4, v40, v7, s87
	v_perm_b32 v3, v6, v3, s87
	v_perm_b32 v2, v53, v2, s87
	v_cvt_pk_bf16_f32 v7, v38, v39
	v_lshl_add_u64 v[38:39], v[46:47], 0, v[10:11]
	v_cvt_pk_bf16_f32 v9, v44, v45
	v_cvt_pk_bf16_f32 v8, v42, v43
	v_perm_b32 v6, v41, v25, s87
	global_store_dwordx4 v[38:39], v[2:5], off
	global_store_dwordx4 v[38:39], v[6:9], off offset:16
	s_barrier

.LBB0_37:
	s_andn2_b64 vcc, exec, s[24:25]
	s_cbranch_vccnz .LBB0_39
	s_lshl_b32 s22, s90, 2
	s_add_i32 s22, s22, 0x3c400
	s_and_b32 s24, s22, 0x3ffc0
	s_lshl_b32 s22, s90, 6
	s_and_b32 s25, s22, 0x3c0
	s_lshl_b32 s22, s25, 2
	v_or_b32_e32 v2, s24, v128
	v_lshl_add_u64 v[42:43], v[16:17], 0, s[22:23]
	v_lshlrev_b32_e32 v10, 12, v2
	v_lshl_add_u64 v[2:3], v[42:43], 0, v[10:11]
	v_add_lshl_u32 v10, s24, v34, 12
	v_lshl_add_u64 v[6:7], v[42:43], 0, v[10:11]
	global_load_dwordx4 v[2:5], v[2:3], off nt
	s_nop 0
	global_load_dwordx4 v[6:9], v[6:7], off nt
	v_add_lshl_u32 v10, s24, v35, 12
	v_lshl_add_u64 v[38:39], v[42:43], 0, v[10:11]
	global_load_dwordx4 v[38:41], v[38:39], off nt
	v_add_lshl_u32 v10, s24, v36, 12
	v_lshl_add_u64 v[42:43], v[42:43], 0, v[10:11]
	global_load_dwordx4 v[42:45], v[42:43], off nt
	v_add_u32_e32 v25, v12, v33
	v_add_u32_e32 v48, 0x800, v37
	v_add_u32_e32 v49, 0x400, v37
	v_add_u32_e32 v50, 0xc00, v37
	v_add_u32_e32 v51, 0x1040, v25
	v_add_u32_e32 v52, 0x1048, v25
	v_add_u32_e32 v53, 0x2080, v25
	v_add_u32_e32 v54, 0x2088, v25
	v_add_u32_e32 v55, 0x30c0, v25
	v_add_u32_e32 v56, 0x30c8, v25
	v_add_lshl_u32 v10, s25, v154, 12
	s_lshl_b32 s22, s24, 1
	v_lshl_add_u64 v[46:47], s[14:15], 0, v[10:11]
	v_lshlrev_b32_e32 v10, 1, v14
	v_lshl_add_u64 v[46:47], v[46:47], 0, s[22:23]
	v_lshl_add_u64 v[46:47], v[46:47], 0, v[10:11]
	s_waitcnt vmcnt(3)
	ds_write2_b32 v25, v2, v3 offset1:1
	ds_write2_b32 v25, v4, v5 offset0:2 offset1:3
	s_waitcnt vmcnt(2)
	ds_write2_b32 v51, v6, v7 offset1:1
	ds_write2_b32 v52, v8, v9 offset1:1
	s_waitcnt vmcnt(1)
	ds_write2_b32 v53, v38, v39 offset1:1
	ds_write2_b32 v54, v40, v41 offset1:1
	s_waitcnt vmcnt(0)
	ds_write2_b32 v55, v42, v43 offset1:1
	ds_write2_b32 v56, v44, v45 offset1:1
	s_waitcnt lgkmcnt(0)
	s_barrier
	ds_read2_b32 v[2:3], v37 offset1:65
	ds_read2_b32 v[4:5], v48 offset0:8 offset1:73
	ds_read2_b32 v[6:7], v37 offset0:130 offset1:195
	ds_read2_b32 v[8:9], v49 offset0:134 offset1:199
	ds_read2_b32 v[38:39], v48 offset0:138 offset1:203
	ds_read2_b32 v[40:41], v49 offset0:4 offset1:69
	ds_read2_b32 v[42:43], v50 offset0:12 offset1:77
	ds_read2_b32 v[44:45], v50 offset0:142 offset1:207
	s_waitcnt lgkmcnt(4)
	s_waitcnt lgkmcnt(2)
	v_bfe_u32 v48, v41, 16, 1
	v_bfe_u32 v49, v40, 16, 1
	v_bfe_u32 v50, v7, 16, 1
	v_bfe_u32 v51, v6, 16, 1
	v_bfe_u32 v52, v3, 16, 1
	v_bfe_u32 v53, v2, 16, 1
	s_waitcnt lgkmcnt(0)
	v_bfe_u32 v54, v45, 16, 1
	v_bfe_u32 v55, v44, 16, 1
	v_bfe_u32 v56, v43, 16, 1
	v_bfe_u32 v57, v42, 16, 1
	v_bfe_u32 v60, v5, 16, 1
	v_bfe_u32 v61, v4, 16, 1
	v_add3_u32 v2, v2, v53, s33
	v_add3_u32 v52, v3, v52, s33
	v_add3_u32 v3, v6, v51, s33
	v_add3_u32 v6, v7, v50, s33
	v_add3_u32 v7, v40, v49, s33
	v_add3_u32 v40, v41, v48, s33
	v_add3_u32 v10, v4, v61, s33
	v_add3_u32 v25, v5, v60, s33
	v_add3_u32 v41, v42, v57, s33
	v_add3_u32 v42, v43, v56, s33
	v_add3_u32 v43, v44, v55, s33
	v_add3_u32 v44, v45, v54, s33
	v_cvt_pk_bf16_f32 v5, v8, v9
	v_perm_b32 v4, v40, v7, s87
	v_perm_b32 v3, v6, v3, s87
	v_perm_b32 v2, v52, v2, s87
	v_perm_b32 v9, v44, v43, s87
	v_perm_b32 v8, v42, v41, s87
	v_cvt_pk_bf16_f32 v7, v38, v39
	v_perm_b32 v6, v25, v10, s87
	global_store_dwordx4 v[46:47], v[2:5], off
	global_store_dwordx4 v[46:47], v[6:9], off offset:16
	s_barrier

.LBB0_40:
	s_andn2_b64 vcc, exec, s[24:25]
	s_cbranch_vccnz .LBB0_42
	s_add_i32 s22, s90, 0xf700
	s_and_b32 s24, s22, 0xffff
	s_mul_i32 s24, s24, 0xaaab
	s_lshr_b32 s25, s24, 22
	s_mulk_i32 s25, 0x60
	s_lshr_b32 s24, s24, 16
	s_sub_i32 s22, s22, s25
	s_and_b32 s24, s24, 0xffc0
	s_lshl_b32 s22, s22, 6
	s_and_b32 s25, s22, 0xffc0
	v_or_b32_e32 v2, s24, v128
	s_lshl_b32 s22, s25, 2
	v_mul_u32_u24_e32 v2, 0x1800, v2
	v_add_u32_e32 v4, s24, v34
	v_lshl_add_u64 v[42:43], v[18:19], 0, s[22:23]
	v_lshlrev_b32_e32 v10, 2, v2
	v_mul_u32_u24_e32 v4, 0x1800, v4
	v_lshl_add_u64 v[2:3], v[42:43], 0, v[10:11]
	v_lshlrev_b32_e32 v10, 2, v4
	v_lshl_add_u64 v[6:7], v[42:43], 0, v[10:11]
	v_add_u32_e32 v10, s24, v35
	global_load_dwordx4 v[2:5], v[2:3], off nt
	s_nop 0
	global_load_dwordx4 v[6:9], v[6:7], off nt
	v_mul_u32_u24_e32 v10, 0x1800, v10
	v_lshlrev_b32_e32 v10, 2, v10
	v_lshl_add_u64 v[38:39], v[42:43], 0, v[10:11]
	v_add_u32_e32 v10, s24, v36
	v_mul_u32_u24_e32 v10, 0x1800, v10
	global_load_dwordx4 v[38:41], v[38:39], off nt
	v_lshlrev_b32_e32 v10, 2, v10
	v_lshl_add_u64 v[42:43], v[42:43], 0, v[10:11]
	global_load_dwordx4 v[42:45], v[42:43], off nt
	v_add_u32_e32 v25, v12, v33
	v_add_u32_e32 v46, 0x800, v37
	v_add_u32_e32 v47, 0x400, v37
	v_add_u32_e32 v48, 0xc00, v37
	v_add_u32_e32 v49, 0x1040, v25
	v_add_u32_e32 v50, 0x1048, v25
	v_add_u32_e32 v51, 0x2080, v25
	v_add_u32_e32 v52, 0x2088, v25
	v_add_u32_e32 v53, 0x30c0, v25
	v_add_u32_e32 v54, 0x30c8, v25
	v_add_lshl_u32 v10, v154, s25, 11
	s_lshl_b32 s22, s24, 1
	s_waitcnt vmcnt(3)
	ds_write2_b32 v25, v2, v3 offset1:1
	ds_write2_b32 v25, v4, v5 offset0:2 offset1:3
	s_waitcnt vmcnt(2)
	ds_write2_b32 v49, v6, v7 offset1:1
	ds_write2_b32 v50, v8, v9 offset1:1
	s_waitcnt vmcnt(1)
	ds_write2_b32 v51, v38, v39 offset1:1
	ds_write2_b32 v52, v40, v41 offset1:1
	s_waitcnt vmcnt(0)
	ds_write2_b32 v53, v42, v43 offset1:1
	ds_write2_b32 v54, v44, v45 offset1:1
	s_waitcnt lgkmcnt(0)
	s_barrier
	ds_read2_b32 v[2:3], v37 offset1:65
	ds_read2_b32 v[4:5], v46 offset0:8 offset1:73
	ds_read2_b32 v[6:7], v37 offset0:130 offset1:195
	ds_read2_b32 v[8:9], v47 offset0:134 offset1:199
	ds_read2_b32 v[38:39], v46 offset0:138 offset1:203
	ds_read2_b32 v[40:41], v47 offset0:4 offset1:69
	ds_read2_b32 v[42:43], v48 offset0:12 offset1:77
	ds_read2_b32 v[44:45], v48 offset0:142 offset1:207
	s_waitcnt lgkmcnt(5)
	v_bfe_u32 v49, v7, 16, 1
	v_bfe_u32 v50, v6, 16, 1
	s_waitcnt lgkmcnt(2)
	v_bfe_u32 v47, v41, 16, 1
	v_bfe_u32 v48, v40, 16, 1
	v_bfe_u32 v51, v3, 16, 1
	v_bfe_u32 v60, v4, 16, 1
	v_add3_u32 v51, v3, v51, s33
	v_add3_u32 v3, v6, v50, s33
	v_add3_u32 v6, v7, v49, s33
	v_add3_u32 v7, v40, v48, s33
	v_add3_u32 v40, v41, v47, s33
	v_bfe_u32 v52, v2, 16, 1
	v_add3_u32 v25, v4, v60, s33
	v_perm_b32 v4, v40, v7, s87
	v_cvt_pk_bf16_f32 v7, v38, v39
	v_lshl_add_u64 v[38:39], s[50:51], 0, v[10:11]
	s_waitcnt lgkmcnt(0)
	v_bfe_u32 v59, v5, 16, 1
	v_add3_u32 v2, v2, v52, s33
	v_lshl_add_u64 v[38:39], v[38:39], 0, s[22:23]
	v_lshlrev_b32_e32 v10, 1, v14
	v_add3_u32 v41, v5, v59, s33
	v_cvt_pk_bf16_f32 v5, v8, v9
	v_perm_b32 v3, v6, v3, s87
	v_perm_b32 v2, v51, v2, s87
	v_lshl_add_u64 v[38:39], v[38:39], 0, v[10:11]
	v_cvt_pk_bf16_f32 v9, v44, v45
	v_cvt_pk_bf16_f32 v8, v42, v43
	v_perm_b32 v6, v41, v25, s87
	global_store_dwordx4 v[38:39], v[2:5], off
	global_store_dwordx4 v[38:39], v[6:9], off offset:16
	s_barrier

.LBB0_43:
	s_andn2_b64 vcc, exec, s[24:25]
	s_cbranch_vccnz .LBB0_45
	s_lshl_b32 s22, s90, 2
	s_add_i32 s22, s22, 0x3e400
	s_and_b32 s24, s22, 0x3ffc0
	s_lshl_b32 s22, s90, 6
	s_and_b32 s25, s22, 0x3c0
	s_lshl_b32 s22, s25, 2
	v_or_b32_e32 v2, s24, v128
	v_lshl_add_u64 v[42:43], v[20:21], 0, s[22:23]
	v_lshlrev_b32_e32 v10, 12, v2
	v_lshl_add_u64 v[2:3], v[42:43], 0, v[10:11]
	v_add_lshl_u32 v10, s24, v34, 12
	v_lshl_add_u64 v[6:7], v[42:43], 0, v[10:11]
	global_load_dwordx4 v[2:5], v[2:3], off nt
	s_nop 0
	global_load_dwordx4 v[6:9], v[6:7], off nt
	v_add_lshl_u32 v10, s24, v35, 12
	v_lshl_add_u64 v[38:39], v[42:43], 0, v[10:11]
	global_load_dwordx4 v[38:41], v[38:39], off nt
	v_add_lshl_u32 v10, s24, v36, 12
	v_lshl_add_u64 v[42:43], v[42:43], 0, v[10:11]
	global_load_dwordx4 v[42:45], v[42:43], off nt
	v_add_u32_e32 v25, v12, v33
	v_add_u32_e32 v48, 0x800, v37
	v_add_u32_e32 v49, 0x400, v37
	v_add_u32_e32 v50, 0xc00, v37
	v_add_u32_e32 v51, 0x1040, v25
	v_add_u32_e32 v52, 0x1048, v25
	v_add_u32_e32 v53, 0x2080, v25
	v_add_u32_e32 v54, 0x2088, v25
	v_add_u32_e32 v55, 0x30c0, v25
	v_add_u32_e32 v56, 0x30c8, v25
	v_add_lshl_u32 v10, s25, v154, 12
	s_lshl_b32 s22, s24, 1
	v_lshl_add_u64 v[46:47], s[16:17], 0, v[10:11]
	v_lshlrev_b32_e32 v10, 1, v14
	v_lshl_add_u64 v[46:47], v[46:47], 0, s[22:23]
	v_lshl_add_u64 v[46:47], v[46:47], 0, v[10:11]
	s_waitcnt vmcnt(3)
	ds_write2_b32 v25, v2, v3 offset1:1
	ds_write2_b32 v25, v4, v5 offset0:2 offset1:3
	s_waitcnt vmcnt(2)
	ds_write2_b32 v51, v6, v7 offset1:1
	ds_write2_b32 v52, v8, v9 offset1:1
	s_waitcnt vmcnt(1)
	ds_write2_b32 v53, v38, v39 offset1:1
	ds_write2_b32 v54, v40, v41 offset1:1
	s_waitcnt vmcnt(0)
	ds_write2_b32 v55, v42, v43 offset1:1
	ds_write2_b32 v56, v44, v45 offset1:1
	s_waitcnt lgkmcnt(0)
	s_barrier
	ds_read2_b32 v[2:3], v37 offset1:65
	ds_read2_b32 v[4:5], v48 offset0:8 offset1:73
	ds_read2_b32 v[6:7], v37 offset0:130 offset1:195
	ds_read2_b32 v[8:9], v49 offset0:134 offset1:199
	ds_read2_b32 v[38:39], v48 offset0:138 offset1:203
	ds_read2_b32 v[40:41], v49 offset0:4 offset1:69
	ds_read2_b32 v[42:43], v50 offset0:12 offset1:77
	ds_read2_b32 v[44:45], v50 offset0:142 offset1:207
	s_waitcnt lgkmcnt(4)
	s_waitcnt lgkmcnt(2)
	v_bfe_u32 v48, v41, 16, 1
	v_bfe_u32 v49, v40, 16, 1
	v_bfe_u32 v50, v7, 16, 1
	v_bfe_u32 v51, v6, 16, 1
	v_bfe_u32 v52, v3, 16, 1
	v_bfe_u32 v53, v2, 16, 1
	s_waitcnt lgkmcnt(0)
	v_bfe_u32 v54, v45, 16, 1
	v_bfe_u32 v55, v44, 16, 1
	v_bfe_u32 v56, v43, 16, 1
	v_bfe_u32 v57, v42, 16, 1
	v_bfe_u32 v60, v5, 16, 1
	v_bfe_u32 v61, v4, 16, 1
	v_add3_u32 v2, v2, v53, s33
	v_add3_u32 v52, v3, v52, s33
	v_add3_u32 v3, v6, v51, s33
	v_add3_u32 v6, v7, v50, s33
	v_add3_u32 v7, v40, v49, s33
	v_add3_u32 v40, v41, v48, s33
	v_add3_u32 v10, v4, v61, s33
	v_add3_u32 v25, v5, v60, s33
	v_add3_u32 v41, v42, v57, s33
	v_add3_u32 v42, v43, v56, s33
	v_add3_u32 v43, v44, v55, s33
	v_add3_u32 v44, v45, v54, s33
	v_cvt_pk_bf16_f32 v5, v8, v9
	v_perm_b32 v4, v40, v7, s87
	v_perm_b32 v3, v6, v3, s87
	v_perm_b32 v2, v52, v2, s87
	v_perm_b32 v9, v44, v43, s87
	v_perm_b32 v8, v42, v41, s87
	v_cvt_pk_bf16_f32 v7, v38, v39
	v_perm_b32 v6, v25, v10, s87
	global_store_dwordx4 v[46:47], v[2:5], off
	global_store_dwordx4 v[46:47], v[6:9], off offset:16
	s_barrier

.LBB0_46:
	s_mul_hi_i32 s22, s90, 0x92492493
	s_add_i32 s22, s22, s90
	s_lshr_b32 s24, s22, 31
	s_ashr_i32 s22, s22, 6
	s_add_i32 s22, s22, s24
	s_lshl_b32 s24, s22, 6
	s_mulk_i32 s22, 0x70
	s_sub_i32 s22, s90, s22
	s_lshl_b32 s26, s22, 6
	s_ashr_i32 s27, s26, 31
	v_lshl_add_u64 v[42:43], s[26:27], 2, v[22:23]
	v_or_b32_e32 v2, s24, v128
	v_add_u32_e32 v4, s24, v34
	v_mad_i64_i32 v[2:3], s[28:29], v2, s88, v[42:43]
	v_mad_i64_i32 v[6:7], s[28:29], v4, s88, v[42:43]
	global_load_dwordx4 v[2:5], v[2:3], off nt
	s_nop 0
	global_load_dwordx4 v[6:9], v[6:7], off nt
	v_add_u32_e32 v10, s24, v35
	v_mad_i64_i32 v[38:39], s[28:29], v10, s88, v[42:43]
	global_load_dwordx4 v[38:41], v[38:39], off nt
	v_add_u32_e32 v10, s24, v36
	v_mad_i64_i32 v[42:43], s[28:29], v10, s88, v[42:43]
	global_load_dwordx4 v[42:45], v[42:43], off nt
	v_add_u32_e32 v10, v12, v33
	v_add_u32_e32 v25, 0x800, v37
	v_add_u32_e32 v48, 0x400, v37
	v_add_u32_e32 v49, 0xc00, v37
	v_add_u32_e32 v50, 0x1040, v10
	v_add_u32_e32 v51, 0x1048, v10
	v_add_u32_e32 v52, 0x2080, v10
	v_add_u32_e32 v53, 0x2088, v10
	v_add_u32_e32 v54, 0x30c0, v10
	v_add_u32_e32 v55, 0x30c8, v10
	v_add_u32_e32 v46, s26, v154
	v_ashrrev_i32_e32 v47, 31, v46
	s_ashr_i32 s25, s24, 31
	s_waitcnt vmcnt(3)
	ds_write2_b32 v10, v2, v3 offset1:1
	ds_write2_b32 v10, v4, v5 offset0:2 offset1:3
	s_waitcnt vmcnt(2)
	ds_write2_b32 v50, v6, v7 offset1:1
	ds_write2_b32 v51, v8, v9 offset1:1
	s_waitcnt vmcnt(1)
	ds_write2_b32 v52, v38, v39 offset1:1
	ds_write2_b32 v53, v40, v41 offset1:1
	s_waitcnt vmcnt(0)
	ds_write2_b32 v54, v42, v43 offset1:1
	ds_write2_b32 v55, v44, v45 offset1:1
	s_waitcnt lgkmcnt(0)
	s_barrier
	ds_read2_b32 v[2:3], v37 offset1:65
	ds_read2_b32 v[4:5], v25 offset0:8 offset1:73
	ds_read2_b32 v[6:7], v37 offset0:130 offset1:195
	ds_read2_b32 v[8:9], v48 offset0:134 offset1:199
	ds_read2_b32 v[38:39], v25 offset0:138 offset1:203
	ds_read2_b32 v[40:41], v48 offset0:4 offset1:69
	ds_read2_b32 v[42:43], v49 offset0:12 offset1:77
	ds_read2_b32 v[44:45], v49 offset0:142 offset1:207
	s_waitcnt lgkmcnt(5)
	v_bfe_u32 v50, v7, 16, 1
	v_bfe_u32 v51, v6, 16, 1
	s_waitcnt lgkmcnt(2)
	v_bfe_u32 v48, v41, 16, 1
	v_bfe_u32 v49, v40, 16, 1
	v_bfe_u32 v52, v3, 16, 1
	v_bfe_u32 v61, v4, 16, 1
	v_add3_u32 v52, v3, v52, s33
	v_add3_u32 v3, v6, v51, s33
	v_add3_u32 v6, v7, v50, s33
	v_add3_u32 v7, v40, v49, s33
	v_add3_u32 v40, v41, v48, s33
	v_bfe_u32 v60, v5, 16, 1
	v_add3_u32 v10, v4, v61, s33
	v_perm_b32 v4, v40, v7, s87
	v_cvt_pk_bf16_f32 v7, v38, v39
	v_lshlrev_b64 v[38:39], 11, v[46:47]
	v_bfe_u32 v53, v2, 16, 1
	v_add3_u32 v25, v5, v60, s33
	v_lshl_add_u64 v[38:39], s[18:19], 0, v[38:39]
	s_waitcnt lgkmcnt(0)
	v_bfe_u32 v54, v45, 16, 1
	v_bfe_u32 v55, v44, 16, 1
	v_bfe_u32 v56, v43, 16, 1
	v_bfe_u32 v57, v42, 16, 1
	v_add3_u32 v2, v2, v53, s33
	v_perm_b32 v3, v6, v3, s87
	v_perm_b32 v6, v25, v10, s87
	v_lshl_add_u64 v[38:39], s[24:25], 1, v[38:39]
	v_lshlrev_b32_e32 v10, 1, v14
	v_add3_u32 v41, v42, v57, s33
	v_add3_u32 v42, v43, v56, s33
	v_add3_u32 v43, v44, v55, s33
	v_add3_u32 v44, v45, v54, s33
	v_cvt_pk_bf16_f32 v5, v8, v9
	v_perm_b32 v2, v52, v2, s87
	v_lshl_add_u64 v[38:39], v[38:39], 0, v[10:11]
	v_perm_b32 v9, v44, v43, s87
	v_perm_b32 v8, v42, v41, s87
	global_store_dwordx4 v[38:39], v[2:5], off
	global_store_dwordx4 v[38:39], v[6:9], off offset:16
	s_barrier
	s_branch .LBB0_5

.LBB0_193:
	v_add_u32_e32 v14, 0x400, v162
	ds_write2_b32 v162, v64, v68 offset1:16
	ds_write2_b32 v162, v65, v69 offset0:128 offset1:144
	ds_write2_b32 v14, v66, v70 offset1:16
	ds_write2_b32 v14, v67, v71 offset0:128 offset1:144
	ds_write2_b32 v162, v72, v76 offset0:32 offset1:48
	ds_write2_b32 v162, v73, v77 offset0:160 offset1:176
	ds_write2_b32 v14, v74, v78 offset0:32 offset1:48
	ds_write2_b32 v14, v75, v79 offset0:160 offset1:176
	ds_write2_b32 v162, v80, v84 offset0:64 offset1:80
	ds_write2_b32 v162, v81, v85 offset0:192 offset1:208
	ds_write2_b32 v14, v82, v86 offset0:64 offset1:80
	ds_write2_b32 v14, v83, v87 offset0:192 offset1:208
	ds_write2st64_b32 v163, v88, v89 offset1:2
	ds_write2st64_b32 v163, v90, v91 offset0:4 offset1:6
	ds_write2st64_b32 v164, v92, v93 offset1:2
	ds_write2st64_b32 v164, v94, v95 offset0:4 offset1:6
	ds_read_b128 v[0:3], v161 offset:16
	ds_read_b128 v[4:7], v161
	s_waitcnt lgkmcnt(0)
	v_cvt_pk_bf16_f32 v3, v2, v3
	v_cvt_pk_bf16_f32 v2, v0, v1
	v_cvt_pk_bf16_f32 v1, v6, v7
	v_cvt_pk_bf16_f32 v0, v4, v5
	ds_read_b128 v[4:7], v166
	ds_read_b128 v[8:11], v166 offset:16
	v_mul_hi_u32_u24_e32 v13, s0, v165
	v_mul_u32_u24_e32 v12, s0, v165
	v_lshl_add_u64 v[12:13], v[12:13], 1, s[4:5]
	v_lshl_add_u64 v[12:13], v[12:13], 0, v[142:143]
	global_store_dwordx4 v[12:13], v[0:3], off
	s_waitcnt lgkmcnt(0)
	v_cvt_pk_bf16_f32 v3, v10, v11
	v_cvt_pk_bf16_f32 v2, v8, v9
	v_cvt_pk_bf16_f32 v1, v6, v7
	v_cvt_pk_bf16_f32 v0, v4, v5
	ds_read_b128 v[4:7], v168
	ds_read_b128 v[8:11], v168 offset:16
	v_mul_hi_u32_u24_e32 v13, s0, v167
	v_mul_u32_u24_e32 v12, s0, v167
	v_lshl_add_u64 v[12:13], v[12:13], 1, s[4:5]
	v_lshl_add_u64 v[12:13], v[12:13], 0, v[142:143]
	global_store_dwordx4 v[12:13], v[0:3], off
	s_waitcnt lgkmcnt(0)
	v_cvt_pk_bf16_f32 v3, v10, v11
	v_cvt_pk_bf16_f32 v2, v8, v9
	v_cvt_pk_bf16_f32 v1, v6, v7
	v_cvt_pk_bf16_f32 v0, v4, v5
	ds_read_b128 v[4:7], v170
	ds_read_b128 v[8:11], v170 offset:16
	v_mul_hi_u32_u24_e32 v13, s0, v169
	v_mul_u32_u24_e32 v12, s0, v169
	v_lshl_add_u64 v[12:13], v[12:13], 1, s[4:5]
	v_lshl_add_u64 v[12:13], v[12:13], 0, v[142:143]
	global_store_dwordx4 v[12:13], v[0:3], off
	s_waitcnt lgkmcnt(0)
	v_cvt_pk_bf16_f32 v3, v10, v11
	v_cvt_pk_bf16_f32 v0, v4, v5
	v_mul_hi_u32_u24_e32 v5, s0, v171
	v_mul_u32_u24_e32 v4, s0, v171
	v_lshl_add_u64 v[4:5], v[4:5], 1, s[4:5]
	v_cvt_pk_bf16_f32 v2, v8, v9
	v_cvt_pk_bf16_f32 v1, v6, v7
	v_lshl_add_u64 v[4:5], v[4:5], 0, v[142:143]
	global_store_dwordx4 v[4:5], v[0:3], off
	ds_write2_b32 v162, v96, v100 offset1:16
	ds_write2_b32 v162, v97, v101 offset0:128 offset1:144
	ds_write2_b32 v14, v98, v102 offset1:16
	ds_write2_b32 v14, v99, v103 offset0:128 offset1:144
	ds_write2_b32 v162, v104, v108 offset0:32 offset1:48
	ds_write2_b32 v162, v105, v109 offset0:160 offset1:176
	ds_write2_b32 v14, v106, v110 offset0:32 offset1:48
	ds_write2_b32 v14, v107, v111 offset0:160 offset1:176
	ds_write2_b32 v162, v112, v116 offset0:64 offset1:80
	ds_write2_b32 v162, v113, v117 offset0:192 offset1:208
	ds_write2_b32 v14, v114, v118 offset0:64 offset1:80
	ds_write2_b32 v14, v115, v119 offset0:192 offset1:208
	ds_write2st64_b32 v163, v120, v121 offset1:2
	ds_write2st64_b32 v163, v122, v123 offset0:4 offset1:6
	ds_write2st64_b32 v164, v124, v125 offset1:2
	ds_write2st64_b32 v164, v126, v127 offset0:4 offset1:6
	ds_read_b128 v[0:3], v161 offset:16
	ds_read_b128 v[4:7], v161
	s_waitcnt lgkmcnt(0)
	v_cvt_pk_bf16_f32 v3, v2, v3
	v_cvt_pk_bf16_f32 v2, v0, v1
	v_cvt_pk_bf16_f32 v1, v6, v7
	v_cvt_pk_bf16_f32 v0, v4, v5
	ds_read_b128 v[4:7], v166
	ds_read_b128 v[8:11], v166 offset:16
	v_mul_hi_u32_u24_e32 v13, s0, v172
	v_mul_u32_u24_e32 v12, s0, v172
	v_lshl_add_u64 v[12:13], v[12:13], 1, s[4:5]
	v_lshl_add_u64 v[12:13], v[12:13], 0, v[142:143]
	global_store_dwordx4 v[12:13], v[0:3], off
	s_waitcnt lgkmcnt(0)
	v_cvt_pk_bf16_f32 v3, v10, v11
	v_cvt_pk_bf16_f32 v2, v8, v9
	v_cvt_pk_bf16_f32 v1, v6, v7
	v_cvt_pk_bf16_f32 v0, v4, v5
	ds_read_b128 v[4:7], v168
	ds_read_b128 v[8:11], v168 offset:16
	v_mul_hi_u32_u24_e32 v13, s0, v173
	v_mul_u32_u24_e32 v12, s0, v173
	v_lshl_add_u64 v[12:13], v[12:13], 1, s[4:5]
	v_lshl_add_u64 v[12:13], v[12:13], 0, v[142:143]
	global_store_dwordx4 v[12:13], v[0:3], off
	s_waitcnt lgkmcnt(0)
	v_cvt_pk_bf16_f32 v3, v10, v11
	v_cvt_pk_bf16_f32 v2, v8, v9
	v_cvt_pk_bf16_f32 v1, v6, v7
	v_cvt_pk_bf16_f32 v0, v4, v5
	ds_read_b128 v[4:7], v170
	ds_read_b128 v[8:11], v170 offset:16
	v_mul_hi_u32_u24_e32 v13, s0, v174
	v_mul_u32_u24_e32 v12, s0, v174
	v_lshl_add_u64 v[12:13], v[12:13], 1, s[4:5]
	v_lshl_add_u64 v[12:13], v[12:13], 0, v[142:143]
	global_store_dwordx4 v[12:13], v[0:3], off
	s_waitcnt lgkmcnt(0)
	v_cvt_pk_bf16_f32 v3, v10, v11
	v_cvt_pk_bf16_f32 v0, v4, v5
	v_mul_hi_u32_u24_e32 v5, s0, v175
	v_mul_u32_u24_e32 v4, s0, v175
	v_lshl_add_u64 v[4:5], v[4:5], 1, s[4:5]
	v_cvt_pk_bf16_f32 v2, v8, v9
	v_cvt_pk_bf16_f32 v1, v6, v7
	v_lshl_add_u64 v[4:5], v[4:5], 0, v[142:143]
	global_store_dwordx4 v[4:5], v[0:3], off
	s_cbranch_execnz .LBB0_170
.LBB0_194:
	s_nop 0
	v_cvt_pk_bf16_f32 v1, v66, v67
	v_cvt_pk_bf16_f32 v0, v64, v65
	v_cvt_pk_bf16_f32 v3, v70, v71
	v_cvt_pk_bf16_f32 v2, v68, v69
	v_cvt_pk_bf16_f32 v5, v74, v75
	v_cvt_pk_bf16_f32 v4, v72, v73
	v_cvt_pk_bf16_f32 v7, v78, v79
	v_cvt_pk_bf16_f32 v6, v76, v77
	v_cvt_pk_bf16_f32 v9, v82, v83
	v_cvt_pk_bf16_f32 v8, v80, v81
	v_cvt_pk_bf16_f32 v11, v86, v87
	v_cvt_pk_bf16_f32 v10, v84, v85
	v_cvt_pk_bf16_f32 v13, v90, v91
	v_cvt_pk_bf16_f32 v12, v88, v89
	v_cvt_pk_bf16_f32 v15, v94, v95
	v_cvt_pk_bf16_f32 v14, v92, v93
	v_cvt_pk_bf16_f32 v17, v98, v99
	v_cvt_pk_bf16_f32 v16, v96, v97
	ds_write2_b64 v191, v[0:1], v[16:17] offset1:4
	v_cvt_pk_bf16_f32 v1, v102, v103
	v_cvt_pk_bf16_f32 v0, v100, v101
	v_add_u32_e32 v16, 0x1000, v191
	ds_write2_b64 v16, v[2:3], v[0:1] offset0:32 offset1:36
	v_cvt_pk_bf16_f32 v1, v106, v107
	v_cvt_pk_bf16_f32 v0, v104, v105
	v_add_u32_e32 v2, 0x2000, v191
	ds_write2_b64 v2, v[4:5], v[0:1] offset0:64 offset1:68
	v_cvt_pk_bf16_f32 v1, v110, v111
	v_cvt_pk_bf16_f32 v0, v108, v109
	v_add_u32_e32 v2, 0x3000, v191
	ds_write2_b64 v2, v[6:7], v[0:1] offset0:96 offset1:100
	v_cvt_pk_bf16_f32 v1, v114, v115
	v_cvt_pk_bf16_f32 v0, v112, v113
	v_add_u32_e32 v2, 0x4000, v191
	ds_write2_b64 v2, v[8:9], v[0:1] offset0:128 offset1:132
	v_cvt_pk_bf16_f32 v1, v118, v119
	v_cvt_pk_bf16_f32 v0, v116, v117
	v_add_u32_e32 v2, 0x5000, v191
	ds_write2_b64 v2, v[10:11], v[0:1] offset0:160 offset1:164
	v_cvt_pk_bf16_f32 v1, v122, v123
	v_cvt_pk_bf16_f32 v0, v120, v121
	v_add_u32_e32 v2, 0x6000, v191
	ds_write2_b64 v2, v[12:13], v[0:1] offset0:192 offset1:196
	v_cvt_pk_bf16_f32 v1, v126, v127
	v_cvt_pk_bf16_f32 v0, v124, v125
	v_add_u32_e32 v2, 0x7000, v191
	ds_write2_b64 v2, v[14:15], v[0:1] offset0:224 offset1:228
	s_waitcnt vmcnt(0) lgkmcnt(0)
	s_barrier
	ds_read_b128 v[0:3], v192
	v_mul_u32_u24_e32 v4, s0, v128
	v_lshl_add_u64 v[12:13], s[4:5], 0, v[142:143]
	v_lshlrev_b32_e32 v142, 1, v4
	v_lshl_add_u64 v[8:9], v[12:13], 0, v[142:143]
	s_waitcnt lgkmcnt(0)
	global_store_dwordx4 v[8:9], v[0:3], off
	ds_read_b128 v[0:3], v193
	v_mul_u32_u24_e32 v8, s0, v176
	v_lshlrev_b32_e32 v142, 1, v8
	ds_read_b128 v[8:11], v194
	v_lshl_add_u64 v[14:15], v[12:13], 0, v[142:143]
	s_waitcnt lgkmcnt(1)
	global_store_dwordx4 v[14:15], v[0:3], off
	ds_read_b128 v[4:7], v192 offset:17408
	s_nop 0
	v_mul_u32_u24_e32 v0, s0, v177
	v_lshlrev_b32_e32 v142, 1, v0
	v_lshl_add_u64 v[0:1], v[12:13], 0, v[142:143]
	s_waitcnt lgkmcnt(1)
	global_store_dwordx4 v[0:1], v[8:11], off
	ds_read_b128 v[0:3], v195
	s_nop 0
	v_mul_u32_u24_e32 v8, s0, v178
	v_lshlrev_b32_e32 v142, 1, v8
	v_lshl_add_u64 v[14:15], v[12:13], 0, v[142:143]
	ds_read_b128 v[8:11], v196
	s_waitcnt lgkmcnt(1)
	global_store_dwordx4 v[14:15], v[0:3], off
	s_nop 1
	v_mul_u32_u24_e32 v0, s0, v179
	v_lshlrev_b32_e32 v142, 1, v0
	v_lshl_add_u64 v[0:1], v[12:13], 0, v[142:143]
	global_store_dwordx4 v[0:1], v[4:7], off
	v_mul_hi_u32_u24_e32 v1, s0, v180
	v_mul_u32_u24_e32 v0, s0, v180
	v_lshl_add_u64 v[0:1], v[0:1], 1, v[12:13]
	s_waitcnt lgkmcnt(0)
	global_store_dwordx4 v[0:1], v[8:11], off
	ds_read_b128 v[0:3], v197
	v_mul_hi_u32_u24_e32 v5, s0, v181
	v_mul_u32_u24_e32 v4, s0, v181
	v_lshl_add_u64 v[8:9], v[4:5], 1, v[12:13]
	ds_read_b128 v[4:7], v198
	s_waitcnt lgkmcnt(1)
	global_store_dwordx4 v[8:9], v[0:3], off
	s_nop 1
	v_mul_hi_u32_u24_e32 v1, s0, v182
	v_mul_u32_u24_e32 v0, s0, v182
	v_lshl_add_u64 v[0:1], v[0:1], 1, v[12:13]
	s_waitcnt lgkmcnt(0)
	global_store_dwordx4 v[0:1], v[4:7], off
	s_branch .LBB0_170

.LBB0_250:
	v_mov_b32_e32 v1, s83
	v_or_b32_e32 v0, s82, v76
	v_lshl_add_u64 v[48:49], v[0:1], 0, s[80:81]
	v_or_b32_e32 v0, v48, v134
	v_mov_b32_e32 v1, v49
	v_lshlrev_b64 v[0:1], 12, v[0:1]
	v_lshl_add_u64 v[0:1], s[50:51], 0, v[0:1]
	s_lshl_b32 s28, s89, 1
	v_lshl_add_u64 v[0:1], v[0:1], 0, s[28:29]
	v_mov_b32_e32 v93, v72
	v_lshl_add_u64 v[0:1], v[0:1], 0, v[92:93]
	v_or_b32_e32 v4, v48, v136
	v_mov_b32_e32 v5, v49
	v_add_co_u32_e32 v50, vcc, s87, v0
	v_lshlrev_b64 v[4:5], 12, v[4:5]
	s_nop 0
	v_addc_co_u32_e32 v51, vcc, 0, v1, vcc
	v_lshl_add_u64 v[4:5], s[50:51], 0, v[4:5]
	global_load_dwordx4 v[0:3], v[50:51], off offset:2048
	v_lshl_add_u64 v[4:5], v[4:5], 0, s[28:29]
	v_lshl_add_u64 v[4:5], v[4:5], 0, v[92:93]
	v_add_co_u32_e32 v52, vcc, s87, v4
	s_nop 1
	v_addc_co_u32_e32 v53, vcc, 0, v5, vcc
	global_load_dwordx4 v[4:7], v[52:53], off offset:2048
	ds_write_b128 v169, v[16:19]
	ds_write_b128 v169, v[20:23] offset:64
	ds_write_b128 v169, v[24:27] offset:128
	ds_write_b128 v169, v[32:35] offset:192
	ds_write_b128 v169, v[28:31] offset:256
	ds_write_b128 v169, v[36:39] offset:320
	ds_write_b128 v169, v[40:43] offset:384
	ds_write_b128 v169, v[44:47] offset:448
	v_or_b32_e32 v16, v48, v132
	v_mov_b32_e32 v17, v49
	v_lshlrev_b64 v[16:17], 12, v[16:17]
	v_lshl_add_u64 v[16:17], s[50:51], 0, v[16:17]
	v_lshl_add_u64 v[16:17], v[16:17], 0, s[28:29]
	v_lshl_add_u64 v[16:17], v[16:17], 0, v[92:93]
	v_add_co_u32_e32 v32, vcc, s87, v16
	ds_read_b128 v[8:11], v170
	ds_read_b128 v[12:15], v170 offset:16
	v_addc_co_u32_e32 v33, vcc, 0, v17, vcc
	global_load_dwordx4 v[16:19], v[32:33], off offset:2048
	v_or_b32_e32 v48, v48, v130
	v_lshlrev_b64 v[28:29], 12, v[48:49]
	v_lshl_add_u64 v[28:29], s[50:51], 0, v[28:29]
	v_lshl_add_u64 v[28:29], v[28:29], 0, s[28:29]
	v_lshl_add_u64 v[28:29], v[28:29], 0, v[92:93]
	v_add_co_u32_e32 v34, vcc, s87, v28
	ds_read_b128 v[20:23], v170 offset:2112
	ds_read_b128 v[24:27], v170 offset:2128
	v_addc_co_u32_e32 v35, vcc, 0, v29, vcc
	global_load_dwordx4 v[28:31], v[34:35], off offset:2048
	s_waitcnt vmcnt(3)
	v_and_b32_e32 v37, 0xffff0000, v0
	v_lshlrev_b32_e32 v36, 16, v0
	v_and_b32_e32 v39, 0xffff0000, v2
	v_lshlrev_b32_e32 v38, 16, v2
	v_and_b32_e32 v41, 0xffff0000, v1
	v_lshlrev_b32_e32 v40, 16, v1
	v_and_b32_e32 v1, 0xffff0000, v3
	v_lshlrev_b32_e32 v0, 16, v3
	s_waitcnt lgkmcnt(3)
	v_pk_mul_f32 v[2:3], v[8:9], v[36:37]
	s_waitcnt lgkmcnt(2)
	v_pk_mul_f32 v[8:9], v[12:13], v[38:39]
	v_pk_mul_f32 v[10:11], v[10:11], v[40:41]
	v_pk_mul_f32 v[0:1], v[14:15], v[0:1]
	v_bfe_u32 v14, v9, 16, 1
	v_bfe_u32 v15, v8, 16, 1
	v_bfe_u32 v38, v3, 16, 1
	v_bfe_u32 v39, v2, 16, 1
	v_add3_u32 v39, v2, v39, s84
	v_add3_u32 v38, v3, v38, s84
	v_add3_u32 v2, v8, v15, s84
	v_add3_u32 v8, v9, v14, s84
	v_cvt_pk_bf16_f32 v3, v0, v1
	v_perm_b32 v2, v8, v2, s85
	v_cvt_pk_bf16_f32 v1, v10, v11
	v_perm_b32 v0, v38, v39, s85
	s_waitcnt vmcnt(2)
	v_and_b32_e32 v9, 0xffff0000, v5
	v_lshlrev_b32_e32 v8, 16, v5
	v_and_b32_e32 v43, 0xffff0000, v4
	global_store_dwordx4 v[50:51], v[0:3], off offset:2048
	v_lshlrev_b32_e32 v42, 16, v4
	s_waitcnt lgkmcnt(1)
	v_pk_mul_f32 v[4:5], v[22:23], v[8:9]
	v_and_b32_e32 v3, 0xffff0000, v6
	v_lshlrev_b32_e32 v2, 16, v6
	v_and_b32_e32 v9, 0xffff0000, v7
	v_lshlrev_b32_e32 v8, 16, v7
	v_pk_mul_f32 v[0:1], v[20:21], v[42:43]
	s_waitcnt lgkmcnt(0)
	v_pk_mul_f32 v[2:3], v[24:25], v[2:3]
	v_pk_mul_f32 v[6:7], v[26:27], v[8:9]
	v_bfe_u32 v10, v3, 16, 1
	v_bfe_u32 v8, v7, 16, 1
	v_bfe_u32 v9, v6, 16, 1
	v_bfe_u32 v11, v2, 16, 1
	v_bfe_u32 v12, v5, 16, 1
	v_bfe_u32 v13, v4, 16, 1
	v_bfe_u32 v14, v1, 16, 1
	v_bfe_u32 v15, v0, 16, 1
	v_add3_u32 v0, v0, v15, s84
	v_add3_u32 v14, v1, v14, s84
	v_add3_u32 v1, v4, v13, s84
	v_add3_u32 v4, v5, v12, s84
	v_add3_u32 v2, v2, v11, s84
	v_add3_u32 v5, v3, v10, s84
	v_add3_u32 v3, v6, v9, s84
	v_add3_u32 v6, v7, v8, s84
	v_perm_b32 v3, v6, v3, s85
	v_perm_b32 v2, v5, v2, s85
	v_perm_b32 v1, v4, v1, s85
	v_perm_b32 v0, v14, v0, s85
	ds_read_b128 v[4:7], v170 offset:4224
	global_store_dwordx4 v[52:53], v[0:3], off offset:2048
	ds_read_b128 v[0:3], v170 offset:4240
	s_waitcnt vmcnt(3)
	v_and_b32_e32 v9, 0xffff0000, v16
	v_lshlrev_b32_e32 v8, 16, v16
	s_waitcnt lgkmcnt(1)
	v_pk_mul_f32 v[4:5], v[4:5], v[8:9]
	v_and_b32_e32 v9, 0xffff0000, v18
	v_lshlrev_b32_e32 v8, 16, v18
	s_waitcnt lgkmcnt(0)
	v_pk_mul_f32 v[0:1], v[0:1], v[8:9]
	v_and_b32_e32 v9, 0xffff0000, v17
	v_lshlrev_b32_e32 v8, 16, v17
	v_pk_mul_f32 v[6:7], v[6:7], v[8:9]
	v_and_b32_e32 v9, 0xffff0000, v19
	v_lshlrev_b32_e32 v8, 16, v19
	v_pk_mul_f32 v[2:3], v[2:3], v[8:9]
	v_cvt_pk_bf16_f32 v3, v2, v3
	v_cvt_pk_bf16_f32 v2, v0, v1
	v_cvt_pk_bf16_f32 v1, v6, v7
	v_cvt_pk_bf16_f32 v0, v4, v5
	ds_read_b128 v[4:7], v170 offset:6336
	global_store_dwordx4 v[32:33], v[0:3], off offset:2048
	ds_read_b128 v[0:3], v170 offset:6352
	s_waitcnt vmcnt(3)
	v_and_b32_e32 v9, 0xffff0000, v28
	v_lshlrev_b32_e32 v8, 16, v28
	s_waitcnt lgkmcnt(1)
	v_pk_mul_f32 v[4:5], v[4:5], v[8:9]
	v_and_b32_e32 v9, 0xffff0000, v30
	v_lshlrev_b32_e32 v8, 16, v30
	s_waitcnt lgkmcnt(0)
	v_pk_mul_f32 v[0:1], v[0:1], v[8:9]
	v_and_b32_e32 v9, 0xffff0000, v29
	v_lshlrev_b32_e32 v8, 16, v29
	v_pk_mul_f32 v[6:7], v[6:7], v[8:9]
	v_and_b32_e32 v9, 0xffff0000, v31
	v_lshlrev_b32_e32 v8, 16, v31
	v_pk_mul_f32 v[2:3], v[2:3], v[8:9]
	v_cvt_pk_bf16_f32 v3, v2, v3
	v_cvt_pk_bf16_f32 v2, v0, v1
	v_cvt_pk_bf16_f32 v1, v6, v7
	v_cvt_pk_bf16_f32 v0, v4, v5
	global_store_dwordx4 v[34:35], v[0:3], off offset:2048
	s_barrier

.LBB0_254:
	s_and_b32 s10, s88, 7
	s_lshl_b32 s28, s10, 15
	v_readfirstlane_b32 s8, v129
	v_lshl_add_u64 v[4:5], v[78:79], 0, s[28:29]
	s_mov_b32 m0, s8
	v_readfirstlane_b32 s8, v141
	s_barrier
	global_load_lds_dwordx4 v[4:5], off
	v_lshl_add_u64 v[0:1], v[4:5], 0, s[38:39]
	s_mov_b32 m0, s8
	v_readfirstlane_b32 s8, v142
	s_add_i32 s9, s88, 0xfffff800
	global_load_lds_dwordx4 v[0:1], off
	v_lshl_add_u64 v[0:1], v[4:5], 0, s[46:47]
	s_mov_b32 m0, s8
	v_readfirstlane_b32 s8, v143
	global_load_lds_dwordx4 v[0:1], off
	v_lshl_add_u64 v[0:1], v[4:5], 0, s[52:53]
	s_mov_b32 m0, s8
	s_lshl_b32 s28, s9, 15
	v_readfirstlane_b32 s8, v144
	global_load_lds_dwordx4 v[0:1], off
	v_lshl_add_u64 v[6:7], v[80:81], 0, s[28:29]
	s_mov_b32 m0, s8
	v_readfirstlane_b32 s8, v145
	global_load_lds_dwordx4 v[6:7], off
	v_lshl_add_u64 v[0:1], v[6:7], 0, s[38:39]
	s_mov_b32 m0, s8
	v_readfirstlane_b32 s8, v146
	global_load_lds_dwordx4 v[0:1], off
	v_lshl_add_u64 v[0:1], v[6:7], 0, s[46:47]
	s_mov_b32 m0, s8
	v_readfirstlane_b32 s8, v147
	global_load_lds_dwordx4 v[0:1], off
	v_lshl_add_u64 v[0:1], v[6:7], 0, s[52:53]
	s_mov_b32 m0, s8
	v_readfirstlane_b32 s8, v148
	global_load_lds_dwordx4 v[0:1], off
	v_lshl_add_u64 v[8:9], v[4:5], 0, s[56:57]
	s_mov_b32 m0, s8
	v_readfirstlane_b32 s8, v150
	s_waitcnt vmcnt(0)
	s_barrier
	ds_read_b128 v[0:3], v166 offset:16384
	ds_read_b128 v[28:31], v166 offset:18432
	ds_read_b128 v[32:35], v166 offset:20480
	global_load_lds_dwordx4 v[8:9], off
	v_lshl_add_u64 v[8:9], v[4:5], 0, s[58:59]
	s_mov_b32 m0, s8
	v_readfirstlane_b32 s8, v151
	global_load_lds_dwordx4 v[8:9], off
	v_lshl_add_u64 v[8:9], v[4:5], 0, s[60:61]
	s_mov_b32 m0, s8
	v_readfirstlane_b32 s8, v160
	global_load_lds_dwordx4 v[8:9], off
	v_lshl_add_u64 v[4:5], v[4:5], 0, s[64:65]
	s_mov_b32 m0, s8
	v_readfirstlane_b32 s8, v161
	global_load_lds_dwordx4 v[4:5], off
	v_lshl_add_u64 v[4:5], v[6:7], 0, s[56:57]
	s_mov_b32 m0, s8
	v_readfirstlane_b32 s8, v162
	global_load_lds_dwordx4 v[4:5], off
	v_lshl_add_u64 v[4:5], v[6:7], 0, s[58:59]
	s_mov_b32 m0, s8
	v_readfirstlane_b32 s8, v163
	global_load_lds_dwordx4 v[4:5], off
	v_lshl_add_u64 v[4:5], v[6:7], 0, s[60:61]
	s_mov_b32 m0, s8
	v_readfirstlane_b32 s8, v164
	global_load_lds_dwordx4 v[4:5], off
	v_lshl_add_u64 v[4:5], v[6:7], 0, s[64:65]
	s_mov_b32 m0, s8
	s_lshl_b32 s9, s9, 4
	global_load_lds_dwordx4 v[4:5], off
	ds_read_b128 v[36:39], v165
	ds_read_b128 v[64:67], v165 offset:2048
	ds_read_b128 v[44:47], v166 offset:22528
	ds_read_b128 v[48:51], v166 offset:24576
	ds_read_b128 v[52:55], v166 offset:26624
	ds_read_b128 v[56:59], v166 offset:28672
	ds_read_b128 v[68:71], v166 offset:30720
	ds_read_b128 v[60:63], v167
	ds_read_b128 v[94:97], v167 offset:2048
	ds_read_b128 v[98:101], v168 offset:16384
	ds_read_b128 v[40:43], v168 offset:18432
	ds_read_b128 v[174:177], v168 offset:20480
	ds_read_b128 v[178:181], v168 offset:22528
	ds_read_b128 v[182:185], v168 offset:24576
	ds_read_b128 v[186:189], v168 offset:26624
	ds_read_b128 v[190:193], v168 offset:28672
	ds_read_b128 v[194:197], v168 offset:30720
	s_waitcnt vmcnt(0)
	s_barrier
	ds_read_b128 v[198:201], v165 offset:32768
	ds_read_b128 v[202:205], v165 offset:34816
	ds_read_b128 v[206:209], v166 offset:49152
	ds_read_b128 v[210:213], v166 offset:51200
	ds_read_b128 v[214:217], v166 offset:61440
	ds_read_b128 v[218:221], v166 offset:53248
	ds_read_b128 v[222:225], v166 offset:59392
	ds_read_b128 v[226:229], v166 offset:55296
	ds_read_b128 v[230:233], v166 offset:57344
	ds_read_b128 v[234:237], v166 offset:63488
	ds_read_b128 v[242:245], v167 offset:32768
	s_waitcnt lgkmcnt(0)
	v_mfma_f32_16x16x32_bf16 v[4:7], v[64:67], v[56:59], 0
	s_and_b32 s9, s9, 0x3f80
	s_lshl_b32 s28, s10, 8
	v_mov_b32_e32 v93, v72
	v_mfma_f32_16x16x32_bf16 v[4:7], v[94:97], v[190:193], v[4:7]
	v_add_u32_e32 v73, s9, v109
	v_add_u32_e32 v85, s9, v111
	s_lshl_b32 s8, s10, 7
	v_mfma_f32_16x16x32_bf16 v[16:19], v[202:205], v[214:217], v[4:7]
	v_mfma_f32_16x16x32_bf16 v[4:7], v[64:67], v[52:55], 0
	v_mfma_f32_16x16x32_bf16 v[4:7], v[94:97], v[186:189], v[4:7]
	v_mfma_f32_16x16x32_bf16 v[24:27], v[202:205], v[222:225], v[4:7]
	v_mfma_f32_16x16x32_bf16 v[4:7], v[64:67], v[48:51], 0
	v_mfma_f32_16x16x32_bf16 v[4:7], v[94:97], v[182:185], v[4:7]
	v_mfma_f32_16x16x32_bf16 v[20:23], v[202:205], v[230:233], v[4:7]
	v_mfma_f32_16x16x32_bf16 v[4:7], v[64:67], v[44:47], 0
	v_mfma_f32_16x16x32_bf16 v[4:7], v[94:97], v[178:181], v[4:7]
	v_mfma_f32_16x16x32_bf16 v[12:15], v[202:205], v[226:229], v[4:7]
	v_mfma_f32_16x16x32_bf16 v[4:7], v[64:67], v[32:35], 0
	v_mfma_f32_16x16x32_bf16 v[4:7], v[94:97], v[174:177], v[4:7]
	v_mfma_f32_16x16x32_bf16 v[8:11], v[202:205], v[218:221], v[4:7]
	v_mfma_f32_16x16x32_bf16 v[4:7], v[64:67], v[28:31], 0
	v_mfma_f32_16x16x32_bf16 v[4:7], v[94:97], v[40:43], v[4:7]
	v_mfma_f32_16x16x32_bf16 v[28:31], v[36:39], v[28:31], 0
	v_mfma_f32_16x16x32_bf16 v[28:31], v[60:63], v[40:43], v[28:31]
	ds_read_b128 v[40:43], v167 offset:34816
	v_mfma_f32_16x16x32_bf16 v[4:7], v[202:205], v[210:213], v[4:7]
	v_mfma_f32_16x16x32_bf16 v[210:213], v[198:201], v[210:213], v[28:31]
	v_mfma_f32_16x16x32_bf16 v[28:31], v[36:39], v[32:35], 0
	v_mfma_f32_16x16x32_bf16 v[28:31], v[60:63], v[174:177], v[28:31]
	ds_read_b128 v[174:177], v168 offset:49152
	v_mfma_f32_16x16x32_bf16 v[32:35], v[198:201], v[218:221], v[28:31]
	v_mfma_f32_16x16x32_bf16 v[28:31], v[36:39], v[44:47], 0
	v_mfma_f32_16x16x32_bf16 v[28:31], v[60:63], v[178:181], v[28:31]
	v_mfma_f32_16x16x32_bf16 v[178:181], v[198:201], v[226:229], v[28:31]
	s_nop 6
	ds_read_b128 v[28:31], v168 offset:51200
	v_mfma_f32_16x16x32_bf16 v[44:47], v[36:39], v[48:51], 0
	v_mfma_f32_16x16x32_bf16 v[44:47], v[60:63], v[182:185], v[44:47]
	v_mfma_f32_16x16x32_bf16 v[182:185], v[198:201], v[230:233], v[44:47]
	s_nop 6
	ds_read_b128 v[44:47], v168 offset:53248
	v_mfma_f32_16x16x32_bf16 v[48:51], v[36:39], v[52:55], 0
	v_mfma_f32_16x16x32_bf16 v[48:51], v[60:63], v[186:189], v[48:51]
	v_mfma_f32_16x16x32_bf16 v[186:189], v[198:201], v[222:225], v[48:51]
	s_nop 6
	ds_read_b128 v[48:51], v168 offset:55296
	v_mfma_f32_16x16x32_bf16 v[52:55], v[36:39], v[56:59], 0
	v_mfma_f32_16x16x32_bf16 v[52:55], v[60:63], v[190:193], v[52:55]
	v_mfma_f32_16x16x32_bf16 v[190:193], v[198:201], v[214:217], v[52:55]
	s_nop 6
	ds_read_b128 v[52:55], v168 offset:57344
	ds_read_b128 v[56:59], v168 offset:59392
	v_mfma_f32_16x16x32_bf16 v[238:241], v[36:39], v[0:3], 0
	v_mfma_f32_16x16x32_bf16 v[238:241], v[60:63], v[98:101], v[238:241]
	v_mfma_f32_16x16x32_bf16 v[36:39], v[36:39], v[68:71], 0
	v_mfma_f32_16x16x32_bf16 v[36:39], v[60:63], v[194:197], v[36:39]
	ds_read_b128 v[60:63], v168 offset:61440
	v_mfma_f32_16x16x32_bf16 v[0:3], v[64:67], v[0:3], 0
	v_mfma_f32_16x16x32_bf16 v[64:67], v[64:67], v[68:71], 0
	ds_read_b128 v[68:71], v168 offset:63488
	s_barrier
	v_mfma_f32_16x16x32_bf16 v[238:241], v[198:201], v[206:209], v[238:241]
	v_mfma_f32_16x16x32_bf16 v[36:39], v[198:201], v[234:237], v[36:39]
	v_mfma_f32_16x16x32_bf16 v[0:3], v[94:97], v[98:101], v[0:3]
	v_mfma_f32_16x16x32_bf16 v[64:67], v[94:97], v[194:197], v[64:67]
	s_waitcnt lgkmcnt(0)
	v_mfma_f32_16x16x32_bf16 v[94:97], v[242:245], v[174:177], v[238:241]
	v_mfma_f32_16x16x32_bf16 v[98:101], v[242:245], v[28:31], v[210:213]
	s_nop 7
	ds_write2_b32 v171, v97, v101 offset0:128 offset1:144
	v_mfma_f32_16x16x32_bf16 v[32:35], v[242:245], v[44:47], v[32:35]
	ds_write2_b32 v171, v96, v100 offset1:16
	v_mfma_f32_16x16x32_bf16 v[178:181], v[242:245], v[48:51], v[178:181]
	s_nop 7
	ds_write2_b32 v171, v35, v181 offset0:160 offset1:176
	v_mfma_f32_16x16x32_bf16 v[182:185], v[242:245], v[52:55], v[182:185]
	ds_write2_b32 v171, v34, v180 offset0:32 offset1:48
	v_mfma_f32_16x16x32_bf16 v[186:189], v[242:245], v[56:59], v[186:189]
	s_nop 7
	ds_write2_b32 v171, v185, v189 offset0:192 offset1:208
	v_mfma_f32_16x16x32_bf16 v[190:193], v[242:245], v[60:63], v[190:193]
	ds_write2_b32 v171, v184, v188 offset0:64 offset1:80
	v_mfma_f32_16x16x32_bf16 v[36:39], v[242:245], v[68:71], v[36:39]
	ds_write2_b32 v102, v183, v187 offset0:192 offset1:208
	s_nop 4
	ds_write2st64_b32 v103, v192, v193 offset0:4 offset1:6
	s_nop 0
	ds_write2st64_b32 v104, v38, v39 offset0:4 offset1:6
	ds_write2_b32 v102, v182, v186 offset0:64 offset1:80
	ds_write2_b32 v102, v33, v179 offset0:160 offset1:176
	ds_write2_b32 v102, v32, v178 offset0:32 offset1:48
	ds_write2_b32 v102, v95, v99 offset0:128 offset1:144
	ds_write2_b32 v102, v94, v98 offset1:16
	ds_write2st64_b32 v103, v190, v191 offset1:2
	ds_write2st64_b32 v104, v36, v37 offset1:2
	ds_read_b128 v[32:35], v110 offset:16
	ds_read_b128 v[36:39], v110
	ds_read_b128 v[94:97], v108 offset:16
	v_mfma_f32_16x16x32_bf16 v[8:11], v[40:43], v[44:47], v[8:11]
	v_mfma_f32_16x16x32_bf16 v[12:15], v[40:43], v[48:51], v[12:15]
	ds_read_b128 v[46:49], v108
	ds_read_b128 v[98:101], v106 offset:16
	v_mfma_f32_16x16x32_bf16 v[4:7], v[40:43], v[28:31], v[4:7]
	v_mfma_f32_16x16x32_bf16 v[20:23], v[40:43], v[52:55], v[20:23]
	v_add_u32_e32 v53, s9, v107
	v_add_lshl_u32 v52, s8, v105, 2
	v_mfma_f32_16x16x32_bf16 v[28:31], v[40:43], v[56:59], v[24:27]
	ds_read_b128 v[54:57], v106
	v_mfma_f32_16x16x32_bf16 v[16:19], v[40:43], v[60:63], v[16:19]
	ds_read_b128 v[58:61], v77 offset:16
	v_mfma_f32_16x16x32_bf16 v[64:67], v[202:205], v[234:237], v[64:67]
	v_mfma_f32_16x16x32_bf16 v[24:27], v[40:43], v[68:71], v[64:67]
	s_nop 6
	ds_read_b128 v[62:65], v77
	v_mfma_f32_16x16x32_bf16 v[0:3], v[202:205], v[206:209], v[0:3]
	v_mfma_f32_16x16x32_bf16 v[0:3], v[40:43], v[174:177], v[0:3]
	v_add_u32_e32 v42, s9, v105
	v_lshlrev_b32_e32 v40, 11, v42
	v_mov_b32_e32 v41, v72
	v_lshl_add_u64 v[40:41], s[48:49], 0, v[40:41]
	v_lshl_add_u64 v[40:41], v[40:41], 0, s[28:29]
	v_lshl_add_u64 v[50:51], v[40:41], 0, v[92:93]
	v_lshlrev_b32_e32 v40, 12, v42
	v_mov_b32_e32 v41, v72
	v_lshl_add_u64 v[40:41], s[36:37], 0, v[40:41]
	v_lshl_add_u64 v[40:41], v[40:41], 0, s[28:29]
	v_lshl_add_u64 v[70:71], v[40:41], 0, v[92:93]
	v_lshlrev_b32_e32 v40, 12, v53
	v_mov_b32_e32 v41, v72
	v_lshl_add_u64 v[40:41], s[36:37], 0, v[40:41]
	v_lshl_add_u64 v[40:41], v[40:41], 0, s[28:29]
	v_lshl_add_u64 v[186:187], v[40:41], 0, v[92:93]
	v_lshlrev_b32_e32 v40, 12, v73
	v_mov_b32_e32 v41, v72
	v_lshl_add_u64 v[40:41], s[36:37], 0, v[40:41]
	v_lshl_add_u64 v[40:41], v[40:41], 0, s[28:29]
	v_lshl_add_u64 v[188:189], v[40:41], 0, v[92:93]
	v_lshlrev_b32_e32 v40, 12, v85
	v_mov_b32_e32 v41, v72
	v_lshl_add_u64 v[40:41], s[36:37], 0, v[40:41]
	v_lshl_add_u64 v[40:41], v[40:41], 0, s[28:29]
	v_lshl_add_u64 v[44:45], v[40:41], 0, v[92:93]
	global_load_dwordx4 v[40:43], v[44:45], off
	global_load_dwordx4 v[66:69], v[188:189], off
	global_load_dwordx4 v[174:177], v[186:187], off
	global_load_dwordx4 v[178:181], v[70:71], off
	global_load_dwordx4 v[182:185], v[50:51], off
	s_waitcnt vmcnt(0)
	v_and_b32_e32 v191, 0xffff0000, v182
	global_load_dword v50, v52, s[54:55]
	v_lshlrev_b32_e32 v190, 16, v182
	v_lshlrev_b32_e32 v182, 16, v179
	s_waitcnt vmcnt(0) lgkmcnt(0)
	v_pk_add_f32 v[62:63], v[62:63], v[50:51] op_sel_hi:[1,0]
	v_pk_add_f32 v[64:65], v[64:65], v[50:51] op_sel_hi:[1,0]
	v_pk_add_f32 v[58:59], v[58:59], v[50:51] op_sel_hi:[1,0]
	v_pk_add_f32 v[50:51], v[60:61], v[50:51] op_sel_hi:[1,0]
	v_and_b32_e32 v61, 0xffff0000, v185
	v_lshlrev_b32_e32 v60, 16, v185
	v_pk_mul_f32 v[62:63], v[62:63], v[190:191]
	v_and_b32_e32 v191, 0xffff0000, v178
	v_lshlrev_b32_e32 v190, 16, v178
	v_pk_mul_f32 v[50:51], v[50:51], v[60:61]
	v_and_b32_e32 v61, 0xffff0000, v181
	v_lshlrev_b32_e32 v60, 16, v181
	v_pk_mul_f32 v[62:63], v[62:63], v[190:191]
	v_and_b32_e32 v191, 0xffff0000, v183
	v_lshlrev_b32_e32 v190, 16, v183
	v_and_b32_e32 v183, 0xffff0000, v179
	v_and_b32_e32 v179, 0xffff0000, v184
	v_lshlrev_b32_e32 v178, 16, v184
	v_pk_mul_f32 v[50:51], v[50:51], v[60:61]
	v_pk_mul_f32 v[64:65], v[64:65], v[190:191]
	v_pk_mul_f32 v[58:59], v[58:59], v[178:179]
	v_and_b32_e32 v179, 0xffff0000, v180
	v_lshlrev_b32_e32 v178, 16, v180
	v_pk_mul_f32 v[64:65], v[64:65], v[182:183]
	v_pk_mul_f32 v[58:59], v[58:59], v[178:179]
	v_bfe_u32 v87, v59, 16, 1
	v_bfe_u32 v89, v58, 16, 1
	v_bfe_u32 v91, v65, 16, 1
	v_bfe_u32 v173, v64, 16, 1
	v_cvt_pk_bf16_f32 v61, v50, v51
	v_lshlrev_b32_e32 v50, 11, v53
	v_mov_b32_e32 v51, v72
	v_add3_u32 v64, v64, v173, s84
	v_add3_u32 v65, v65, v91, s84
	v_add3_u32 v58, v58, v89, s84
	v_add3_u32 v59, v59, v87, s84
	v_lshl_add_u64 v[50:51], s[48:49], 0, v[50:51]
	v_perm_b32 v60, v59, v58, s85
	v_perm_b32 v59, v65, v64, s85
	v_cvt_pk_bf16_f32 v58, v62, v63
	v_lshl_add_u64 v[50:51], v[50:51], 0, s[28:29]
	global_store_dwordx4 v[70:71], v[58:61], off
	v_lshl_add_u64 v[50:51], v[50:51], 0, v[92:93]
	global_load_dwordx4 v[58:61], v[50:51], off
	v_and_b32_e32 v63, 0xffff0000, v174
	global_load_dword v50, v52, s[54:55] offset:16
	v_lshlrev_b32_e32 v62, 16, v174
	v_and_b32_e32 v65, 0xffff0000, v175
	v_lshlrev_b32_e32 v64, 16, v175
	v_and_b32_e32 v71, 0xffff0000, v176
	v_lshlrev_b32_e32 v70, 16, v176
	v_add_lshl_u32 v87, s8, v74, 2
	s_waitcnt vmcnt(1)
	v_and_b32_e32 v175, 0xffff0000, v58
	v_lshlrev_b32_e32 v174, 16, v58
	s_waitcnt vmcnt(0)
	v_pk_add_f32 v[54:55], v[54:55], v[50:51] op_sel_hi:[1,0]
	v_pk_add_f32 v[56:57], v[56:57], v[50:51] op_sel_hi:[1,0]
	v_pk_mul_f32 v[54:55], v[54:55], v[174:175]
	v_and_b32_e32 v179, 0xffff0000, v59
	v_lshlrev_b32_e32 v178, 16, v59
	v_pk_add_f32 v[58:59], v[98:99], v[50:51] op_sel_hi:[1,0]
	v_pk_mul_f32 v[54:55], v[54:55], v[62:63]
	v_pk_add_f32 v[50:51], v[100:101], v[50:51] op_sel_hi:[1,0]
	v_and_b32_e32 v63, 0xffff0000, v61
	v_lshlrev_b32_e32 v62, 16, v61
	v_and_b32_e32 v99, 0xffff0000, v60
	v_lshlrev_b32_e32 v98, 16, v60
	v_pk_mul_f32 v[50:51], v[50:51], v[62:63]
	v_and_b32_e32 v61, 0xffff0000, v177
	v_lshlrev_b32_e32 v60, 16, v177
	v_pk_mul_f32 v[56:57], v[56:57], v[178:179]
	v_pk_mul_f32 v[50:51], v[50:51], v[60:61]
	v_pk_mul_f32 v[58:59], v[58:59], v[98:99]
	v_pk_mul_f32 v[56:57], v[56:57], v[64:65]
	v_pk_mul_f32 v[58:59], v[58:59], v[70:71]
	v_bfe_u32 v63, v57, 16, 1
	v_bfe_u32 v61, v59, 16, 1
	v_bfe_u32 v62, v58, 16, 1
	v_bfe_u32 v64, v56, 16, 1
	v_bfe_u32 v65, v55, 16, 1
	v_bfe_u32 v70, v54, 16, 1
	v_add3_u32 v63, v57, v63, s84
	v_cvt_pk_bf16_f32 v57, v50, v51
	v_lshlrev_b32_e32 v50, 11, v73
	v_mov_b32_e32 v51, v72
	v_add3_u32 v54, v54, v70, s84
	v_add3_u32 v65, v55, v65, s84
	v_add3_u32 v55, v56, v64, s84
	v_add3_u32 v56, v58, v62, s84
	v_add3_u32 v58, v59, v61, s84
	v_lshl_add_u64 v[50:51], s[48:49], 0, v[50:51]
	v_perm_b32 v56, v58, v56, s85
	v_perm_b32 v55, v63, v55, s85
	v_perm_b32 v54, v65, v54, s85
	v_lshl_add_u64 v[50:51], v[50:51], 0, s[28:29]
	global_store_dwordx4 v[186:187], v[54:57], off
	v_lshl_add_u64 v[50:51], v[50:51], 0, v[92:93]
	global_load_dwordx4 v[54:57], v[50:51], off
	v_and_b32_e32 v61, 0xffff0000, v66
	global_load_dword v50, v52, s[54:55] offset:32
	v_lshlrev_b32_e32 v60, 16, v66
	v_and_b32_e32 v63, 0xffff0000, v67
	v_lshlrev_b32_e32 v62, 16, v67
	v_and_b32_e32 v65, 0xffff0000, v68
	v_lshlrev_b32_e32 v64, 16, v68
	v_and_b32_e32 v67, 0xffff0000, v69
	v_lshlrev_b32_e32 v66, 16, v69
	v_mov_b32_e32 v59, v72
	v_lshlrev_b32_e32 v58, 11, v85
	v_lshl_add_u64 v[58:59], s[48:49], 0, v[58:59]
	v_lshl_add_u64 v[58:59], v[58:59], 0, s[28:29]
	v_lshl_add_u64 v[58:59], v[58:59], 0, v[92:93]
	v_add_u32_e32 v73, s9, v113
	v_add_u32_e32 v85, s9, v114
	s_waitcnt vmcnt(1)
	v_and_b32_e32 v69, 0xffff0000, v54
	v_lshlrev_b32_e32 v68, 16, v54
	s_waitcnt vmcnt(0)
	v_pk_add_f32 v[46:47], v[46:47], v[50:51] op_sel_hi:[1,0]
	v_pk_add_f32 v[48:49], v[48:49], v[50:51] op_sel_hi:[1,0]
	v_and_b32_e32 v71, 0xffff0000, v55
	v_lshlrev_b32_e32 v70, 16, v55
	v_pk_add_f32 v[54:55], v[94:95], v[50:51] op_sel_hi:[1,0]
	v_and_b32_e32 v95, 0xffff0000, v56
	v_lshlrev_b32_e32 v94, 16, v56
	v_pk_add_f32 v[50:51], v[96:97], v[50:51] op_sel_hi:[1,0]
	v_and_b32_e32 v97, 0xffff0000, v57
	v_lshlrev_b32_e32 v96, 16, v57
	v_pk_mul_f32 v[46:47], v[46:47], v[68:69]
	v_pk_mul_f32 v[48:49], v[48:49], v[70:71]
	v_pk_mul_f32 v[54:55], v[54:55], v[94:95]
	v_pk_mul_f32 v[50:51], v[50:51], v[96:97]
	v_pk_mul_f32 v[46:47], v[46:47], v[60:61]
	v_pk_mul_f32 v[48:49], v[48:49], v[62:63]
	v_pk_mul_f32 v[54:55], v[54:55], v[64:65]
	v_pk_mul_f32 v[50:51], v[50:51], v[66:67]
	v_bfe_u32 v57, v55, 16, 1
	v_bfe_u32 v53, v51, 16, 1
	v_bfe_u32 v56, v50, 16, 1
	v_bfe_u32 v60, v54, 16, 1
	v_bfe_u32 v61, v49, 16, 1
	v_bfe_u32 v62, v48, 16, 1
	v_bfe_u32 v63, v47, 16, 1
	v_bfe_u32 v64, v46, 16, 1
	v_add3_u32 v46, v46, v64, s84
	v_add3_u32 v63, v47, v63, s84
	v_add3_u32 v47, v48, v62, s84
	v_add3_u32 v61, v49, v61, s84
	v_add3_u32 v48, v54, v60, s84
	v_add3_u32 v54, v55, v57, s84
	v_add3_u32 v49, v50, v56, s84
	v_add3_u32 v50, v51, v53, s84
	v_perm_b32 v49, v50, v49, s85
	v_perm_b32 v48, v54, v48, s85
	v_perm_b32 v47, v61, v47, s85
	v_perm_b32 v46, v63, v46, s85
	global_store_dwordx4 v[188:189], v[46:49], off
	global_load_dwordx4 v[54:57], v[58:59], off
	v_and_b32_e32 v63, 0xffff0000, v41
	global_load_dword v58, v52, s[54:55] offset:48
	v_add_u32_e32 v48, s9, v74
	v_mov_b32_e32 v47, v72
	v_mov_b32_e32 v49, v72
	v_lshlrev_b32_e32 v46, 11, v48
	v_lshlrev_b32_e32 v48, 12, v48
	v_lshl_add_u64 v[46:47], s[48:49], 0, v[46:47]
	v_lshl_add_u64 v[48:49], s[36:37], 0, v[48:49]
	v_lshl_add_u64 v[46:47], v[46:47], 0, s[28:29]
	v_lshl_add_u64 v[60:61], v[48:49], 0, s[28:29]
	v_lshl_add_u64 v[48:49], v[46:47], 0, v[92:93]
	v_lshl_add_u64 v[46:47], v[60:61], 0, v[92:93]
	v_and_b32_e32 v61, 0xffff0000, v40
	v_lshlrev_b32_e32 v60, 16, v40
	v_lshlrev_b32_e32 v62, 16, v41
	v_and_b32_e32 v41, 0xffff0000, v42
	v_lshlrev_b32_e32 v40, 16, v42
	v_and_b32_e32 v65, 0xffff0000, v43
	v_lshlrev_b32_e32 v64, 16, v43
	v_add_u32_e32 v53, s9, v112
	v_mov_b32_e32 v51, v72
	v_lshlrev_b32_e32 v50, 12, v53
	s_waitcnt vmcnt(1)
	v_and_b32_e32 v43, 0xffff0000, v54
	v_lshlrev_b32_e32 v42, 16, v54
	s_waitcnt vmcnt(0)
	v_pk_add_f32 v[36:37], v[36:37], v[58:59] op_sel_hi:[1,0]
	v_pk_add_f32 v[38:39], v[38:39], v[58:59] op_sel_hi:[1,0]
	v_and_b32_e32 v67, 0xffff0000, v55
	v_lshlrev_b32_e32 v66, 16, v55
	v_pk_add_f32 v[32:33], v[32:33], v[58:59] op_sel_hi:[1,0]
	v_and_b32_e32 v55, 0xffff0000, v56
	v_lshlrev_b32_e32 v54, 16, v56
	v_pk_add_f32 v[34:35], v[34:35], v[58:59] op_sel_hi:[1,0]
	v_and_b32_e32 v59, 0xffff0000, v57
	v_lshlrev_b32_e32 v58, 16, v57
	v_pk_mul_f32 v[36:37], v[36:37], v[42:43]
	v_pk_mul_f32 v[38:39], v[38:39], v[66:67]
	v_pk_mul_f32 v[32:33], v[32:33], v[54:55]
	v_pk_mul_f32 v[34:35], v[34:35], v[58:59]
	v_pk_mul_f32 v[36:37], v[36:37], v[60:61]
	v_pk_mul_f32 v[38:39], v[38:39], v[62:63]
	v_pk_mul_f32 v[32:33], v[32:33], v[40:41]
	v_pk_mul_f32 v[34:35], v[34:35], v[64:65]
	v_cvt_pk_bf16_f32 v35, v34, v35
	v_cvt_pk_bf16_f32 v34, v32, v33
	v_cvt_pk_bf16_f32 v33, v38, v39
	v_cvt_pk_bf16_f32 v32, v36, v37
	global_store_dwordx4 v[44:45], v[32:35], off
	ds_write2_b32 v171, v23, v31 offset0:192 offset1:208
	ds_write2_b32 v171, v22, v30 offset0:64 offset1:80
	ds_write2_b32 v102, v21, v29 offset0:192 offset1:208
	ds_write2_b32 v171, v11, v15 offset0:160 offset1:176
	ds_write2_b32 v171, v10, v14 offset0:32 offset1:48
	ds_write2_b32 v171, v3, v7 offset0:128 offset1:144
	ds_write2_b32 v171, v2, v6 offset1:16
	ds_write2st64_b32 v103, v18, v19 offset0:4 offset1:6
	ds_write2st64_b32 v104, v26, v27 offset0:4 offset1:6
	ds_write2_b32 v102, v20, v28 offset0:64 offset1:80
	ds_write2_b32 v102, v9, v13 offset0:160 offset1:176
	ds_write2_b32 v102, v8, v12 offset0:32 offset1:48
	v_lshl_add_u64 v[8:9], s[36:37], 0, v[50:51]
	v_lshl_add_u64 v[8:9], v[8:9], 0, s[28:29]
	v_lshl_add_u64 v[58:59], v[8:9], 0, v[92:93]
	v_lshlrev_b32_e32 v8, 12, v73
	v_mov_b32_e32 v9, v72
	v_lshl_add_u64 v[8:9], s[36:37], 0, v[8:9]
	v_lshl_add_u64 v[8:9], v[8:9], 0, s[28:29]
	v_lshl_add_u64 v[60:61], v[8:9], 0, v[92:93]
	v_lshlrev_b32_e32 v8, 12, v85
	v_mov_b32_e32 v9, v72
	v_lshl_add_u64 v[8:9], s[36:37], 0, v[8:9]
	ds_write2_b32 v102, v1, v5 offset0:128 offset1:144
	ds_write2_b32 v102, v0, v4 offset1:16
	ds_write2st64_b32 v103, v16, v17 offset1:2
	ds_write2st64_b32 v104, v24, v25 offset1:2
	v_lshl_add_u64 v[8:9], v[8:9], 0, s[28:29]
	v_lshl_add_u64 v[8:9], v[8:9], 0, v[92:93]
	ds_read_b128 v[0:3], v110 offset:16
	ds_read_b128 v[4:7], v110
	ds_read_b128 v[10:13], v108 offset:16
	ds_read_b128 v[14:17], v108
	ds_read_b128 v[18:21], v106 offset:16
	ds_read_b128 v[22:25], v106
	ds_read_b128 v[26:29], v77 offset:16
	ds_read_b128 v[30:33], v77
	global_load_dwordx4 v[34:37], v[8:9], off
	global_load_dwordx4 v[38:41], v[60:61], off
	global_load_dwordx4 v[42:45], v[58:59], off
	global_load_dwordx4 v[54:57], v[46:47], off
	v_lshlrev_b32_e32 v62, 11, v53
	global_load_dwordx4 v[48:51], v[48:49], off
	v_mov_b32_e32 v63, v72
	global_load_dword v52, v52, s[54:55] offset:64
	v_lshl_add_u64 v[62:63], s[48:49], 0, v[62:63]
	v_lshl_add_u64 v[62:63], v[62:63], 0, s[28:29]
	v_lshl_add_u64 v[62:63], v[62:63], 0, v[92:93]
	s_waitcnt vmcnt(2)
	v_and_b32_e32 v67, 0xffff0000, v54
	v_lshlrev_b32_e32 v66, 16, v54
	s_waitcnt vmcnt(1)
	v_and_b32_e32 v65, 0xffff0000, v48
	v_lshlrev_b32_e32 v64, 16, v48
	s_waitcnt vmcnt(0) lgkmcnt(0)
	v_pk_add_f32 v[30:31], v[30:31], v[52:53] op_sel_hi:[1,0]
	v_pk_add_f32 v[32:33], v[32:33], v[52:53] op_sel_hi:[1,0]
	v_and_b32_e32 v69, 0xffff0000, v49
	v_lshlrev_b32_e32 v68, 16, v49
	v_and_b32_e32 v49, 0xffff0000, v55
	v_lshlrev_b32_e32 v48, 16, v55
	v_pk_add_f32 v[26:27], v[26:27], v[52:53] op_sel_hi:[1,0]
	v_and_b32_e32 v55, 0xffff0000, v50
	v_lshlrev_b32_e32 v54, 16, v50
	v_pk_add_f32 v[28:29], v[28:29], v[52:53] op_sel_hi:[1,0]
	v_and_b32_e32 v53, 0xffff0000, v51
	v_lshlrev_b32_e32 v52, 16, v51
	v_and_b32_e32 v71, 0xffff0000, v56
	v_lshlrev_b32_e32 v70, 16, v56
	v_and_b32_e32 v51, 0xffff0000, v57
	v_lshlrev_b32_e32 v50, 16, v57
	v_pk_mul_f32 v[30:31], v[30:31], v[64:65]
	v_pk_mul_f32 v[32:33], v[32:33], v[68:69]
	v_pk_mul_f32 v[26:27], v[26:27], v[54:55]
	v_pk_mul_f32 v[28:29], v[28:29], v[52:53]
	v_pk_mul_f32 v[30:31], v[30:31], v[66:67]
	v_pk_mul_f32 v[32:33], v[32:33], v[48:49]
	v_pk_mul_f32 v[26:27], v[26:27], v[70:71]
	v_pk_mul_f32 v[28:29], v[28:29], v[50:51]
	v_bfe_u32 v54, v31, 16, 1
	v_bfe_u32 v55, v30, 16, 1
	v_add3_u32 v30, v30, v55, s84
	v_add3_u32 v31, v31, v54, s84
	v_cvt_pk_bf16_f32 v29, v28, v29
	v_cvt_pk_bf16_f32 v28, v26, v27
	v_cvt_pk_bf16_f32 v27, v32, v33
	v_perm_b32 v26, v31, v30, s85
	global_store_dwordx4 v[46:47], v[26:29], off
	global_load_dword v30, v87, s[54:55] offset:16
	v_and_b32_e32 v47, 0xffff0000, v42
	global_load_dwordx4 v[26:29], v[62:63], off
	v_lshlrev_b32_e32 v46, 16, v42
	v_and_b32_e32 v49, 0xffff0000, v43
	v_lshlrev_b32_e32 v48, 16, v43
	v_and_b32_e32 v43, 0xffff0000, v44
	v_lshlrev_b32_e32 v42, 16, v44
	v_and_b32_e32 v51, 0xffff0000, v45
	v_lshlrev_b32_e32 v50, 16, v45
	v_mov_b32_e32 v33, v72
	v_lshlrev_b32_e32 v32, 11, v73
	v_lshl_add_u64 v[32:33], s[48:49], 0, v[32:33]
	v_lshl_add_u64 v[32:33], v[32:33], 0, s[28:29]
	v_lshl_add_u64 v[32:33], v[32:33], 0, v[92:93]
	s_waitcnt vmcnt(1)
	v_pk_add_f32 v[22:23], v[22:23], v[30:31] op_sel_hi:[1,0]
	v_pk_add_f32 v[24:25], v[24:25], v[30:31] op_sel_hi:[1,0]
	s_waitcnt vmcnt(0)
	v_and_b32_e32 v45, 0xffff0000, v26
	v_lshlrev_b32_e32 v44, 16, v26
	v_and_b32_e32 v53, 0xffff0000, v27
	v_lshlrev_b32_e32 v52, 16, v27
	v_pk_add_f32 v[18:19], v[18:19], v[30:31] op_sel_hi:[1,0]
	v_and_b32_e32 v27, 0xffff0000, v28
	v_lshlrev_b32_e32 v26, 16, v28
	v_pk_add_f32 v[20:21], v[20:21], v[30:31] op_sel_hi:[1,0]
	v_and_b32_e32 v31, 0xffff0000, v29
	v_lshlrev_b32_e32 v30, 16, v29
	v_pk_mul_f32 v[22:23], v[22:23], v[44:45]
	v_pk_mul_f32 v[24:25], v[24:25], v[52:53]
	v_pk_mul_f32 v[18:19], v[18:19], v[26:27]
	v_pk_mul_f32 v[20:21], v[20:21], v[30:31]
	v_pk_mul_f32 v[22:23], v[22:23], v[46:47]
	v_pk_mul_f32 v[24:25], v[24:25], v[48:49]
	v_pk_mul_f32 v[18:19], v[18:19], v[42:43]
	v_pk_mul_f32 v[20:21], v[20:21], v[50:51]
	v_bfe_u32 v42, v23, 16, 1
	v_bfe_u32 v43, v22, 16, 1
	v_add3_u32 v22, v22, v43, s84
	v_add3_u32 v23, v23, v42, s84
	v_cvt_pk_bf16_f32 v21, v20, v21
	v_cvt_pk_bf16_f32 v20, v18, v19
	v_cvt_pk_bf16_f32 v19, v24, v25
	v_perm_b32 v18, v23, v22, s85
	global_store_dwordx4 v[58:59], v[18:21], off
	global_load_dwordx4 v[18:21], v[32:33], off
	v_and_b32_e32 v27, 0xffff0000, v38
	global_load_dword v22, v87, s[54:55] offset:32
	v_lshlrev_b32_e32 v26, 16, v38
	v_and_b32_e32 v29, 0xffff0000, v39
	v_lshlrev_b32_e32 v28, 16, v39
	v_and_b32_e32 v31, 0xffff0000, v40
	v_lshlrev_b32_e32 v30, 16, v40
	v_and_b32_e32 v33, 0xffff0000, v41
	v_lshlrev_b32_e32 v32, 16, v41
	v_mov_b32_e32 v25, v72
	v_lshlrev_b32_e32 v24, 11, v85
	v_lshl_add_u64 v[24:25], s[48:49], 0, v[24:25]
	v_lshl_add_u64 v[24:25], v[24:25], 0, s[28:29]
	v_lshl_add_u64 v[24:25], v[24:25], 0, v[92:93]
	s_waitcnt vmcnt(1)
	v_and_b32_e32 v39, 0xffff0000, v18
	v_lshlrev_b32_e32 v38, 16, v18
	s_waitcnt vmcnt(0)
	v_pk_add_f32 v[14:15], v[14:15], v[22:23] op_sel_hi:[1,0]
	v_pk_add_f32 v[16:17], v[16:17], v[22:23] op_sel_hi:[1,0]
	v_and_b32_e32 v41, 0xffff0000, v19
	v_lshlrev_b32_e32 v40, 16, v19
	v_pk_add_f32 v[10:11], v[10:11], v[22:23] op_sel_hi:[1,0]
	v_and_b32_e32 v19, 0xffff0000, v20
	v_lshlrev_b32_e32 v18, 16, v20
	v_pk_add_f32 v[12:13], v[12:13], v[22:23] op_sel_hi:[1,0]
	v_and_b32_e32 v23, 0xffff0000, v21
	v_lshlrev_b32_e32 v22, 16, v21
	v_pk_mul_f32 v[14:15], v[14:15], v[38:39]
	v_pk_mul_f32 v[16:17], v[16:17], v[40:41]
	v_pk_mul_f32 v[10:11], v[10:11], v[18:19]
	v_pk_mul_f32 v[12:13], v[12:13], v[22:23]
	v_pk_mul_f32 v[14:15], v[14:15], v[26:27]
	v_pk_mul_f32 v[16:17], v[16:17], v[28:29]
	v_pk_mul_f32 v[10:11], v[10:11], v[30:31]
	v_pk_mul_f32 v[12:13], v[12:13], v[32:33]
	v_bfe_u32 v26, v15, 16, 1
	v_bfe_u32 v27, v14, 16, 1
	v_add3_u32 v14, v14, v27, s84
	v_add3_u32 v15, v15, v26, s84
	v_cvt_pk_bf16_f32 v13, v12, v13
	v_cvt_pk_bf16_f32 v12, v10, v11
	v_cvt_pk_bf16_f32 v11, v16, v17
	v_perm_b32 v10, v15, v14, s85
	global_store_dwordx4 v[60:61], v[10:13], off
	global_load_dword v14, v87, s[54:55] offset:48
	v_and_b32_e32 v17, 0xffff0000, v34
	global_load_dwordx4 v[10:13], v[24:25], off
	v_lshlrev_b32_e32 v16, 16, v34
	v_and_b32_e32 v19, 0xffff0000, v35
	v_lshlrev_b32_e32 v18, 16, v35
	v_and_b32_e32 v21, 0xffff0000, v36
	v_lshlrev_b32_e32 v20, 16, v36
	v_and_b32_e32 v23, 0xffff0000, v37
	v_lshlrev_b32_e32 v22, 16, v37
	s_waitcnt vmcnt(1)
	v_pk_add_f32 v[4:5], v[4:5], v[14:15] op_sel_hi:[1,0]
	v_pk_add_f32 v[6:7], v[6:7], v[14:15] op_sel_hi:[1,0]
	s_waitcnt vmcnt(0)
	v_and_b32_e32 v25, 0xffff0000, v10
	v_lshlrev_b32_e32 v24, 16, v10
	v_and_b32_e32 v27, 0xffff0000, v11
	v_lshlrev_b32_e32 v26, 16, v11
	v_pk_add_f32 v[0:1], v[0:1], v[14:15] op_sel_hi:[1,0]
	v_and_b32_e32 v11, 0xffff0000, v12
	v_lshlrev_b32_e32 v10, 16, v12
	v_pk_add_f32 v[2:3], v[2:3], v[14:15] op_sel_hi:[1,0]
	v_and_b32_e32 v15, 0xffff0000, v13
	v_lshlrev_b32_e32 v14, 16, v13
	v_pk_mul_f32 v[4:5], v[4:5], v[24:25]
	v_pk_mul_f32 v[6:7], v[6:7], v[26:27]
	v_pk_mul_f32 v[0:1], v[0:1], v[10:11]
	v_pk_mul_f32 v[2:3], v[2:3], v[14:15]
	v_pk_mul_f32 v[4:5], v[4:5], v[16:17]
	v_pk_mul_f32 v[6:7], v[6:7], v[18:19]
	v_pk_mul_f32 v[0:1], v[0:1], v[20:21]
	v_pk_mul_f32 v[2:3], v[2:3], v[22:23]
	v_cvt_pk_bf16_f32 v3, v2, v3
	v_cvt_pk_bf16_f32 v2, v0, v1
	v_cvt_pk_bf16_f32 v1, v6, v7
	v_cvt_pk_bf16_f32 v0, v4, v5
	global_store_dwordx4 v[8:9], v[0:3], off
	s_cbranch_execnz .LBB0_251

.LBB0_259:
	v_add_u32_e32 v68, s92, v116
	v_add_u32_e32 v70, v68, v120
	ds_read_b128 v[48:51], v70
	ds_read_b128 v[52:55], v70 offset:4096
	ds_read_b128 v[56:59], v70 offset:8192
	ds_read_b128 v[94:97], v70 offset:12288
	v_add_u32_e32 v70, v68, v121
	v_add_u32_e32 v71, v68, v122
	ds_read_b128 v[174:177], v71 offset:12288
	v_add_u32_e32 v68, v68, v123
	ds_read_b128 v[178:181], v68 offset:12288
	s_waitcnt lgkmcnt(0)
	v_mfma_f32_16x16x32_bf16 v[52:55], v[52:55], v[0:3], 0
	v_mfma_f32_16x16x32_bf16 v[98:101], v[56:59], v[0:3], 0
	ds_read_b128 v[56:59], v70 offset:12288
	v_mfma_f32_16x16x32_bf16 v[94:97], v[94:97], v[0:3], 0
	s_waitcnt lgkmcnt(0)
	v_mfma_f32_16x16x32_bf16 v[56:59], v[56:59], v[4:7], v[94:97]
	s_nop 5
	ds_read_b128 v[94:97], v70 offset:8192
	ds_read_b128 v[182:185], v71 offset:8192
	ds_read_b128 v[186:189], v68 offset:8192
	v_mfma_f32_16x16x32_bf16 v[56:59], v[174:177], v[8:11], v[56:59]
	ds_read_b128 v[174:177], v70
	ds_read_b128 v[190:193], v70 offset:4096
	ds_read_b128 v[194:197], v71
	ds_read_b128 v[198:201], v71 offset:4096
	v_mfma_f32_16x16x32_bf16 v[56:59], v[178:181], v[12:15], v[56:59]
	ds_read_b128 v[178:181], v68
	ds_read_b128 v[202:205], v68 offset:4096
	s_waitcnt lgkmcnt(0)
	v_mfma_f32_16x16x32_bf16 v[94:97], v[94:97], v[4:7], v[98:101]
	s_nop 3
	v_exp_f32_e64 v70, -|v56|
	v_exp_f32_e64 v73, -|v57|
	v_max_f32_e32 v68, v56, v56
	v_mfma_f32_16x16x32_bf16 v[48:51], v[48:51], v[0:3], 0
	v_add_f32_e32 v70, 1.0, v70
	v_log_f32_e32 v70, v70
	v_max_f32_e32 v68, 0, v68
	v_mfma_f32_16x16x32_bf16 v[94:97], v[182:185], v[8:11], v[94:97]
	v_add_f32_e32 v68, v68, v70
	v_max_f32_e32 v70, v57, v57
	v_mfma_f32_16x16x32_bf16 v[52:55], v[190:193], v[4:7], v[52:55]
	v_max_f32_e32 v71, 0, v70
	v_add_f32_e32 v70, 1.0, v73
	v_max_f32_e32 v73, v58, v58
	v_mfma_f32_16x16x32_bf16 v[48:51], v[174:177], v[4:7], v[48:51]
	v_max_f32_e32 v193, 0, v73
	v_max_f32_e32 v73, v59, v59
	v_max_f32_e32 v183, 0, v73
	v_mfma_f32_16x16x32_bf16 v[174:177], v[186:189], v[12:15], v[94:97]
	v_log_f32_e32 v191, v70
	v_exp_f32_e64 v70, -|v58|
	v_mfma_f32_16x16x32_bf16 v[52:55], v[198:201], v[8:11], v[52:55]
	v_add_u32_e32 v198, s90, v159
	s_nop 3
	v_exp_f32_e64 v73, -|v174|
	v_exp_f32_e64 v94, -|v175|
	v_mfma_f32_16x16x32_bf16 v[52:55], v[202:205], v[12:15], v[52:55]
	v_exp_f32_e64 v96, -|v177|
	v_add_f32_e32 v73, 1.0, v73
	v_log_f32_e32 v190, v73
	v_max_f32_e32 v73, v175, v175
	v_max_f32_e32 v192, 0, v73
	v_add_f32_e32 v73, 1.0, v94
	v_exp_f32_e64 v94, -|v176|
	s_nop 0
	v_exp_f32_e64 v97, -|v52|
	v_add_f32_e32 v96, 1.0, v96
	v_mfma_f32_16x16x32_bf16 v[48:51], v[194:197], v[8:11], v[48:51]
	v_log_f32_e32 v194, v73
	v_max_f32_e32 v73, v176, v176
	v_log_f32_e32 v96, v96
	v_max_f32_e32 v182, 0, v73
	v_add_f32_e32 v73, 1.0, v94
	v_add_f32_e32 v97, 1.0, v97
	v_log_f32_e32 v94, v73
	v_max_f32_e32 v73, v177, v177
	v_log_f32_e32 v97, v97
	v_max_f32_e32 v73, 0, v73
	v_add_f32_e32 v185, v73, v96
	v_max_f32_e32 v73, v52, v52
	v_exp_f32_e64 v96, -|v54|
	v_max_f32_e32 v73, 0, v73
	v_add_f32_e32 v97, v73, v97
	v_exp_f32_e64 v73, -|v53|
	v_add_f32_e32 v96, 1.0, v96
	v_mfma_f32_16x16x32_bf16 v[48:51], v[178:181], v[12:15], v[48:51]
	v_log_f32_e32 v96, v96
	v_add_f32_e32 v73, 1.0, v73
	v_log_f32_e32 v181, v73
	v_max_f32_e32 v73, v54, v54
	v_max_f32_e32 v73, 0, v73
	v_add_f32_e32 v196, v73, v96
	s_nop 1
	v_exp_f32_e64 v96, -|v48|
	v_exp_f32_e64 v73, -|v55|
	v_exp_f32_e64 v100, -|v50|
	v_add_f32_e32 v70, 1.0, v70
	v_add_f32_e32 v96, 1.0, v96
	v_log_f32_e32 v96, v96
	v_add_f32_e32 v73, 1.0, v73
	v_log_f32_e32 v180, v73
	v_max_f32_e32 v73, v48, v48
	v_max_f32_e32 v73, 0, v73
	v_add_f32_e32 v73, v73, v96
	v_exp_f32_e64 v96, -|v49|
	v_max_f32_e32 v98, v53, v53
	v_log_f32_e32 v195, v70
	v_exp_f32_e64 v70, -|v59|
	v_add_f32_e32 v96, 1.0, v96
	v_log_f32_e32 v101, v96
	v_add_f32_e32 v96, 1.0, v100
	v_max_f32_e32 v179, 0, v98
	v_max_f32_e32 v98, v55, v55
	v_log_f32_e32 v96, v96
	v_max_f32_e32 v178, 0, v98
	v_max_f32_e32 v98, v49, v49
	v_exp_f32_e64 v100, -|v51|
	v_max_f32_e32 v99, 0, v98
	v_max_f32_e32 v98, v50, v50
	v_max_f32_e32 v98, 0, v98
	v_add_f32_e32 v70, 1.0, v70
	v_add_f32_e32 v197, v98, v96
	v_max_f32_e32 v96, v51, v51
	v_log_f32_e32 v95, v70
	v_max_f32_e32 v98, 0, v96
	v_add_f32_e32 v96, 1.0, v100
	v_cmp_lt_u32_e64 s[12:13], v198, v60
	v_max_f32_e32 v70, v174, v174
	v_log_f32_e32 v100, v96
	v_cndmask_b32_e64 v96, 0, -v73, s[12:13]
	v_or_b32_e32 v73, 48, v198
	v_max_f32_e32 v70, 0, v70
	v_or_b32_e32 v188, 33, v198
	v_or_b32_e32 v189, 32, v198
	v_or_b32_e32 v201, 49, v198
	v_cmp_lt_u32_e64 s[14:15], v73, v60
	v_or_b32_e32 v204, 50, v198
	v_pk_add_f32 v[70:71], v[70:71], v[190:191]
	v_cndmask_b32_e64 v184, 0, -v68, s[14:15]
	v_pk_add_f32 v[186:187], v[192:193], v[194:195]
	v_cmp_lt_u32_e64 s[16:17], v204, v60
	v_cmp_lt_u32_e32 vcc, v188, v61
	v_cmp_lt_u32_e64 s[18:19], v201, v61
	v_cmp_lt_u32_e64 s[8:9], v189, v60
	v_add_f32_e32 v73, 0, v184
	v_or_b32_e32 v202, 34, v198
	v_or_b32_e32 v203, 51, v198
	v_pk_add_f32 v[94:95], v[182:183], v[94:95]
	v_cndmask_b32_e64 v183, 0, -v187, s[16:17]
	v_cndmask_b32_e64 v182, 0, -v186, vcc
	v_cndmask_b32_e64 v187, 0, -v71, s[18:19]
	v_cndmask_b32_e64 v186, 0, -v70, s[8:9]
	v_pk_add_f32 v[70:71], v[186:187], v[72:73]
	v_cmp_lt_u32_e64 s[24:25], v203, v61
	v_cmp_lt_u32_e64 s[20:21], v202, v60
	v_pk_add_f32 v[70:71], v[182:183], v[70:71]
	v_cndmask_b32_e64 v189, 0, -v95, s[24:25]
	v_cndmask_b32_e64 v188, 0, -v94, s[20:21]
	v_pk_add_f32 v[70:71], v[188:189], v[70:71]
	ds_bpermute_b32 v95, v85, v71
	v_or_b32_e32 v68, 35, v198
	v_cmp_lt_u32_e64 s[10:11], v68, v61
	ds_bpermute_b32 v191, v87, v71
	v_add_f32_e32 v201, v176, v188
	v_cndmask_b32_e64 v94, 0, -v185, s[10:11]
	s_waitcnt lgkmcnt(0)
	v_pk_add_f32 v[70:71], v[94:95], v[70:71]
	ds_bpermute_b32 v190, v85, v70
	ds_bpermute_b32 v193, v87, v95
	ds_bpermute_b32 v192, v87, v70
	v_add_f32_e32 v185, v58, v183
	v_cndmask_b32_e64 v58, 0, v95, s[0:1]
	s_waitcnt lgkmcnt(0)
	ds_bpermute_b32 v68, v87, v190
	v_pk_add_f32 v[70:71], v[70:71], v[190:191]
	v_cndmask_b32_e64 v73, 0, v190, s[0:1]
	v_cndmask_b32_e64 v95, 0, v192, s[22:23]
	v_pk_add_f32 v[70:71], v[70:71], v[192:193]
	v_add_f32_e32 v73, v73, v95
	s_waitcnt lgkmcnt(0)
	v_cndmask_b32_e64 v95, 0, v68, s[4:5]
	v_pk_add_f32 v[194:195], v[70:71], v[68:69]
	v_cndmask_b32_e64 v68, 0, v191, s[22:23]
	v_add_f32_e32 v58, v58, v68
	v_cndmask_b32_e64 v68, 0, v193, s[4:5]
	v_mov_b32_e32 v70, v188
	v_add_f32_e32 v188, v58, v68
	v_mov_b32_e32 v58, v69
	v_pk_add_f32 v[58:59], v[58:59], v[188:189]
	v_add_f32_e32 v202, v177, v94
	v_pk_add_f32 v[176:177], v[72:73], v[94:95]
	v_mov_b32_e32 v71, v195
	v_add_f32_e32 v68, v58, v59
	v_pk_add_f32 v[70:71], v[70:71], v[176:177]
	v_add_f32_e32 v68, 0, v68
	v_add_f32_e32 v204, v175, v182
	v_mov_b32_e32 v94, v182
	v_mov_b32_e32 v95, v174
	v_mov_b32_e32 v174, v70
	v_mov_b32_e32 v175, v186
	v_exp_f32_e32 v177, v68
	v_mov_b32_e32 v68, v189
	v_mov_b32_e32 v69, v57
	v_mov_b32_e32 v73, v187
	v_pk_add_f32 v[94:95], v[94:95], v[174:175]
	v_pk_add_f32 v[68:69], v[68:69], v[72:73]
	v_pk_mov_b32 v[174:175], v[182:183], v[58:59] op_sel:[1,0]
	v_add_f32_e32 v186, v58, v185
	v_pk_add_f32 v[174:175], v[174:175], v[68:69]
	v_mov_b32_e32 v57, v187
	v_mov_b32_e32 v185, v174
	v_pk_add_f32 v[56:57], v[56:57], v[184:185]
	v_add_f32_e32 v59, v68, v186
	v_add_f32_e32 v56, v58, v56
	v_add_f32_e32 v56, v56, v57
	v_exp_f32_e32 v56, v56
	v_exp_f32_e32 v59, v59
	v_add_f32_e32 v68, v174, v175
	v_exp_f32_e32 v68, v68
	v_cndmask_b32_e64 v187, 0, v56, s[14:15]
	v_add_f32_e32 v56, v201, v71
	v_add_f32_e32 v56, v176, v56
	v_exp_f32_e32 v56, v56
	v_add_f32_e32 v57, v202, v71
	v_add_f32_e32 v57, 0, v57
	v_or_b32_e32 v58, 2, v198
	v_cndmask_b32_e64 v189, 0, v56, s[20:21]
	v_or_b32_e32 v56, 16, v198
	v_cndmask_b32_e64 v185, 0, v59, s[16:17]
	v_exp_f32_e32 v188, v57
	v_or_b32_e32 v57, 17, v198
	v_cmp_lt_u32_e64 s[16:17], v56, v60
	v_cmp_lt_u32_e64 s[14:15], v58, v60
	v_cndmask_b32_e64 v186, 0, v68, s[18:19]
	v_cndmask_b32_e64 v56, 0, -v97, s[16:17]
	v_cndmask_b32_e64 v58, 0, -v197, s[14:15]
	v_or_b32_e32 v68, 18, v198
	v_pk_add_f32 v[174:175], v[178:179], v[180:181]
	v_cmp_lt_u32_e64 s[20:21], v57, v61
	v_add_f32_e32 v59, 0, v56
	v_add_f32_e32 v191, v50, v58
	v_or_b32_e32 v50, 19, v198
	v_cmp_lt_u32_e64 s[18:19], v68, v60
	v_cndmask_b32_e64 v175, 0, -v175, s[20:21]
	v_cndmask_b32_e64 v184, 0, v177, s[24:25]
	v_cndmask_b32_e64 v68, 0, -v196, s[18:19]
	v_cmp_lt_u32_e64 s[24:25], v50, v61
	v_add_f32_e32 v50, v175, v59
	v_add_f32_e32 v50, v68, v50
	v_cndmask_b32_e64 v174, 0, -v174, s[24:25]
	v_add_f32_e32 v50, v174, v50
	ds_bpermute_b32 v57, v85, v50
	ds_bpermute_b32 v176, v87, v50
	v_mov_b32_e32 v73, v53
	v_mov_b32_e32 v181, v194
	v_mov_b32_e32 v183, v195
	s_waitcnt lgkmcnt(0)
	ds_bpermute_b32 v177, v87, v57
	v_add_f32_e32 v50, v50, v57
	v_add_f32_e32 v179, v50, v176
	v_cndmask_b32_e64 v50, 0, v57, s[0:1]
	v_cndmask_b32_e64 v53, 0, v176, s[22:23]
	v_add_f32_e32 v180, v50, v53
	s_waitcnt lgkmcnt(0)
	v_cndmask_b32_e64 v182, 0, v177, s[4:5]
	v_pk_add_f32 v[180:181], v[180:181], v[182:183]
	v_add_f32_e32 v69, v54, v68
	v_mov_b32_e32 v53, v180
	v_mov_b32_e32 v57, v181
	v_add_f32_e32 v59, v55, v174
	v_pk_add_f32 v[52:53], v[52:53], v[56:57]
	v_pk_add_f32 v[54:55], v[72:73], v[174:175]
	v_add_f32_e32 v50, v59, v53
	v_add_f32_e32 v56, v69, v53
	v_add_f32_e32 v50, 0, v50
	v_add_f32_e32 v56, v54, v56
	v_exp_f32_e32 v56, v56
	v_exp_f32_e32 v50, v50
	v_mov_b32_e32 v69, v53
	v_add_u32_e32 v199, 1, v198
	v_pk_add_f32 v[54:55], v[68:69], v[54:55]
	v_or_b32_e32 v97, 3, v198
	v_cndmask_b32_e64 v68, 0, v56, s[18:19]
	v_cndmask_b32_e64 v69, 0, v50, s[24:25]
	v_add_f32_e32 v50, v54, v55
	v_add_f32_e32 v55, v52, v53
	v_pk_add_f32 v[52:53], v[98:99], v[100:101]
	v_cmp_lt_u32_e64 s[18:19], v199, v61
	v_add_f32_e32 v200, 0, v96
	v_cmp_lt_u32_e64 s[24:25], v97, v61
	v_cndmask_b32_e64 v57, 0, -v53, s[18:19]
	v_exp_f32_e32 v50, v50
	v_cndmask_b32_e64 v56, 0, -v52, s[24:25]
	v_add_f32_e32 v52, v57, v200
	v_add_f32_e32 v52, v58, v52
	v_add_f32_e32 v182, v56, v52
	ds_bpermute_b32 v183, v85, v182
	v_add_f32_e32 v52, v175, v54
	ds_bpermute_b32 v192, v87, v182
	v_add_f32_e32 v52, v52, v55
	v_exp_f32_e32 v52, v52
	s_waitcnt lgkmcnt(0)
	ds_bpermute_b32 v193, v87, v183
	v_cndmask_b32_e64 v178, 0, v183, s[0:1]
	v_cndmask_b32_e64 v176, 0, v192, s[22:23]
	v_cndmask_b32_e64 v99, 0, v52, s[16:17]
	v_pk_add_f32 v[52:53], v[178:179], v[176:177]
	s_waitcnt lgkmcnt(0)
	v_cndmask_b32_e64 v180, 0, v193, s[4:5]
	v_pk_add_f32 v[52:53], v[52:53], v[180:181]
	v_mov_b32_e32 v73, v49
	v_mov_b32_e32 v49, v52
	v_mov_b32_e32 v97, v53
	v_pk_add_f32 v[48:49], v[48:49], v[96:97]
	v_cndmask_b32_e64 v98, 0, v50, s[20:21]
	v_add_f32_e32 v100, v51, v56
	v_pk_add_f32 v[50:51], v[72:73], v[56:57]
	v_mov_b32_e32 v59, v49
	v_pk_add_f32 v[54:55], v[58:59], v[50:51]
	v_add_f32_e32 v51, v100, v49
	v_add_f32_e32 v52, v191, v49
	v_add_f32_e32 v48, v48, v49
	v_add_f32_e32 v49, v57, v54
	v_add_f32_e32 v51, 0, v51
	v_add_f32_e32 v50, v50, v52
	v_add_f32_e32 v52, v54, v55
	v_add_f32_e32 v48, v49, v48
	v_exp_f32_e32 v51, v51
	v_exp_f32_e32 v50, v50
	v_exp_f32_e32 v52, v52
	v_exp_f32_e32 v48, v48
	v_bfe_u32 v59, v68, 16, 1
	v_cndmask_b32_e64 v49, 0, v50, s[14:15]
	v_cndmask_b32_e64 v50, 0, v51, s[24:25]
	v_cndmask_b32_e64 v51, 0, v52, s[18:19]
	v_cndmask_b32_e64 v48, 0, v48, s[12:13]
	v_add_u32_e32 v52, s92, v75
	v_bfe_u32 v56, v48, 16, 1
	v_bfe_u32 v57, v51, 16, 1
	v_bfe_u32 v73, v50, 16, 1
	v_bfe_u32 v96, v49, 16, 1
	v_add3_u32 v59, v68, v59, s84
	v_add3_u32 v68, v52, v124, v117
	v_add3_u32 v191, v52, v125, v117
	v_add3_u32 v97, v51, v57, s84
	v_add3_u32 v100, v48, v56, s84
	v_add3_u32 v101, v49, v96, s84
	v_add3_u32 v73, v50, v73, s84
	ds_read2st64_b64 v[48:51], v68 offset0:32 offset1:36
	ds_read2st64_b64 v[54:57], v191 offset0:32 offset1:36
	v_bfe_u32 v58, v69, 16, 1
	v_add3_u32 v58, v69, v58, s84
	v_cvt_pk_bf16_f32 v98, v99, v98
	s_waitcnt lgkmcnt(0)
	v_mov_b32_e32 v174, v48
	v_mov_b32_e32 v175, v49
	v_mov_b32_e32 v176, v54
	v_mov_b32_e32 v177, v55
	v_perm_b32 v96, v97, v100, s85
	v_perm_b32 v99, v58, v59, s85
	v_perm_b32 v97, v73, v101, s85
	ds_read2st64_b64 v[178:181], v68 offset0:40 offset1:44
	v_mov_b32_e32 v54, v50
	v_mfma_f32_16x16x32_bf16 v[16:19], v[174:177], v[96:99], v[16:19]
	ds_read2st64_b64 v[174:177], v191 offset0:40 offset1:44
	v_mov_b32_e32 v55, v51
	s_waitcnt lgkmcnt(0)
	v_mov_b32_e32 v48, v178
	v_mov_b32_e32 v49, v179
	v_add_f32_e32 v190, v204, v71
	v_mov_b32_e32 v50, v174
	v_mov_b32_e32 v51, v175
	v_mfma_f32_16x16x32_bf16 v[20:23], v[54:57], v[96:99], v[20:23]
	v_add_f32_e32 v54, v70, v190
	v_exp_f32_e32 v58, v54
	ds_read2st64_b64 v[54:57], v68 offset0:48 offset1:52
	v_mfma_f32_16x16x32_bf16 v[24:27], v[48:51], v[96:99], v[24:27]
	ds_read2st64_b64 v[48:51], v191 offset0:48 offset1:52
	v_mov_b32_e32 v174, v180
	v_mov_b32_e32 v175, v181
	s_waitcnt lgkmcnt(0)
	v_mov_b32_e32 v178, v54
	v_mov_b32_e32 v179, v55
	v_mov_b32_e32 v180, v48
	v_add_f32_e32 v48, v95, v71
	v_mov_b32_e32 v181, v49
	v_mfma_f32_16x16x32_bf16 v[32:35], v[174:177], v[96:99], v[32:35]
	v_add_f32_e32 v59, v94, v48
	ds_read2st64_b64 v[68:71], v68 offset0:56 offset1:60
	ds_read2st64_b64 v[174:177], v191 offset0:56 offset1:60
	v_mov_b32_e32 v48, v56
	v_mov_b32_e32 v49, v57
	v_mfma_f32_16x16x32_bf16 v[28:31], v[178:181], v[96:99], v[28:31]
	s_waitcnt lgkmcnt(0)
	v_mov_b32_e32 v54, v68
	v_mov_b32_e32 v55, v69
	v_mov_b32_e32 v56, v174
	v_mov_b32_e32 v57, v175
	v_mfma_f32_16x16x32_bf16 v[36:39], v[48:51], v[96:99], v[36:39]
	v_exp_f32_e32 v48, v59
	v_mov_b32_e32 v174, v70
	v_mov_b32_e32 v175, v71
	v_cndmask_b32_e64 v49, 0, v188, s[10:11]
	v_cndmask_b32_e32 v50, 0, v58, vcc
	v_cndmask_b32_e64 v48, 0, v48, s[8:9]
	v_mfma_f32_16x16x32_bf16 v[40:43], v[54:57], v[96:99], v[40:43]
	v_bfe_u32 v51, v48, 16, 1
	v_bfe_u32 v54, v50, 16, 1
	v_bfe_u32 v55, v49, 16, 1
	v_mfma_f32_16x16x32_bf16 v[44:47], v[174:177], v[96:99], v[44:47]
	v_bfe_u32 v56, v189, 16, 1
	v_add3_u32 v174, v52, v126, v117
	v_add3_u32 v52, v52, v127, v117
	v_add3_u32 v69, v50, v54, s84
	v_add3_u32 v70, v48, v51, s84
	v_add3_u32 v73, v189, v56, s84
	v_add3_u32 v95, v49, v55, s84
	ds_read2st64_b64 v[48:51], v174 offset0:32 offset1:36
	ds_read2st64_b64 v[54:57], v52 offset0:32 offset1:36
	v_perm_b32 v94, v69, v70, s85
	s_waitcnt lgkmcnt(0)
	v_mov_b32_e32 v68, v48
	v_mov_b32_e32 v69, v49
	v_mov_b32_e32 v70, v54
	v_mov_b32_e32 v71, v55
	v_perm_b32 v95, v95, v73, s85
	v_cvt_pk_bf16_f32 v96, v187, v186
	v_cvt_pk_bf16_f32 v97, v185, v184
	ds_read2st64_b64 v[98:101], v174 offset0:40 offset1:44
	v_mov_b32_e32 v54, v50
	v_mfma_f32_16x16x32_bf16 v[16:19], v[68:71], v[94:97], v[16:19]
	ds_read2st64_b64 v[68:71], v52 offset0:40 offset1:44
	v_mov_b32_e32 v55, v51
	s_waitcnt lgkmcnt(0)
	v_mov_b32_e32 v48, v98
	v_mov_b32_e32 v49, v99
	v_mfma_f32_16x16x32_bf16 v[20:23], v[54:57], v[94:97], v[20:23]
	v_mov_b32_e32 v50, v68
	v_mov_b32_e32 v51, v69
	v_add_f32_e32 v54, v182, v183
	v_add_f32_e32 v58, v54, v192
	ds_read2st64_b64 v[54:57], v174 offset0:48 offset1:52
	v_mov_b32_e32 v68, v100
	v_mov_b32_e32 v69, v101
	v_mfma_f32_16x16x32_bf16 v[24:27], v[48:51], v[94:97], v[24:27]
	ds_read2st64_b64 v[48:51], v52 offset0:48 offset1:52
	s_waitcnt lgkmcnt(0)
	v_mov_b32_e32 v98, v54
	v_add_f32_e32 v54, v58, v193
	v_mfma_f32_16x16x32_bf16 v[32:35], v[68:71], v[94:97], v[32:35]
	v_add_f32_e32 v69, v54, v53
	v_mov_b32_e32 v100, v48
	v_mov_b32_e32 v48, v56
	ds_bpermute_b32 v56, v89, v69
	v_mov_b32_e32 v101, v49
	v_mov_b32_e32 v49, v57
	v_mov_b32_e32 v99, v55
	s_waitcnt lgkmcnt(0)
	v_max_f32_e32 v56, v56, v56
	v_max_f32_e32 v68, v69, v56
	ds_bpermute_b32 v70, v91, v68
	v_mfma_f32_16x16x32_bf16 v[36:39], v[48:51], v[94:97], v[36:39]
	ds_read2st64_b64 v[48:51], v174 offset0:56 offset1:60
	ds_read2st64_b64 v[52:55], v52 offset0:56 offset1:60
	s_waitcnt lgkmcnt(0)
	v_mov_b32_e32 v56, v48
	v_max_f32_e32 v48, v70, v70
	v_max_f32_e32 v48, v68, v48
	v_mov_b32_e32 v57, v49
	ds_bpermute_b32 v49, v93, v48
	v_mov_b32_e32 v58, v52
	v_mov_b32_e32 v59, v53
	v_mov_b32_e32 v52, v50
	v_mov_b32_e32 v53, v51
	s_waitcnt lgkmcnt(0)
	v_max_f32_e32 v49, v49, v49
	v_max_f32_e32 v48, v48, v49
	ds_bpermute_b32 v49, v173, v48
	v_mfma_f32_16x16x32_bf16 v[28:31], v[98:101], v[94:97], v[28:31]
	v_mfma_f32_16x16x32_bf16 v[40:43], v[56:59], v[94:97], v[40:43]
	v_mfma_f32_16x16x32_bf16 v[44:47], v[52:55], v[94:97], v[44:47]
	s_and_saveexec_b64 s[8:9], s[6:7]
	s_cbranch_execz .LBB0_256
	s_waitcnt lgkmcnt(0)
	v_max_f32_e32 v49, v49, v49
	v_max_f32_e32 v48, v48, v48
	v_max_f32_e32 v48, v48, v49
	ds_write_b32 v119, v48
	s_branch .LBB0_256

.LBB0_445:
	v_add_u32_e32 v14, 0x400, v164
	ds_write2_b32 v164, v76, v78 offset1:16
	ds_write2_b32 v164, v77, v79 offset0:128 offset1:144
	ds_write2_b32 v14, v88, v92 offset1:16
	ds_write2_b32 v14, v89, v93 offset0:128 offset1:144
	ds_write2_b32 v164, v80, v82 offset0:32 offset1:48
	ds_write2_b32 v164, v81, v83 offset0:160 offset1:176
	ds_write2_b32 v14, v96, v98 offset0:32 offset1:48
	ds_write2_b32 v14, v97, v99 offset0:160 offset1:176
	ds_write2_b32 v164, v84, v86 offset0:64 offset1:80
	ds_write2_b32 v164, v85, v87 offset0:192 offset1:208
	ds_write2_b32 v14, v100, v102 offset0:64 offset1:80
	ds_write2_b32 v14, v101, v103 offset0:192 offset1:208
	ds_write2st64_b32 v165, v90, v91 offset1:2
	ds_write2st64_b32 v165, v104, v105 offset0:4 offset1:6
	ds_write2st64_b32 v166, v94, v95 offset1:2
	ds_write2st64_b32 v166, v106, v107 offset0:4 offset1:6
	ds_read_b128 v[0:3], v163 offset:16
	ds_read_b128 v[4:7], v163
	s_waitcnt lgkmcnt(0)
	v_cvt_pk_bf16_f32 v3, v2, v3
	v_cvt_pk_bf16_f32 v2, v0, v1
	v_cvt_pk_bf16_f32 v0, v4, v5
	v_mul_u32_u24_e32 v4, s4, v167
	v_cvt_pk_bf16_f32 v1, v6, v7
	v_lshlrev_b32_e32 v12, 1, v4
	ds_read_b128 v[4:7], v168
	ds_read_b128 v[8:11], v168 offset:16
	v_mov_b32_e32 v13, v65
	v_lshl_add_u64 v[12:13], s[56:57], 0, v[12:13]
	v_lshl_add_u64 v[12:13], v[12:13], 0, v[64:65]
	global_store_dwordx4 v[12:13], v[0:3], off
	s_waitcnt lgkmcnt(0)
	v_cvt_pk_bf16_f32 v3, v10, v11
	v_cvt_pk_bf16_f32 v0, v4, v5
	v_mul_u32_u24_e32 v4, s4, v169
	v_cvt_pk_bf16_f32 v2, v8, v9
	v_cvt_pk_bf16_f32 v1, v6, v7
	v_lshlrev_b32_e32 v12, 1, v4
	ds_read_b128 v[4:7], v170
	ds_read_b128 v[8:11], v170 offset:16
	v_mov_b32_e32 v13, v65
	v_lshl_add_u64 v[12:13], s[56:57], 0, v[12:13]
	v_lshl_add_u64 v[12:13], v[12:13], 0, v[64:65]
	global_store_dwordx4 v[12:13], v[0:3], off
	s_waitcnt lgkmcnt(0)
	v_cvt_pk_bf16_f32 v3, v10, v11
	v_cvt_pk_bf16_f32 v0, v4, v5
	v_mul_u32_u24_e32 v4, s4, v171
	v_cvt_pk_bf16_f32 v2, v8, v9
	v_cvt_pk_bf16_f32 v1, v6, v7
	v_lshlrev_b32_e32 v12, 1, v4
	ds_read_b128 v[4:7], v172
	ds_read_b128 v[8:11], v172 offset:16
	v_mov_b32_e32 v13, v65
	v_lshl_add_u64 v[12:13], s[56:57], 0, v[12:13]
	v_lshl_add_u64 v[12:13], v[12:13], 0, v[64:65]
	global_store_dwordx4 v[12:13], v[0:3], off
	s_waitcnt lgkmcnt(0)
	v_cvt_pk_bf16_f32 v3, v10, v11
	v_cvt_pk_bf16_f32 v0, v4, v5
	v_mul_u32_u24_e32 v4, s4, v173
	v_lshlrev_b32_e32 v4, 1, v4
	v_mov_b32_e32 v5, v65
	v_lshl_add_u64 v[4:5], s[56:57], 0, v[4:5]
	v_cvt_pk_bf16_f32 v2, v8, v9
	v_cvt_pk_bf16_f32 v1, v6, v7
	v_lshl_add_u64 v[4:5], v[4:5], 0, v[64:65]
	global_store_dwordx4 v[4:5], v[0:3], off
	ds_write2_b32 v164, v108, v110 offset1:16
	ds_write2_b32 v164, v109, v111 offset0:128 offset1:144
	ds_write2_b32 v14, v120, v124 offset1:16
	ds_write2_b32 v14, v121, v125 offset0:128 offset1:144
	ds_write2_b32 v164, v112, v114 offset0:32 offset1:48
	ds_write2_b32 v164, v113, v115 offset0:160 offset1:176
	ds_write2_b32 v14, v140, v142 offset0:32 offset1:48
	ds_write2_b32 v14, v141, v143 offset0:160 offset1:176
	ds_write2_b32 v164, v116, v118 offset0:64 offset1:80
	ds_write2_b32 v164, v117, v119 offset0:192 offset1:208
	ds_write2_b32 v14, v144, v146 offset0:64 offset1:80
	ds_write2_b32 v14, v145, v147 offset0:192 offset1:208
	ds_write2st64_b32 v165, v122, v123 offset1:2
	ds_write2st64_b32 v165, v148, v149 offset0:4 offset1:6
	ds_write2st64_b32 v166, v126, v127 offset1:2
	ds_write2st64_b32 v166, v150, v151 offset0:4 offset1:6
	ds_read_b128 v[0:3], v163 offset:16
	ds_read_b128 v[4:7], v163
	s_waitcnt lgkmcnt(0)
	v_cvt_pk_bf16_f32 v3, v2, v3
	v_cvt_pk_bf16_f32 v2, v0, v1
	v_cvt_pk_bf16_f32 v0, v4, v5
	v_mul_u32_u24_e32 v4, s4, v174
	v_cvt_pk_bf16_f32 v1, v6, v7
	v_lshlrev_b32_e32 v12, 1, v4
	ds_read_b128 v[4:7], v168
	ds_read_b128 v[8:11], v168 offset:16
	v_mov_b32_e32 v13, v65
	v_lshl_add_u64 v[12:13], s[56:57], 0, v[12:13]
	v_lshl_add_u64 v[12:13], v[12:13], 0, v[64:65]
	global_store_dwordx4 v[12:13], v[0:3], off
	s_waitcnt lgkmcnt(0)
	v_cvt_pk_bf16_f32 v3, v10, v11
	v_cvt_pk_bf16_f32 v0, v4, v5
	v_mul_u32_u24_e32 v4, s4, v175
	v_cvt_pk_bf16_f32 v2, v8, v9
	v_cvt_pk_bf16_f32 v1, v6, v7
	v_lshlrev_b32_e32 v12, 1, v4
	ds_read_b128 v[4:7], v170
	ds_read_b128 v[8:11], v170 offset:16
	v_mov_b32_e32 v13, v65
	v_lshl_add_u64 v[12:13], s[56:57], 0, v[12:13]
	v_lshl_add_u64 v[12:13], v[12:13], 0, v[64:65]
	global_store_dwordx4 v[12:13], v[0:3], off
	s_waitcnt lgkmcnt(0)
	v_cvt_pk_bf16_f32 v3, v10, v11
	v_cvt_pk_bf16_f32 v0, v4, v5
	v_mul_u32_u24_e32 v4, s4, v176
	v_cvt_pk_bf16_f32 v2, v8, v9
	v_cvt_pk_bf16_f32 v1, v6, v7
	v_lshlrev_b32_e32 v12, 1, v4
	ds_read_b128 v[4:7], v172
	ds_read_b128 v[8:11], v172 offset:16
	v_mov_b32_e32 v13, v65
	v_lshl_add_u64 v[12:13], s[56:57], 0, v[12:13]
	v_lshl_add_u64 v[12:13], v[12:13], 0, v[64:65]
	global_store_dwordx4 v[12:13], v[0:3], off
	s_waitcnt lgkmcnt(0)
	v_cvt_pk_bf16_f32 v3, v10, v11
	v_cvt_pk_bf16_f32 v0, v4, v5
	v_mul_u32_u24_e32 v4, s4, v177
	v_lshlrev_b32_e32 v4, 1, v4
	v_mov_b32_e32 v5, v65
	v_lshl_add_u64 v[4:5], s[56:57], 0, v[4:5]
	v_cvt_pk_bf16_f32 v2, v8, v9
	v_cvt_pk_bf16_f32 v1, v6, v7
	v_lshl_add_u64 v[4:5], v[4:5], 0, v[64:65]
	global_store_dwordx4 v[4:5], v[0:3], off
	s_cbranch_execnz .LBB0_429
.LBB0_446:
	s_nop 0
	v_cvt_pk_bf16_f32 v1, v88, v89
	v_cvt_pk_bf16_f32 v0, v76, v77
	v_cvt_pk_bf16_f32 v3, v92, v93
	v_cvt_pk_bf16_f32 v2, v78, v79
	v_cvt_pk_bf16_f32 v5, v96, v97
	v_cvt_pk_bf16_f32 v4, v80, v81
	v_cvt_pk_bf16_f32 v7, v98, v99
	v_cvt_pk_bf16_f32 v6, v82, v83
	v_cvt_pk_bf16_f32 v9, v100, v101
	v_cvt_pk_bf16_f32 v8, v84, v85
	v_cvt_pk_bf16_f32 v11, v102, v103
	v_cvt_pk_bf16_f32 v10, v86, v87
	v_cvt_pk_bf16_f32 v13, v104, v105
	v_cvt_pk_bf16_f32 v12, v90, v91
	v_cvt_pk_bf16_f32 v15, v106, v107
	v_cvt_pk_bf16_f32 v14, v94, v95
	v_cvt_pk_bf16_f32 v17, v120, v121
	v_cvt_pk_bf16_f32 v16, v108, v109
	ds_write2_b64 v193, v[0:1], v[16:17] offset1:4
	v_cvt_pk_bf16_f32 v1, v124, v125
	v_cvt_pk_bf16_f32 v0, v110, v111
	v_add_u32_e32 v16, 0x1000, v193
	ds_write2_b64 v16, v[2:3], v[0:1] offset0:32 offset1:36
	v_cvt_pk_bf16_f32 v1, v140, v141
	v_cvt_pk_bf16_f32 v0, v112, v113
	v_add_u32_e32 v2, 0x2000, v193
	ds_write2_b64 v2, v[4:5], v[0:1] offset0:64 offset1:68
	v_cvt_pk_bf16_f32 v1, v142, v143
	v_cvt_pk_bf16_f32 v0, v114, v115
	v_add_u32_e32 v2, 0x3000, v193
	ds_write2_b64 v2, v[6:7], v[0:1] offset0:96 offset1:100
	v_cvt_pk_bf16_f32 v1, v144, v145
	v_cvt_pk_bf16_f32 v0, v116, v117
	v_add_u32_e32 v2, 0x4000, v193
	ds_write2_b64 v2, v[8:9], v[0:1] offset0:128 offset1:132
	v_cvt_pk_bf16_f32 v1, v146, v147
	v_cvt_pk_bf16_f32 v0, v118, v119
	v_add_u32_e32 v2, 0x5000, v193
	ds_write2_b64 v2, v[10:11], v[0:1] offset0:160 offset1:164
	v_cvt_pk_bf16_f32 v1, v148, v149
	v_cvt_pk_bf16_f32 v0, v122, v123
	v_add_u32_e32 v2, 0x6000, v193
	ds_write2_b64 v2, v[12:13], v[0:1] offset0:192 offset1:196
	v_cvt_pk_bf16_f32 v1, v150, v151
	v_cvt_pk_bf16_f32 v0, v126, v127
	v_add_u32_e32 v2, 0x7000, v193
	ds_write2_b64 v2, v[14:15], v[0:1] offset0:224 offset1:228
	s_waitcnt vmcnt(0) lgkmcnt(0)
	s_barrier
	ds_read_b128 v[0:3], v194
	v_mul_u32_u24_e32 v4, s4, v128
	v_lshl_add_u64 v[12:13], s[56:57], 0, v[64:65]
	v_lshlrev_b32_e32 v64, 1, v4
	v_lshl_add_u64 v[8:9], v[12:13], 0, v[64:65]
	s_waitcnt lgkmcnt(0)
	global_store_dwordx4 v[8:9], v[0:3], off
	ds_read_b128 v[0:3], v195
	v_mul_u32_u24_e32 v8, s4, v178
	v_lshlrev_b32_e32 v64, 1, v8
	ds_read_b128 v[8:11], v196
	v_lshl_add_u64 v[14:15], v[12:13], 0, v[64:65]
	s_waitcnt lgkmcnt(1)
	global_store_dwordx4 v[14:15], v[0:3], off
	ds_read_b128 v[4:7], v194 offset:17408
	s_nop 0
	v_mul_u32_u24_e32 v0, s4, v179
	v_lshlrev_b32_e32 v64, 1, v0
	v_lshl_add_u64 v[0:1], v[12:13], 0, v[64:65]
	s_waitcnt lgkmcnt(1)
	global_store_dwordx4 v[0:1], v[8:11], off
	ds_read_b128 v[0:3], v197
	s_nop 0
	v_mul_u32_u24_e32 v8, s4, v180
	v_lshlrev_b32_e32 v64, 1, v8
	v_lshl_add_u64 v[14:15], v[12:13], 0, v[64:65]
	s_waitcnt lgkmcnt(0)
	global_store_dwordx4 v[14:15], v[0:3], off
	ds_read_b128 v[8:11], v198
	s_nop 0
	v_mul_u32_u24_e32 v0, s4, v181
	v_lshlrev_b32_e32 v64, 1, v0
	v_lshl_add_u64 v[0:1], v[12:13], 0, v[64:65]
	global_store_dwordx4 v[0:1], v[4:7], off
	v_mul_u32_u24_e32 v0, s4, v182
	v_lshlrev_b32_e32 v64, 1, v0
	v_lshl_add_u64 v[0:1], v[12:13], 0, v[64:65]
	s_waitcnt lgkmcnt(0)
	global_store_dwordx4 v[0:1], v[8:11], off
	ds_read_b128 v[0:3], v199
	v_mul_u32_u24_e32 v4, s4, v183
	v_lshlrev_b32_e32 v64, 1, v4
	ds_read_b128 v[4:7], v200
	v_lshl_add_u64 v[8:9], v[12:13], 0, v[64:65]
	s_waitcnt lgkmcnt(1)
	global_store_dwordx4 v[8:9], v[0:3], off
	s_nop 1
	v_mul_u32_u24_e32 v0, s4, v184
	v_lshlrev_b32_e32 v64, 1, v0
	v_lshl_add_u64 v[0:1], v[12:13], 0, v[64:65]
	s_waitcnt lgkmcnt(0)
	global_store_dwordx4 v[0:1], v[4:7], off
	s_branch .LBB0_429

.LBB0_506:
	v_readfirstlane_b32 s5, v129
	v_lshl_add_u64 v[114:115], s[18:19], 1, v[110:111]
	v_readfirstlane_b32 s6, v164
	s_mov_b32 m0, s5
	v_readfirstlane_b32 s7, v165
	v_lshl_add_u64 v[116:117], v[114:115], 0, s[20:21]
	global_load_lds_dwordx4 v[114:115], off
	s_mov_b32 m0, s6
	v_readfirstlane_b32 s8, v166
	v_add_lshl_u32 v64, v91, s18, 11
	v_lshl_add_u64 v[118:119], v[114:115], 0, s[22:23]
	global_load_lds_dwordx4 v[116:117], off
	s_mov_b32 m0, s7
	v_lshl_add_u64 v[120:121], v[114:115], 0, s[24:25]
	v_lshl_add_u64 v[122:123], v[112:113], 0, v[64:65]
	global_load_lds_dwordx4 v[118:119], off
	s_mov_b32 m0, s8
	v_add_u32_e32 v93, s18, v154
	global_load_lds_dwordx4 v[120:121], off
	global_load_dwordx4 v[114:117], v[122:123], off
	v_sub_u32_e32 v93, 0x7f, v93
	v_cvt_f32_i32_e32 v64, v93
	s_mov_b32 s18, 64
	s_and_b64 vcc, exec, s[0:1]
	s_mov_b64 s[0:1], 0
	v_mul_f32_e32 v64, v95, v64
	v_mul_f32_e32 v64, 0x3fb8aa3b, v64
	v_exp_f32_e32 v64, v64
	s_waitcnt vmcnt(0)
	v_lshlrev_b32_e32 v93, 16, v114
	v_and_b32_e32 v97, 0xffff0000, v114
	v_lshlrev_b32_e32 v99, 16, v115
	v_and_b32_e32 v101, 0xffff0000, v115
	v_lshlrev_b32_e32 v103, 16, v116
	v_and_b32_e32 v105, 0xffff0000, v116
	v_lshlrev_b32_e32 v107, 16, v117
	v_and_b32_e32 v109, 0xffff0000, v117
	v_mul_f32_e32 v93, v64, v93
	v_mul_f32_e32 v97, v64, v97
	v_mul_f32_e32 v99, v64, v99
	v_mul_f32_e32 v101, v64, v101
	v_mul_f32_e32 v103, v64, v103
	v_mul_f32_e32 v105, v64, v105
	v_mul_f32_e32 v107, v64, v107
	v_mul_f32_e32 v109, v64, v109
	v_bfe_u32 v114, v93, 16, 1
	v_bfe_u32 v115, v97, 16, 1
	v_bfe_u32 v116, v99, 16, 1
	v_bfe_u32 v117, v101, 16, 1
	v_bfe_u32 v118, v103, 16, 1
	v_bfe_u32 v119, v105, 16, 1
	v_bfe_u32 v120, v107, 16, 1
	v_bfe_u32 v121, v109, 16, 1
	v_add3_u32 v93, v93, v114, s53
	v_add3_u32 v97, v97, v115, s53
	v_add3_u32 v99, v99, v116, s53
	v_add3_u32 v101, v101, v117, s53
	v_add3_u32 v103, v103, v118, s53
	v_add3_u32 v105, v105, v119, s53
	v_add3_u32 v107, v107, v120, s53
	v_add3_u32 v109, v109, v121, s53
	ds_write_b16_d16_hi v167, v93 offset:16384
	global_load_dwordx4 v[114:117], v[122:123], off offset:16
	ds_write_b16_d16_hi v167, v97 offset:16512
	global_load_dwordx4 v[118:121], v[122:123], off offset:32
	ds_write_b16_d16_hi v168, v99 offset:16640
	global_load_dwordx4 v[122:125], v[122:123], off offset:48
	ds_write_b16_d16_hi v168, v101 offset:16768
	ds_write_b16_d16_hi v169, v103 offset:16896
	ds_write_b16_d16_hi v169, v105 offset:17024
	ds_write_b16_d16_hi v170, v107 offset:17152
	ds_write_b16_d16_hi v170, v109 offset:17280
	s_waitcnt vmcnt(0)
	v_lshlrev_b32_e32 v93, 16, v114
	v_and_b32_e32 v97, 0xffff0000, v114
	v_lshlrev_b32_e32 v99, 16, v115
	v_and_b32_e32 v101, 0xffff0000, v115
	v_lshlrev_b32_e32 v103, 16, v116
	v_and_b32_e32 v105, 0xffff0000, v116
	v_lshlrev_b32_e32 v107, 16, v117
	v_and_b32_e32 v109, 0xffff0000, v117
	v_lshlrev_b32_e32 v114, 16, v118
	v_and_b32_e32 v115, 0xffff0000, v118
	v_lshlrev_b32_e32 v116, 16, v119
	v_and_b32_e32 v117, 0xffff0000, v119
	v_lshlrev_b32_e32 v118, 16, v120
	v_and_b32_e32 v119, 0xffff0000, v120
	v_lshlrev_b32_e32 v120, 16, v121
	v_and_b32_e32 v121, 0xffff0000, v121
	v_lshlrev_b32_e32 v126, 16, v122
	v_and_b32_e32 v122, 0xffff0000, v122
	v_lshlrev_b32_e32 v127, 16, v123
	v_and_b32_e32 v123, 0xffff0000, v123
	v_lshlrev_b32_e32 v140, 16, v124
	v_and_b32_e32 v124, 0xffff0000, v124
	v_lshlrev_b32_e32 v141, 16, v125
	v_and_b32_e32 v125, 0xffff0000, v125
	v_mul_f32_e32 v93, v64, v93
	v_mul_f32_e32 v97, v64, v97
	v_mul_f32_e32 v99, v64, v99
	v_mul_f32_e32 v101, v64, v101
	v_mul_f32_e32 v103, v64, v103
	v_mul_f32_e32 v105, v64, v105
	v_mul_f32_e32 v107, v64, v107
	v_mul_f32_e32 v109, v64, v109
	v_mul_f32_e32 v114, v64, v114
	v_mul_f32_e32 v115, v64, v115
	v_mul_f32_e32 v116, v64, v116
	v_mul_f32_e32 v117, v64, v117
	v_mul_f32_e32 v118, v64, v118
	v_mul_f32_e32 v119, v64, v119
	v_mul_f32_e32 v120, v64, v120
	v_mul_f32_e32 v121, v64, v121
	v_mul_f32_e32 v126, v64, v126
	v_mul_f32_e32 v122, v64, v122
	v_mul_f32_e32 v127, v64, v127
	v_mul_f32_e32 v123, v64, v123
	v_mul_f32_e32 v140, v64, v140
	v_mul_f32_e32 v124, v64, v124
	v_mul_f32_e32 v141, v64, v141
	v_mul_f32_e32 v64, v64, v125
	v_bfe_u32 v125, v93, 16, 1
	v_bfe_u32 v142, v97, 16, 1
	v_bfe_u32 v143, v99, 16, 1
	v_bfe_u32 v144, v101, 16, 1
	v_bfe_u32 v145, v103, 16, 1
	v_bfe_u32 v146, v105, 16, 1
	v_bfe_u32 v147, v107, 16, 1
	v_bfe_u32 v182, v109, 16, 1
	v_bfe_u32 v183, v114, 16, 1
	v_bfe_u32 v184, v115, 16, 1
	v_bfe_u32 v185, v116, 16, 1
	v_bfe_u32 v186, v117, 16, 1
	v_bfe_u32 v187, v118, 16, 1
	v_bfe_u32 v188, v119, 16, 1
	v_bfe_u32 v189, v120, 16, 1
	v_bfe_u32 v190, v121, 16, 1
	v_bfe_u32 v191, v126, 16, 1
	v_bfe_u32 v192, v122, 16, 1
	v_bfe_u32 v193, v127, 16, 1
	v_bfe_u32 v194, v123, 16, 1
	v_bfe_u32 v195, v140, 16, 1
	v_bfe_u32 v196, v124, 16, 1
	v_bfe_u32 v197, v141, 16, 1
	v_bfe_u32 v198, v64, 16, 1
	v_add3_u32 v93, v93, v125, s53
	v_add3_u32 v97, v97, v142, s53
	v_add3_u32 v99, v99, v143, s53
	v_add3_u32 v101, v101, v144, s53
	v_add3_u32 v103, v103, v145, s53
	v_add3_u32 v105, v105, v146, s53
	v_add3_u32 v107, v107, v147, s53
	v_add3_u32 v109, v109, v182, s53
	v_add3_u32 v114, v114, v183, s53
	v_add3_u32 v115, v115, v184, s53
	v_add3_u32 v116, v116, v185, s53
	v_add3_u32 v117, v117, v186, s53
	v_add3_u32 v118, v118, v187, s53
	v_add3_u32 v119, v119, v188, s53
	v_add3_u32 v120, v120, v189, s53
	v_add3_u32 v121, v121, v190, s53
	v_add3_u32 v125, v126, v191, s53
	v_add3_u32 v122, v122, v192, s53
	v_add3_u32 v126, v127, v193, s53
	v_add3_u32 v123, v123, v194, s53
	v_add3_u32 v127, v140, v195, s53
	v_add3_u32 v124, v124, v196, s53
	v_add3_u32 v140, v141, v197, s53
	v_add3_u32 v64, v64, v198, s53
	ds_write_b16_d16_hi v171, v93 offset:17408
	ds_write_b16_d16_hi v171, v97 offset:17536
	ds_write_b16_d16_hi v172, v99 offset:17664
	ds_write_b16_d16_hi v172, v101 offset:17792
	ds_write_b16_d16_hi v173, v103 offset:17920
	ds_write_b16_d16_hi v173, v105 offset:18048
	ds_write_b16_d16_hi v174, v107 offset:18176
	ds_write_b16_d16_hi v174, v109 offset:18304
	ds_write_b16_d16_hi v167, v114 offset:18432
	ds_write_b16_d16_hi v167, v115 offset:18560
	ds_write_b16_d16_hi v168, v116 offset:18688
	ds_write_b16_d16_hi v168, v117 offset:18816
	ds_write_b16_d16_hi v169, v118 offset:18944
	ds_write_b16_d16_hi v169, v119 offset:19072
	ds_write_b16_d16_hi v170, v120 offset:19200
	ds_write_b16_d16_hi v170, v121 offset:19328
	ds_write_b16_d16_hi v171, v125 offset:19456
	ds_write_b16_d16_hi v171, v122 offset:19584
	ds_write_b16_d16_hi v172, v126 offset:19712
	ds_write_b16_d16_hi v172, v123 offset:19840
	ds_write_b16_d16_hi v173, v127 offset:19968
	ds_write_b16_d16_hi v173, v124 offset:20096
	ds_write_b16_d16_hi v174, v140 offset:20224
	ds_write_b16_d16_hi v174, v64 offset:20352
	s_waitcnt vmcnt(0)
	s_waitcnt lgkmcnt(0)
	s_barrier
	ds_read_b128 v[114:117], v175
	ds_read_b128 v[118:121], v176 offset:16384
	ds_read_b128 v[122:125], v176 offset:18432
	ds_read_b128 v[140:143], v176 offset:20480
	ds_read_b128 v[144:147], v175 offset:2048
	ds_read_b128 v[182:185], v176 offset:22528
	ds_read_b128 v[186:189], v176 offset:24576
	ds_read_b128 v[190:193], v176 offset:26624
	ds_read_b128 v[194:197], v176 offset:28672
	ds_read_b128 v[198:201], v176 offset:30720
	ds_read_b128 v[202:205], v177
	ds_read_b128 v[206:209], v177 offset:2048
	ds_read_b128 v[210:213], v178 offset:16384
	ds_read_b128 v[214:217], v178 offset:18432
	ds_read_b128 v[218:221], v178 offset:20480
	ds_read_b128 v[222:225], v178 offset:22528
	ds_read_b128 v[226:229], v178 offset:24576
	ds_read_b128 v[230:233], v178 offset:26624
	ds_read_b128 v[234:237], v178 offset:28672
	ds_read_b128 v[238:241], v178 offset:30720
	s_waitcnt lgkmcnt(14)
	v_mfma_f32_16x16x32_bf16 v[0:3], v[114:117], v[118:121], v[0:3]
	s_waitcnt lgkmcnt(0)
	s_barrier
	v_mfma_f32_16x16x32_bf16 v[36:39], v[114:117], v[122:125], v[36:39]
	v_mfma_f32_16x16x32_bf16 v[40:43], v[114:117], v[140:143], v[40:43]
	v_mfma_f32_16x16x32_bf16 v[44:47], v[114:117], v[182:185], v[44:47]
	v_mfma_f32_16x16x32_bf16 v[48:51], v[114:117], v[186:189], v[48:51]
	v_mfma_f32_16x16x32_bf16 v[52:55], v[114:117], v[190:193], v[52:55]
	v_mfma_f32_16x16x32_bf16 v[56:59], v[114:117], v[194:197], v[56:59]
	v_mfma_f32_16x16x32_bf16 v[60:63], v[114:117], v[198:201], v[60:63]
	v_mfma_f32_16x16x32_bf16 v[4:7], v[144:147], v[118:121], v[4:7]
	v_mfma_f32_16x16x32_bf16 v[8:11], v[144:147], v[122:125], v[8:11]
	v_mfma_f32_16x16x32_bf16 v[12:15], v[144:147], v[140:143], v[12:15]
	v_mfma_f32_16x16x32_bf16 v[16:19], v[144:147], v[182:185], v[16:19]
	v_mfma_f32_16x16x32_bf16 v[20:23], v[144:147], v[186:189], v[20:23]
	v_mfma_f32_16x16x32_bf16 v[24:27], v[144:147], v[190:193], v[24:27]
	v_mfma_f32_16x16x32_bf16 v[28:31], v[144:147], v[194:197], v[28:31]
	v_mfma_f32_16x16x32_bf16 v[32:35], v[144:147], v[198:201], v[32:35]
	v_mfma_f32_16x16x32_bf16 v[0:3], v[202:205], v[210:213], v[0:3]
	v_mfma_f32_16x16x32_bf16 v[36:39], v[202:205], v[214:217], v[36:39]
	v_mfma_f32_16x16x32_bf16 v[40:43], v[202:205], v[218:221], v[40:43]
	v_mfma_f32_16x16x32_bf16 v[44:47], v[202:205], v[222:225], v[44:47]
	v_mfma_f32_16x16x32_bf16 v[48:51], v[202:205], v[226:229], v[48:51]
	v_mfma_f32_16x16x32_bf16 v[52:55], v[202:205], v[230:233], v[52:55]
	v_mfma_f32_16x16x32_bf16 v[56:59], v[202:205], v[234:237], v[56:59]
	v_mfma_f32_16x16x32_bf16 v[60:63], v[202:205], v[238:241], v[60:63]
	v_mfma_f32_16x16x32_bf16 v[4:7], v[206:209], v[210:213], v[4:7]
	v_mfma_f32_16x16x32_bf16 v[8:11], v[206:209], v[214:217], v[8:11]
	v_mfma_f32_16x16x32_bf16 v[12:15], v[206:209], v[218:221], v[12:15]
	v_mfma_f32_16x16x32_bf16 v[16:19], v[206:209], v[222:225], v[16:19]
	v_mfma_f32_16x16x32_bf16 v[20:23], v[206:209], v[226:229], v[20:23]
	v_mfma_f32_16x16x32_bf16 v[24:27], v[206:209], v[230:233], v[24:27]
	v_mfma_f32_16x16x32_bf16 v[28:31], v[206:209], v[234:237], v[28:31]
	v_mfma_f32_16x16x32_bf16 v[32:35], v[206:209], v[238:241], v[32:35]
	s_cbranch_vccnz .LBB0_506
	v_add_u32_e32 v91, 0x400, v148
	ds_write2_b32 v148, v0, v36 offset1:16
	ds_write2_b32 v148, v1, v37 offset0:128 offset1:144
	ds_write2_b32 v91, v2, v38 offset1:16
	ds_write2_b32 v91, v3, v39 offset0:128 offset1:144
	ds_write2_b32 v148, v40, v44 offset0:32 offset1:48
	ds_write2_b32 v148, v41, v45 offset0:160 offset1:176
	ds_write2_b32 v91, v42, v46 offset0:32 offset1:48
	ds_write2_b32 v91, v43, v47 offset0:160 offset1:176
	ds_write2_b32 v148, v48, v52 offset0:64 offset1:80
	ds_write2_b32 v148, v49, v53 offset0:192 offset1:208
	ds_write2_b32 v91, v50, v54 offset0:64 offset1:80
	ds_write2_b32 v91, v51, v55 offset0:192 offset1:208
	ds_write2st64_b32 v149, v56, v57 offset1:2
	ds_write2st64_b32 v149, v58, v59 offset0:4 offset1:6
	ds_write2st64_b32 v150, v60, v61 offset1:2
	ds_write2st64_b32 v150, v62, v63 offset0:4 offset1:6
	ds_read_b128 v[0:3], v67 offset:16
	ds_read_b128 v[36:39], v67
	s_lshl_b32 s0, s4, 15
	s_add_u32 s0, s33, s0
	s_addc_u32 s1, s44, 0
	s_waitcnt lgkmcnt(1)
	s_waitcnt lgkmcnt(0)
	v_cvt_pk_bf16_f32 v3, v2, v3
	v_cvt_pk_bf16_f32 v2, v0, v1
	v_cvt_pk_bf16_f32 v1, v38, v39
	v_cvt_pk_bf16_f32 v0, v36, v37
	ds_read_b128 v[36:39], v151
	ds_read_b128 v[40:43], v151 offset:16
	v_mov_b32_e32 v95, v65
	v_lshl_add_u64 v[44:45], s[0:1], 0, v[94:95]
	v_lshlrev_b32_e32 v64, 1, v66
	v_lshl_add_u64 v[44:45], v[44:45], 0, v[64:65]
	global_store_dwordx4 v[44:45], v[0:3], off
	s_waitcnt lgkmcnt(1)
	s_waitcnt lgkmcnt(0)
	v_cvt_pk_bf16_f32 v3, v42, v43
	v_cvt_pk_bf16_f32 v2, v40, v41
	v_cvt_pk_bf16_f32 v1, v38, v39
	v_cvt_pk_bf16_f32 v0, v36, v37
	ds_read_b128 v[36:39], v160
	ds_read_b128 v[40:43], v160 offset:16
	v_mov_b32_e32 v97, v65
	v_lshl_add_u64 v[44:45], s[0:1], 0, v[96:97]
	v_lshl_add_u64 v[44:45], v[44:45], 0, v[64:65]
	global_store_dwordx4 v[44:45], v[0:3], off
	s_waitcnt lgkmcnt(1)
	s_waitcnt lgkmcnt(0)
	v_cvt_pk_bf16_f32 v3, v42, v43
	v_cvt_pk_bf16_f32 v2, v40, v41
	v_cvt_pk_bf16_f32 v1, v38, v39
	v_cvt_pk_bf16_f32 v0, v36, v37
	ds_read_b128 v[36:39], v161
	ds_read_b128 v[40:43], v161 offset:16
	v_mov_b32_e32 v99, v65
	v_lshl_add_u64 v[44:45], s[0:1], 0, v[98:99]
	v_lshl_add_u64 v[44:45], v[44:45], 0, v[64:65]
	global_store_dwordx4 v[44:45], v[0:3], off
	s_waitcnt lgkmcnt(1)
	s_waitcnt lgkmcnt(0)
	v_mov_b32_e32 v101, v65
	v_cvt_pk_bf16_f32 v3, v42, v43
	v_cvt_pk_bf16_f32 v0, v36, v37
	v_lshl_add_u64 v[36:37], s[0:1], 0, v[100:101]
	v_cvt_pk_bf16_f32 v2, v40, v41
	v_cvt_pk_bf16_f32 v1, v38, v39
	v_lshl_add_u64 v[36:37], v[36:37], 0, v[64:65]
	global_store_dwordx4 v[36:37], v[0:3], off
	ds_write2_b32 v148, v4, v8 offset1:16
	ds_write2_b32 v148, v5, v9 offset0:128 offset1:144
	ds_write2_b32 v91, v6, v10 offset1:16
	ds_write2_b32 v91, v7, v11 offset0:128 offset1:144
	ds_write2_b32 v148, v12, v16 offset0:32 offset1:48
	ds_write2_b32 v148, v13, v17 offset0:160 offset1:176
	ds_write2_b32 v91, v14, v18 offset0:32 offset1:48
	ds_write2_b32 v91, v15, v19 offset0:160 offset1:176
	ds_write2_b32 v148, v20, v24 offset0:64 offset1:80
	ds_write2_b32 v148, v21, v25 offset0:192 offset1:208
	ds_write2_b32 v91, v22, v26 offset0:64 offset1:80
	ds_write2_b32 v91, v23, v27 offset0:192 offset1:208
	ds_write2st64_b32 v149, v28, v29 offset1:2
	ds_write2st64_b32 v149, v30, v31 offset0:4 offset1:6
	ds_write2st64_b32 v150, v32, v33 offset1:2
	ds_write2st64_b32 v150, v34, v35 offset0:4 offset1:6
	ds_read_b128 v[0:3], v67 offset:16
	ds_read_b128 v[4:7], v67
	v_mov_b32_e32 v103, v65
	v_mov_b32_e32 v105, v65
	v_mov_b32_e32 v107, v65
	s_waitcnt lgkmcnt(1)
	s_waitcnt lgkmcnt(0)
	v_cvt_pk_bf16_f32 v3, v2, v3
	v_cvt_pk_bf16_f32 v2, v0, v1
	v_cvt_pk_bf16_f32 v1, v6, v7
	v_cvt_pk_bf16_f32 v0, v4, v5
	ds_read_b128 v[4:7], v151
	ds_read_b128 v[8:11], v151 offset:16
	v_lshl_add_u64 v[12:13], s[0:1], 0, v[102:103]
	v_lshl_add_u64 v[12:13], v[12:13], 0, v[64:65]
	global_store_dwordx4 v[12:13], v[0:3], off
	s_waitcnt lgkmcnt(1)
	s_waitcnt lgkmcnt(0)
	v_cvt_pk_bf16_f32 v3, v10, v11
	v_cvt_pk_bf16_f32 v2, v8, v9
	v_cvt_pk_bf16_f32 v1, v6, v7
	v_cvt_pk_bf16_f32 v0, v4, v5
	ds_read_b128 v[4:7], v160
	ds_read_b128 v[8:11], v160 offset:16
	v_lshl_add_u64 v[12:13], s[0:1], 0, v[104:105]
	v_lshl_add_u64 v[12:13], v[12:13], 0, v[64:65]
	global_store_dwordx4 v[12:13], v[0:3], off
	s_waitcnt lgkmcnt(1)
	s_waitcnt lgkmcnt(0)
	v_cvt_pk_bf16_f32 v3, v10, v11
	v_cvt_pk_bf16_f32 v2, v8, v9
	v_cvt_pk_bf16_f32 v1, v6, v7
	v_cvt_pk_bf16_f32 v0, v4, v5
	ds_read_b128 v[4:7], v161
	ds_read_b128 v[8:11], v161 offset:16
	v_lshl_add_u64 v[12:13], s[0:1], 0, v[106:107]
	v_lshl_add_u64 v[12:13], v[12:13], 0, v[64:65]
	global_store_dwordx4 v[12:13], v[0:3], off
	s_waitcnt lgkmcnt(1)
	s_waitcnt lgkmcnt(0)
	v_mov_b32_e32 v109, v65
	v_cvt_pk_bf16_f32 v3, v10, v11
	v_cvt_pk_bf16_f32 v0, v4, v5
	v_lshl_add_u64 v[4:5], s[0:1], 0, v[108:109]
	v_cvt_pk_bf16_f32 v2, v8, v9
	v_cvt_pk_bf16_f32 v1, v6, v7
	v_lshl_add_u64 v[4:5], v[4:5], 0, v[64:65]
	global_store_dwordx4 v[4:5], v[0:3], off
	s_branch .LBB0_502

.LBB0_511:
	v_mov_b32_e32 v99, s18
	v_cmp_lt_u32_e64 s[8:9], s18, v93
	v_cmp_lt_u32_e64 s[14:15], s18, v91
	s_add_i32 s6, s18, 1
	s_add_i32 s7, s18, 2
	s_add_i32 s10, s18, 3
	v_cndmask_b32_e64 v101, 0, v99, s[14:15]
	v_cndmask_b32_e64 v99, 0, v99, s[8:9]
	s_cmp_eq_u32 s18, 0
	v_cndmask_b32_e64 v184, 0, v97, s[8:9]
	v_mad_u64_u32 v[182:183], s[8:9], v101, s55, v[116:117]
	v_mad_u64_u32 v[186:187], s[8:9], v99, s55, v[118:119]
	v_mov_b32_e32 v103, s6
	v_cmp_lt_u32_e64 s[0:1], s6, v91
	v_mov_b32_e32 v105, s7
	v_cmp_lt_u32_e64 s[12:13], s7, v91
	v_mov_b32_e32 v107, s10
	v_cmp_lt_u32_e64 s[4:5], s10, v91
	v_cmp_lt_u32_e32 vcc, s6, v93
	v_cmp_lt_u32_e64 s[6:7], s7, v93
	v_cmp_lt_u32_e64 s[10:11], s10, v93
	s_cselect_b64 s[8:9], -1, 0
	v_cndmask_b32_e64 v109, 0, v95, s[14:15]
	v_cndmask_b32_e64 v192, 0, v103, s[0:1]
	v_cndmask_b32_e64 v193, 0, v105, s[12:13]
	v_cndmask_b32_e64 v196, 0, v107, s[4:5]
	v_cndmask_b32_e32 v103, 0, v103, vcc
	v_cndmask_b32_e64 v105, 0, v105, s[6:7]
	v_cndmask_b32_e64 v107, 0, v107, s[10:11]
	v_cndmask_b32_e64 v185, 0, 1.0, s[8:9]
	v_sub_u32_e32 v183, v183, v101
	v_sub_u32_e32 v187, v187, v99
	v_cndmask_b32_e64 v214, 0, v95, s[0:1]
	v_mad_u64_u32 v[190:191], s[0:1], v192, s55, v[116:117]
	v_mad_u64_u32 v[194:195], s[0:1], v193, s55, v[116:117]
	v_mad_u64_u32 v[198:199], s[0:1], v196, s55, v[116:117]
	v_mad_u64_u32 v[202:203], s[0:1], v103, s55, v[118:119]
	v_mad_u64_u32 v[206:207], s[0:1], v105, s55, v[118:119]
	v_mad_u64_u32 v[210:211], s[0:1], v107, s55, v[118:119]
	v_sub_f32_e32 v226, v109, v185
	v_sub_f32_e32 v228, v184, v185
	global_load_dwordx4 v[182:185], v[182:183], off
	s_nop 0
	global_load_dwordx4 v[186:189], v[186:187], off
	v_sub_u32_e32 v191, v191, v192
	v_sub_u32_e32 v195, v195, v193
	v_sub_u32_e32 v199, v199, v196
	v_sub_u32_e32 v203, v203, v103
	v_sub_u32_e32 v207, v207, v105
	v_sub_u32_e32 v211, v211, v107
	global_load_dwordx4 v[190:193], v[190:191], off
	s_nop 0
	global_load_dwordx4 v[194:197], v[194:195], off
	s_nop 0
	global_load_dwordx4 v[198:201], v[198:199], off
	s_nop 0
	global_load_dwordx4 v[202:205], v[202:203], off
	s_nop 0
	global_load_dwordx4 v[206:209], v[206:207], off
	s_nop 0
	global_load_dwordx4 v[210:213], v[210:211], off
	v_cndmask_b32_e32 v220, 0, v97, vcc
	v_cndmask_b32_e64 v216, 0, v95, s[12:13]
	v_cndmask_b32_e64 v222, 0, v97, s[6:7]
	v_cndmask_b32_e64 v218, 0, v95, s[4:5]
	v_cndmask_b32_e64 v224, 0, v97, s[10:11]
	s_add_i32 s18, s18, 4
	s_cmp_ge_u32 s18, s57
	s_waitcnt vmcnt(0)
	v_and_b32_e32 v231, 0xffff0000, v182
	v_lshlrev_b32_e32 v230, 16, v182
	v_and_b32_e32 v233, 0xffff0000, v183
	v_lshlrev_b32_e32 v232, 16, v183
	v_and_b32_e32 v183, 0xffff0000, v184
	v_lshlrev_b32_e32 v182, 16, v184
	v_and_b32_e32 v235, 0xffff0000, v185
	v_lshlrev_b32_e32 v234, 16, v185
	v_and_b32_e32 v185, 0xffff0000, v186
	v_lshlrev_b32_e32 v184, 16, v186
	v_and_b32_e32 v237, 0xffff0000, v187
	v_lshlrev_b32_e32 v236, 16, v187
	v_and_b32_e32 v187, 0xffff0000, v188
	v_lshlrev_b32_e32 v186, 16, v188
	v_and_b32_e32 v239, 0xffff0000, v189
	v_lshlrev_b32_e32 v238, 16, v189
	v_pk_fma_f32 v[146:147], v[226:227], v[230:231], v[146:147] op_sel_hi:[0,1,1]
	v_and_b32_e32 v189, 0xffff0000, v190
	v_lshlrev_b32_e32 v188, 16, v190
	v_pk_fma_f32 v[144:145], v[226:227], v[232:233], v[144:145] op_sel_hi:[0,1,1]
	v_and_b32_e32 v233, 0xffff0000, v191
	v_lshlrev_b32_e32 v232, 16, v191
	v_pk_fma_f32 v[142:143], v[226:227], v[182:183], v[142:143] op_sel_hi:[0,1,1]
	v_and_b32_e32 v183, 0xffff0000, v192
	v_lshlrev_b32_e32 v182, 16, v192
	v_pk_fma_f32 v[140:141], v[226:227], v[234:235], v[140:141] op_sel_hi:[0,1,1]
	v_and_b32_e32 v227, 0xffff0000, v193
	v_lshlrev_b32_e32 v226, 16, v193
	v_pk_fma_f32 v[126:127], v[228:229], v[184:185], v[126:127] op_sel_hi:[0,1,1]
	v_and_b32_e32 v185, 0xffff0000, v202
	v_lshlrev_b32_e32 v184, 16, v202
	v_pk_fma_f32 v[124:125], v[228:229], v[236:237], v[124:125] op_sel_hi:[0,1,1]
	v_and_b32_e32 v237, 0xffff0000, v203
	v_lshlrev_b32_e32 v236, 16, v203
	v_pk_fma_f32 v[122:123], v[228:229], v[186:187], v[122:123] op_sel_hi:[0,1,1]
	v_and_b32_e32 v187, 0xffff0000, v204
	v_lshlrev_b32_e32 v186, 16, v204
	v_pk_fma_f32 v[120:121], v[228:229], v[238:239], v[120:121] op_sel_hi:[0,1,1]
	v_and_b32_e32 v229, 0xffff0000, v205
	v_lshlrev_b32_e32 v228, 16, v205
	v_and_b32_e32 v231, 0xffff0000, v194
	v_lshlrev_b32_e32 v230, 16, v194
	v_and_b32_e32 v241, 0xffff0000, v198
	v_lshlrev_b32_e32 v240, 16, v198
	v_and_b32_e32 v191, 0xffff0000, v195
	v_lshlrev_b32_e32 v190, 16, v195
	v_and_b32_e32 v195, 0xffff0000, v199
	v_lshlrev_b32_e32 v194, 16, v199
	v_and_b32_e32 v199, 0xffff0000, v196
	v_lshlrev_b32_e32 v198, 16, v196
	v_and_b32_e32 v243, 0xffff0000, v200
	v_lshlrev_b32_e32 v242, 16, v200
	v_and_b32_e32 v193, 0xffff0000, v197
	v_lshlrev_b32_e32 v192, 16, v197
	v_and_b32_e32 v197, 0xffff0000, v201
	v_lshlrev_b32_e32 v196, 16, v201
	v_and_b32_e32 v201, 0xffff0000, v206
	v_lshlrev_b32_e32 v200, 16, v206
	v_and_b32_e32 v235, 0xffff0000, v210
	v_lshlrev_b32_e32 v234, 16, v210
	v_and_b32_e32 v203, 0xffff0000, v207
	v_lshlrev_b32_e32 v202, 16, v207
	v_and_b32_e32 v207, 0xffff0000, v211
	v_lshlrev_b32_e32 v206, 16, v211
	v_and_b32_e32 v211, 0xffff0000, v208
	v_lshlrev_b32_e32 v210, 16, v208
	v_and_b32_e32 v205, 0xffff0000, v209
	v_lshlrev_b32_e32 v204, 16, v209
	v_pk_fma_f32 v[146:147], v[214:215], v[188:189], v[146:147] op_sel_hi:[0,1,1]
	v_pk_fma_f32 v[144:145], v[214:215], v[232:233], v[144:145] op_sel_hi:[0,1,1]
	v_pk_fma_f32 v[142:143], v[214:215], v[182:183], v[142:143] op_sel_hi:[0,1,1]
	v_pk_fma_f32 v[140:141], v[214:215], v[226:227], v[140:141] op_sel_hi:[0,1,1]
	v_pk_fma_f32 v[126:127], v[220:221], v[184:185], v[126:127] op_sel_hi:[0,1,1]
	v_pk_fma_f32 v[124:125], v[220:221], v[236:237], v[124:125] op_sel_hi:[0,1,1]
	v_pk_fma_f32 v[122:123], v[220:221], v[186:187], v[122:123] op_sel_hi:[0,1,1]
	v_pk_fma_f32 v[120:121], v[220:221], v[228:229], v[120:121] op_sel_hi:[0,1,1]
	v_and_b32_e32 v245, 0xffff0000, v212
	v_lshlrev_b32_e32 v244, 16, v212
	v_and_b32_e32 v209, 0xffff0000, v213
	v_lshlrev_b32_e32 v208, 16, v213
	v_pk_fma_f32 v[146:147], v[216:217], v[230:231], v[146:147] op_sel_hi:[0,1,1]
	v_pk_fma_f32 v[144:145], v[216:217], v[190:191], v[144:145] op_sel_hi:[0,1,1]
	v_pk_fma_f32 v[142:143], v[216:217], v[198:199], v[142:143] op_sel_hi:[0,1,1]
	v_pk_fma_f32 v[140:141], v[216:217], v[192:193], v[140:141] op_sel_hi:[0,1,1]
	v_pk_fma_f32 v[126:127], v[222:223], v[200:201], v[126:127] op_sel_hi:[0,1,1]
	v_pk_fma_f32 v[124:125], v[222:223], v[202:203], v[124:125] op_sel_hi:[0,1,1]
	v_pk_fma_f32 v[122:123], v[222:223], v[210:211], v[122:123] op_sel_hi:[0,1,1]
	v_pk_fma_f32 v[120:121], v[222:223], v[204:205], v[120:121] op_sel_hi:[0,1,1]
	v_pk_fma_f32 v[146:147], v[218:219], v[240:241], v[146:147] op_sel_hi:[0,1,1]
	v_pk_fma_f32 v[144:145], v[218:219], v[194:195], v[144:145] op_sel_hi:[0,1,1]
	v_pk_fma_f32 v[142:143], v[218:219], v[242:243], v[142:143] op_sel_hi:[0,1,1]
	v_pk_fma_f32 v[140:141], v[218:219], v[196:197], v[140:141] op_sel_hi:[0,1,1]
	v_pk_fma_f32 v[126:127], v[224:225], v[234:235], v[126:127] op_sel_hi:[0,1,1]
	v_pk_fma_f32 v[124:125], v[224:225], v[206:207], v[124:125] op_sel_hi:[0,1,1]
	v_pk_fma_f32 v[122:123], v[224:225], v[244:245], v[122:123] op_sel_hi:[0,1,1]
	v_pk_fma_f32 v[120:121], v[224:225], v[208:209], v[120:121] op_sel_hi:[0,1,1]
	s_cbranch_scc0 .LBB0_511
	v_cvt_pk_bf16_f32 v119, v140, v141
	v_cvt_pk_bf16_f32 v118, v142, v143
	v_cvt_pk_bf16_f32 v117, v144, v145
	v_cvt_pk_bf16_f32 v116, v146, v147
	v_lshl_or_b32 v64, v64, 7, v162
	ds_write_b128 v64, v[116:119]
	v_cvt_pk_bf16_f32 v119, v120, v121
	v_cvt_pk_bf16_f32 v118, v122, v123
	v_cvt_pk_bf16_f32 v117, v124, v125
	v_cvt_pk_bf16_f32 v116, v126, v127
	s_mov_b32 s4, 64
	s_mov_b64 s[0:1], 0
	s_and_b64 vcc, exec, s[42:43]
	ds_write_b128 v64, v[116:119] offset:4096
	s_cbranch_vccz .LBB0_510
	s_waitcnt vmcnt(0)
	s_waitcnt lgkmcnt(0)
	s_barrier
	ds_read_b128 v[114:117], v175
	ds_read_b128 v[118:121], v176 offset:16384
	ds_read_b128 v[122:125], v176 offset:18432
	ds_read_b128 v[140:143], v176 offset:20480
	s_add_i32 s59, s59, 1
	s_waitcnt lgkmcnt(2)
	v_mfma_f32_16x16x32_bf16 v[32:35], v[114:117], v[118:121], v[32:35]
	ds_read_b128 v[144:147], v175 offset:2048
	s_cmp_lg_u32 s59, 4
	s_waitcnt lgkmcnt(2)
	v_mfma_f32_16x16x32_bf16 v[44:47], v[114:117], v[122:125], v[44:47]
	ds_read_b128 v[182:185], v176 offset:22528
	s_waitcnt lgkmcnt(2)
	v_mfma_f32_16x16x32_bf16 v[40:43], v[114:117], v[140:143], v[40:43]
	ds_read_b128 v[186:189], v176 offset:24576
	s_waitcnt lgkmcnt(1)
	v_mfma_f32_16x16x32_bf16 v[52:55], v[114:117], v[182:185], v[52:55]
	ds_read_b128 v[190:193], v176 offset:26624
	s_waitcnt lgkmcnt(1)
	v_mfma_f32_16x16x32_bf16 v[48:51], v[114:117], v[186:189], v[48:51]
	ds_read_b128 v[194:197], v176 offset:28672
	s_waitcnt lgkmcnt(1)
	v_mfma_f32_16x16x32_bf16 v[56:59], v[114:117], v[190:193], v[56:59]
	ds_read_b128 v[198:201], v176 offset:30720
	s_waitcnt lgkmcnt(1)
	v_mfma_f32_16x16x32_bf16 v[60:63], v[114:117], v[194:197], v[60:63]
	ds_read_b128 v[202:205], v177
	s_waitcnt lgkmcnt(1)
	v_mfma_f32_16x16x32_bf16 v[36:39], v[114:117], v[198:201], v[36:39]
	ds_read_b128 v[114:117], v177 offset:2048
	v_mfma_f32_16x16x32_bf16 v[0:3], v[144:147], v[118:121], v[0:3]
	ds_read_b128 v[118:121], v178 offset:16384
	v_mfma_f32_16x16x32_bf16 v[8:11], v[144:147], v[122:125], v[8:11]
	ds_read_b128 v[122:125], v178 offset:18432
	v_mfma_f32_16x16x32_bf16 v[4:7], v[144:147], v[140:143], v[4:7]
	ds_read_b128 v[140:143], v178 offset:20480
	v_mfma_f32_16x16x32_bf16 v[16:19], v[144:147], v[182:185], v[16:19]
	ds_read_b128 v[182:185], v178 offset:22528
	v_mfma_f32_16x16x32_bf16 v[12:15], v[144:147], v[186:189], v[12:15]
	ds_read_b128 v[186:189], v178 offset:24576
	v_mfma_f32_16x16x32_bf16 v[20:23], v[144:147], v[190:193], v[20:23]
	ds_read_b128 v[190:193], v178 offset:26624
	v_mfma_f32_16x16x32_bf16 v[24:27], v[144:147], v[194:197], v[24:27]
	ds_read_b128 v[194:197], v178 offset:28672
	v_mfma_f32_16x16x32_bf16 v[28:31], v[144:147], v[198:201], v[28:31]
	ds_read_b128 v[144:147], v178 offset:30720
	s_waitcnt lgkmcnt(0)
	s_barrier
	v_mfma_f32_16x16x32_bf16 v[32:35], v[202:205], v[118:121], v[32:35]
	v_mfma_f32_16x16x32_bf16 v[44:47], v[202:205], v[122:125], v[44:47]
	v_mfma_f32_16x16x32_bf16 v[40:43], v[202:205], v[140:143], v[40:43]
	v_mfma_f32_16x16x32_bf16 v[52:55], v[202:205], v[182:185], v[52:55]
	v_mfma_f32_16x16x32_bf16 v[48:51], v[202:205], v[186:189], v[48:51]
	v_mfma_f32_16x16x32_bf16 v[56:59], v[202:205], v[190:193], v[56:59]
	v_mfma_f32_16x16x32_bf16 v[60:63], v[202:205], v[194:197], v[60:63]
	v_mfma_f32_16x16x32_bf16 v[36:39], v[202:205], v[144:147], v[36:39]
	v_mfma_f32_16x16x32_bf16 v[0:3], v[114:117], v[118:121], v[0:3]
	v_mfma_f32_16x16x32_bf16 v[8:11], v[114:117], v[122:125], v[8:11]
	v_mfma_f32_16x16x32_bf16 v[4:7], v[114:117], v[140:143], v[4:7]
	v_mfma_f32_16x16x32_bf16 v[16:19], v[114:117], v[182:185], v[16:19]
	v_mfma_f32_16x16x32_bf16 v[12:15], v[114:117], v[186:189], v[12:15]
	v_mfma_f32_16x16x32_bf16 v[20:23], v[114:117], v[190:193], v[20:23]
	v_mfma_f32_16x16x32_bf16 v[24:27], v[114:117], v[194:197], v[24:27]
	v_mfma_f32_16x16x32_bf16 v[28:31], v[114:117], v[144:147], v[28:31]
	s_cbranch_scc1 .LBB0_509
	ds_write2_b32 v148, v32, v44 offset1:16
	ds_write2_b32 v148, v33, v45 offset0:128 offset1:144
	v_or_b32_e32 v44, s39, v66
	s_ashr_i32 s39, s38, 31
	s_lshl_b64 s[0:1], s[38:39], 19
	s_add_u32 s0, s36, s0
	v_add_u32_e32 v33, 0x400, v148
	s_addc_u32 s1, s37, s1
	ds_write2_b32 v33, v34, v46 offset1:16
	ds_write2_b32 v33, v35, v47 offset0:128 offset1:144
	ds_write2_b32 v148, v40, v52 offset0:32 offset1:48
	ds_write2_b32 v148, v41, v53 offset0:160 offset1:176
	ds_write2_b32 v33, v42, v54 offset0:32 offset1:48
	ds_write2_b32 v33, v43, v55 offset0:160 offset1:176
	ds_write2_b32 v148, v48, v56 offset0:64 offset1:80
	ds_write2_b32 v148, v49, v57 offset0:192 offset1:208
	ds_write2_b32 v33, v50, v58 offset0:64 offset1:80
	ds_write2_b32 v33, v51, v59 offset0:192 offset1:208
	ds_write2st64_b32 v149, v60, v61 offset1:2
	ds_write2st64_b32 v149, v62, v63 offset0:4 offset1:6
	ds_write2st64_b32 v150, v36, v37 offset1:2
	ds_write2st64_b32 v150, v38, v39 offset0:4 offset1:6
	v_lshl_add_u64 v[42:43], s[0:1], 0, v[68:69]
	v_lshlrev_b32_e32 v64, 1, v44
	v_lshlrev_b32_e32 v32, 2, v44
	v_lshl_add_u64 v[58:59], v[42:43], 0, v[64:65]
	global_load_dwordx4 v[34:37], v32, s[40:41] offset:16
	global_load_dwordx4 v[38:41], v32, s[40:41]
	global_load_dwordx4 v[42:45], v[58:59], off
	ds_read_b128 v[46:49], v67
	ds_read_b128 v[50:53], v67 offset:16
	v_lshl_add_u64 v[54:55], s[0:1], 0, v[70:71]
	v_lshl_add_u64 v[60:61], v[54:55], 0, v[64:65]
	global_load_dwordx4 v[54:57], v[60:61], off
	s_waitcnt vmcnt(3) lgkmcnt(0)
	v_pk_mul_f32 v[36:37], v[52:53], v[36:37]
	s_waitcnt vmcnt(2)
	v_pk_mul_f32 v[40:41], v[48:49], v[40:41]
	v_pk_mul_f32 v[38:39], v[46:47], v[38:39]
	v_pk_mul_f32 v[34:35], v[50:51], v[34:35]
	s_waitcnt vmcnt(1)
	v_and_b32_e32 v47, 0xffff0000, v42
	v_lshlrev_b32_e32 v46, 16, v42
	v_and_b32_e32 v49, 0xffff0000, v44
	v_lshlrev_b32_e32 v48, 16, v44
	v_and_b32_e32 v51, 0xffff0000, v43
	v_lshlrev_b32_e32 v50, 16, v43
	v_and_b32_e32 v43, 0xffff0000, v45
	v_lshlrev_b32_e32 v42, 16, v45
	v_pk_mul_f32 v[38:39], v[38:39], v[46:47]
	v_pk_mul_f32 v[34:35], v[34:35], v[48:49]
	v_pk_mul_f32 v[40:41], v[40:41], v[50:51]
	v_pk_mul_f32 v[36:37], v[36:37], v[42:43]
	v_cvt_pk_bf16_f32 v37, v36, v37
	v_cvt_pk_bf16_f32 v36, v34, v35
	v_cvt_pk_bf16_f32 v35, v40, v41
	v_cvt_pk_bf16_f32 v34, v38, v39
	global_store_dwordx4 v[58:59], v[34:37], off
	global_load_dwordx4 v[34:37], v32, s[40:41]
	s_nop 0
	global_load_dwordx4 v[38:41], v32, s[40:41] offset:16
	ds_read_b128 v[42:45], v151
	ds_read_b128 v[46:49], v151 offset:16
	s_waitcnt vmcnt(3)
	v_and_b32_e32 v63, 0xffff0000, v54
	v_lshlrev_b32_e32 v62, 16, v54
	v_and_b32_e32 v111, 0xffff0000, v56
	v_lshlrev_b32_e32 v110, 16, v56
	v_and_b32_e32 v113, 0xffff0000, v55
	v_lshlrev_b32_e32 v112, 16, v55
	v_and_b32_e32 v55, 0xffff0000, v57
	v_lshlrev_b32_e32 v54, 16, v57
	v_lshl_add_u64 v[50:51], s[0:1], 0, v[72:73]
	v_lshl_add_u64 v[58:59], v[50:51], 0, v[64:65]
	global_load_dwordx4 v[50:53], v[58:59], off
	s_waitcnt vmcnt(2) lgkmcnt(1)
	v_pk_mul_f32 v[36:37], v[44:45], v[36:37]
	v_pk_mul_f32 v[34:35], v[42:43], v[34:35]
	s_waitcnt vmcnt(1) lgkmcnt(0)
	v_pk_mul_f32 v[40:41], v[48:49], v[40:41]
	v_pk_mul_f32 v[38:39], v[46:47], v[38:39]
	v_pk_mul_f32 v[34:35], v[34:35], v[62:63]
	v_pk_mul_f32 v[38:39], v[38:39], v[110:111]
	v_pk_mul_f32 v[36:37], v[36:37], v[112:113]
	v_pk_mul_f32 v[40:41], v[40:41], v[54:55]
	v_bfe_u32 v42, v39, 16, 1
	v_bfe_u32 v43, v38, 16, 1
	v_bfe_u32 v46, v41, 16, 1
	v_bfe_u32 v47, v40, 16, 1
	v_bfe_u32 v48, v37, 16, 1
	v_bfe_u32 v49, v36, 16, 1
	v_add3_u32 v49, v36, v49, s53
	v_add3_u32 v48, v37, v48, s53
	v_add3_u32 v37, v40, v47, s53
	v_add3_u32 v40, v41, v46, s53
	v_add3_u32 v36, v38, v43, s53
	v_add3_u32 v38, v39, v42, s53
	v_perm_b32 v36, v38, v36, s54
	v_cvt_pk_bf16_f32 v34, v34, v35
	v_perm_b32 v37, v40, v37, s54
	v_perm_b32 v35, v48, v49, s54
	global_store_dwordx4 v[60:61], v[34:37], off
	global_load_dwordx4 v[34:37], v32, s[40:41]
	s_nop 0
	global_load_dwordx4 v[38:41], v32, s[40:41] offset:16
	ds_read_b128 v[42:45], v160
	ds_read_b128 v[46:49], v160 offset:16
	s_waitcnt vmcnt(3)
	v_and_b32_e32 v63, 0xffff0000, v50
	v_lshlrev_b32_e32 v62, 16, v50
	v_and_b32_e32 v111, 0xffff0000, v52
	v_lshlrev_b32_e32 v110, 16, v52
	v_and_b32_e32 v113, 0xffff0000, v51
	v_lshlrev_b32_e32 v112, 16, v51
	v_and_b32_e32 v51, 0xffff0000, v53
	v_lshlrev_b32_e32 v50, 16, v53
	v_lshl_add_u64 v[54:55], s[0:1], 0, v[74:75]
	v_lshl_add_u64 v[60:61], v[54:55], 0, v[64:65]
	global_load_dwordx4 v[54:57], v[60:61], off
	s_waitcnt vmcnt(2) lgkmcnt(1)
	v_pk_mul_f32 v[36:37], v[44:45], v[36:37]
	v_pk_mul_f32 v[34:35], v[42:43], v[34:35]
	s_waitcnt vmcnt(1) lgkmcnt(0)
	v_pk_mul_f32 v[40:41], v[48:49], v[40:41]
	v_pk_mul_f32 v[38:39], v[46:47], v[38:39]
	v_pk_mul_f32 v[34:35], v[34:35], v[62:63]
	v_pk_mul_f32 v[38:39], v[38:39], v[110:111]
	v_pk_mul_f32 v[36:37], v[36:37], v[112:113]
	v_pk_mul_f32 v[40:41], v[40:41], v[50:51]
	v_bfe_u32 v42, v39, 16, 1
	v_bfe_u32 v43, v38, 16, 1
	v_bfe_u32 v46, v41, 16, 1
	v_bfe_u32 v47, v40, 16, 1
	v_bfe_u32 v48, v37, 16, 1
	v_bfe_u32 v49, v36, 16, 1
	v_add3_u32 v49, v36, v49, s53
	v_add3_u32 v48, v37, v48, s53
	v_add3_u32 v37, v40, v47, s53
	v_add3_u32 v40, v41, v46, s53
	v_add3_u32 v36, v38, v43, s53
	v_add3_u32 v38, v39, v42, s53
	v_perm_b32 v36, v38, v36, s54
	v_cvt_pk_bf16_f32 v34, v34, v35
	v_perm_b32 v37, v40, v37, s54
	v_perm_b32 v35, v48, v49, s54
	global_store_dwordx4 v[58:59], v[34:37], off
	global_load_dwordx4 v[34:37], v32, s[40:41]
	s_nop 0
	global_load_dwordx4 v[38:41], v32, s[40:41] offset:16
	ds_read_b128 v[42:45], v161
	ds_read_b128 v[46:49], v161 offset:16
	s_waitcnt vmcnt(3)
	v_and_b32_e32 v53, 0xffff0000, v54
	v_lshlrev_b32_e32 v52, 16, v54
	v_and_b32_e32 v59, 0xffff0000, v56
	v_lshlrev_b32_e32 v58, 16, v56
	v_and_b32_e32 v63, 0xffff0000, v55
	v_lshlrev_b32_e32 v62, 16, v55
	v_and_b32_e32 v55, 0xffff0000, v57
	v_lshlrev_b32_e32 v54, 16, v57
	v_lshl_add_u64 v[50:51], s[0:1], 0, v[76:77]
	s_waitcnt vmcnt(1) lgkmcnt(1)
	v_pk_mul_f32 v[36:37], v[44:45], v[36:37]
	v_pk_mul_f32 v[34:35], v[42:43], v[34:35]
	s_waitcnt vmcnt(0) lgkmcnt(0)
	v_pk_mul_f32 v[40:41], v[48:49], v[40:41]
	v_pk_mul_f32 v[38:39], v[46:47], v[38:39]
	v_pk_mul_f32 v[34:35], v[34:35], v[52:53]
	v_pk_mul_f32 v[38:39], v[38:39], v[58:59]
	v_pk_mul_f32 v[36:37], v[36:37], v[62:63]
	v_pk_mul_f32 v[40:41], v[40:41], v[54:55]
	v_bfe_u32 v44, v39, 16, 1
	v_bfe_u32 v45, v38, 16, 1
	v_bfe_u32 v46, v37, 16, 1
	v_bfe_u32 v47, v36, 16, 1
	v_bfe_u32 v48, v35, 16, 1
	v_bfe_u32 v49, v34, 16, 1
	v_add3_u32 v34, v34, v49, s53
	v_add3_u32 v48, v35, v48, s53
	v_add3_u32 v35, v36, v47, s53
	v_add3_u32 v46, v37, v46, s53
	v_add3_u32 v36, v38, v45, s53
	v_add3_u32 v38, v39, v44, s53
	v_cvt_pk_bf16_f32 v37, v40, v41
	v_perm_b32 v36, v38, v36, s54
	v_perm_b32 v35, v46, v35, s54
	v_perm_b32 v34, v48, v34, s54
	global_store_dwordx4 v[60:61], v[34:37], off
	ds_write2_b32 v148, v0, v8 offset1:16
	ds_write2_b32 v148, v1, v9 offset0:128 offset1:144
	ds_write2_b32 v33, v2, v10 offset1:16
	ds_write2_b32 v33, v3, v11 offset0:128 offset1:144
	ds_write2_b32 v148, v4, v16 offset0:32 offset1:48
	ds_write2_b32 v148, v5, v17 offset0:160 offset1:176
	ds_write2_b32 v33, v6, v18 offset0:32 offset1:48
	ds_write2_b32 v33, v7, v19 offset0:160 offset1:176
	ds_write2_b32 v148, v12, v20 offset0:64 offset1:80
	ds_write2_b32 v148, v13, v21 offset0:192 offset1:208
	ds_write2_b32 v33, v14, v22 offset0:64 offset1:80
	ds_write2_b32 v33, v15, v23 offset0:192 offset1:208
	ds_write2st64_b32 v149, v24, v25 offset1:2
	ds_write2st64_b32 v149, v26, v27 offset0:4 offset1:6
	ds_write2st64_b32 v150, v28, v29 offset1:2
	ds_write2st64_b32 v150, v30, v31 offset0:4 offset1:6
	v_lshl_add_u64 v[24:25], v[50:51], 0, v[64:65]
	global_load_dwordx4 v[0:3], v32, s[40:41]
	global_load_dwordx4 v[4:7], v[24:25], off
	global_load_dwordx4 v[8:11], v32, s[40:41] offset:16
	v_lshl_add_u64 v[16:17], s[0:1], 0, v[78:79]
	ds_read_b128 v[12:15], v67
	v_lshl_add_u64 v[26:27], v[16:17], 0, v[64:65]
	ds_read_b128 v[16:19], v67 offset:16
	global_load_dwordx4 v[20:23], v[26:27], off
	s_waitcnt vmcnt(3) lgkmcnt(1)
	v_pk_mul_f32 v[2:3], v[14:15], v[2:3]
	v_pk_mul_f32 v[0:1], v[12:13], v[0:1]
	s_waitcnt vmcnt(2)
	v_and_b32_e32 v13, 0xffff0000, v4
	v_lshlrev_b32_e32 v12, 16, v4
	s_waitcnt vmcnt(1) lgkmcnt(0)
	v_pk_mul_f32 v[10:11], v[18:19], v[10:11]
	v_pk_mul_f32 v[8:9], v[16:17], v[8:9]
	v_and_b32_e32 v15, 0xffff0000, v6
	v_lshlrev_b32_e32 v14, 16, v6
	v_and_b32_e32 v17, 0xffff0000, v5
	v_lshlrev_b32_e32 v16, 16, v5
	v_and_b32_e32 v5, 0xffff0000, v7
	v_lshlrev_b32_e32 v4, 16, v7
	v_pk_mul_f32 v[0:1], v[0:1], v[12:13]
	v_pk_mul_f32 v[6:7], v[8:9], v[14:15]
	v_pk_mul_f32 v[2:3], v[2:3], v[16:17]
	v_pk_mul_f32 v[4:5], v[10:11], v[4:5]
	v_bfe_u32 v10, v7, 16, 1
	v_bfe_u32 v8, v5, 16, 1
	v_bfe_u32 v9, v4, 16, 1
	v_bfe_u32 v11, v6, 16, 1
	v_bfe_u32 v12, v3, 16, 1
	v_bfe_u32 v13, v2, 16, 1
	v_bfe_u32 v14, v1, 16, 1
	v_bfe_u32 v15, v0, 16, 1
	v_add3_u32 v0, v0, v15, s53
	v_add3_u32 v14, v1, v14, s53
	v_add3_u32 v1, v2, v13, s53
	v_add3_u32 v12, v3, v12, s53
	v_add3_u32 v2, v6, v11, s53
	v_add3_u32 v6, v7, v10, s53
	v_add3_u32 v3, v4, v9, s53
	v_add3_u32 v4, v5, v8, s53
	v_perm_b32 v3, v4, v3, s54
	v_perm_b32 v2, v6, v2, s54
	v_perm_b32 v1, v12, v1, s54
	v_perm_b32 v0, v14, v0, s54
	global_store_dwordx4 v[24:25], v[0:3], off
	global_load_dwordx4 v[0:3], v32, s[40:41]
	s_nop 0
	global_load_dwordx4 v[4:7], v32, s[40:41] offset:16
	v_lshl_add_u64 v[8:9], s[0:1], 0, v[80:81]
	v_lshl_add_u64 v[24:25], v[8:9], 0, v[64:65]
	ds_read_b128 v[8:11], v151
	ds_read_b128 v[12:15], v151 offset:16
	s_waitcnt vmcnt(3)
	v_and_b32_e32 v29, 0xffff0000, v20
	v_lshlrev_b32_e32 v28, 16, v20
	v_and_b32_e32 v31, 0xffff0000, v22
	v_lshlrev_b32_e32 v30, 16, v22
	v_and_b32_e32 v35, 0xffff0000, v21
	v_lshlrev_b32_e32 v34, 16, v21
	v_and_b32_e32 v21, 0xffff0000, v23
	v_lshlrev_b32_e32 v20, 16, v23
	global_load_dwordx4 v[16:19], v[24:25], off
	s_waitcnt vmcnt(2) lgkmcnt(1)
	v_pk_mul_f32 v[2:3], v[10:11], v[2:3]
	v_pk_mul_f32 v[0:1], v[8:9], v[0:1]
	s_waitcnt vmcnt(1) lgkmcnt(0)
	v_pk_mul_f32 v[6:7], v[14:15], v[6:7]
	v_pk_mul_f32 v[4:5], v[12:13], v[4:5]
	v_pk_mul_f32 v[0:1], v[0:1], v[28:29]
	v_pk_mul_f32 v[4:5], v[4:5], v[30:31]
	v_pk_mul_f32 v[2:3], v[2:3], v[34:35]
	v_pk_mul_f32 v[6:7], v[6:7], v[20:21]
	v_bfe_u32 v8, v5, 16, 1
	v_bfe_u32 v9, v4, 16, 1
	v_bfe_u32 v12, v7, 16, 1
	v_bfe_u32 v13, v6, 16, 1
	v_bfe_u32 v14, v3, 16, 1
	v_bfe_u32 v15, v2, 16, 1
	v_add3_u32 v15, v2, v15, s53
	v_add3_u32 v14, v3, v14, s53
	v_add3_u32 v3, v6, v13, s53
	v_add3_u32 v6, v7, v12, s53
	v_add3_u32 v2, v4, v9, s53
	v_add3_u32 v4, v5, v8, s53
	v_perm_b32 v2, v4, v2, s54
	v_cvt_pk_bf16_f32 v0, v0, v1
	v_perm_b32 v3, v6, v3, s54
	v_perm_b32 v1, v14, v15, s54
	global_store_dwordx4 v[26:27], v[0:3], off
	global_load_dwordx4 v[0:3], v32, s[40:41]
	s_nop 0
	global_load_dwordx4 v[4:7], v32, s[40:41] offset:16
	v_lshl_add_u64 v[8:9], s[0:1], 0, v[82:83]
	v_lshl_add_u64 v[26:27], v[8:9], 0, v[64:65]
	ds_read_b128 v[8:11], v160
	ds_read_b128 v[12:15], v160 offset:16
	s_waitcnt vmcnt(3)
	v_and_b32_e32 v29, 0xffff0000, v16
	v_lshlrev_b32_e32 v28, 16, v16
	v_and_b32_e32 v31, 0xffff0000, v18
	v_lshlrev_b32_e32 v30, 16, v18
	v_and_b32_e32 v35, 0xffff0000, v17
	v_lshlrev_b32_e32 v34, 16, v17
	v_and_b32_e32 v17, 0xffff0000, v19
	v_lshlrev_b32_e32 v16, 16, v19
	global_load_dwordx4 v[20:23], v[26:27], off
	s_waitcnt vmcnt(2) lgkmcnt(1)
	v_pk_mul_f32 v[2:3], v[10:11], v[2:3]
	v_pk_mul_f32 v[0:1], v[8:9], v[0:1]
	s_waitcnt vmcnt(1) lgkmcnt(0)
	v_pk_mul_f32 v[6:7], v[14:15], v[6:7]
	v_pk_mul_f32 v[4:5], v[12:13], v[4:5]
	v_pk_mul_f32 v[0:1], v[0:1], v[28:29]
	v_pk_mul_f32 v[4:5], v[4:5], v[30:31]
	v_pk_mul_f32 v[2:3], v[2:3], v[34:35]
	v_pk_mul_f32 v[6:7], v[6:7], v[16:17]
	v_bfe_u32 v8, v5, 16, 1
	v_bfe_u32 v9, v4, 16, 1
	v_bfe_u32 v12, v7, 16, 1
	v_bfe_u32 v13, v6, 16, 1
	v_bfe_u32 v14, v3, 16, 1
	v_bfe_u32 v15, v2, 16, 1
	v_add3_u32 v15, v2, v15, s53
	v_add3_u32 v14, v3, v14, s53
	v_add3_u32 v3, v6, v13, s53
	v_add3_u32 v6, v7, v12, s53
	v_add3_u32 v2, v4, v9, s53
	v_add3_u32 v4, v5, v8, s53
	v_perm_b32 v2, v4, v2, s54
	v_cvt_pk_bf16_f32 v0, v0, v1
	v_perm_b32 v3, v6, v3, s54
	v_perm_b32 v1, v14, v15, s54
	global_store_dwordx4 v[24:25], v[0:3], off
	global_load_dwordx4 v[0:3], v32, s[40:41]
	s_nop 0
	global_load_dwordx4 v[4:7], v32, s[40:41] offset:16
	ds_read_b128 v[8:11], v161
	ds_read_b128 v[12:15], v161 offset:16
	s_waitcnt vmcnt(3)
	v_and_b32_e32 v17, 0xffff0000, v20
	v_lshlrev_b32_e32 v16, 16, v20
	v_and_b32_e32 v19, 0xffff0000, v22
	v_lshlrev_b32_e32 v18, 16, v22
	v_and_b32_e32 v25, 0xffff0000, v21
	v_lshlrev_b32_e32 v24, 16, v21
	v_and_b32_e32 v21, 0xffff0000, v23
	v_lshlrev_b32_e32 v20, 16, v23
	s_waitcnt vmcnt(1) lgkmcnt(1)
	v_pk_mul_f32 v[2:3], v[10:11], v[2:3]
	v_pk_mul_f32 v[0:1], v[8:9], v[0:1]
	s_waitcnt vmcnt(0) lgkmcnt(0)
	v_pk_mul_f32 v[6:7], v[14:15], v[6:7]
	v_pk_mul_f32 v[4:5], v[12:13], v[4:5]
	v_pk_mul_f32 v[0:1], v[0:1], v[16:17]
	v_pk_mul_f32 v[4:5], v[4:5], v[18:19]
	v_pk_mul_f32 v[2:3], v[2:3], v[24:25]
	v_pk_mul_f32 v[6:7], v[6:7], v[20:21]
	v_bfe_u32 v10, v5, 16, 1
	v_bfe_u32 v11, v4, 16, 1
	v_bfe_u32 v12, v3, 16, 1
	v_bfe_u32 v13, v2, 16, 1
	v_bfe_u32 v14, v1, 16, 1
	v_bfe_u32 v15, v0, 16, 1
	v_add3_u32 v0, v0, v15, s53
	v_add3_u32 v14, v1, v14, s53
	v_add3_u32 v1, v2, v13, s53
	v_add3_u32 v12, v3, v12, s53
	v_add3_u32 v2, v4, v11, s53
	v_add3_u32 v4, v5, v10, s53
	v_cvt_pk_bf16_f32 v3, v6, v7
	v_perm_b32 v2, v4, v2, s54
	v_perm_b32 v1, v12, v1, s54
	v_perm_b32 v0, v14, v0, s54
	global_store_dwordx4 v[26:27], v[0:3], off
	s_branch .LBB0_502

.LBB0_625:
	s_lshl_b64 s[56:57], s[56:57], 1
	v_readfirstlane_b32 s31, v129
	v_lshl_add_u64 v[98:99], v[60:61], 0, s[56:57]
	s_mov_b32 m0, s31
	v_readfirstlane_b32 s31, v162
	global_load_lds_dwordx4 v[98:99], off
	v_lshl_add_u64 v[100:101], v[98:99], 0, s[40:41]
	s_mov_b32 m0, s31
	v_readfirstlane_b32 s31, v163
	global_load_lds_dwordx4 v[100:101], off
	v_lshl_add_u64 v[100:101], v[98:99], 0, s[42:43]
	s_mov_b32 m0, s31
	v_readfirstlane_b32 s31, v164
	global_load_lds_dwordx4 v[100:101], off
	v_lshl_add_u64 v[98:99], v[98:99], 0, s[44:45]
	s_mov_b32 m0, s31
	v_readfirstlane_b32 s31, v165
	global_load_lds_dwordx4 v[98:99], off
	v_lshl_add_u64 v[98:99], v[92:93], 0, s[56:57]
	s_mov_b32 m0, s31
	v_readfirstlane_b32 s31, v166
	global_load_lds_dwordx4 v[98:99], off
	v_lshl_add_u64 v[100:101], v[98:99], 0, s[40:41]
	s_mov_b32 m0, s31
	v_readfirstlane_b32 s31, v167
	global_load_lds_dwordx4 v[100:101], off
	v_lshl_add_u64 v[100:101], v[98:99], 0, s[42:43]
	s_mov_b32 m0, s31
	v_readfirstlane_b32 s31, v168
	global_load_lds_dwordx4 v[100:101], off
	v_lshl_add_u64 v[98:99], v[98:99], 0, s[44:45]
	s_mov_b32 m0, s31
	s_mov_b64 s[56:57], 64
	global_load_lds_dwordx4 v[98:99], off
	s_waitcnt vmcnt(0)
	s_waitcnt vmcnt(0) lgkmcnt(0)
	s_barrier
	ds_read_b128 v[98:101], v169
	ds_read_b128 v[180:183], v170 offset:16384
	ds_read_b128 v[184:187], v170 offset:18432
	ds_read_b128 v[188:191], v170 offset:20480
	ds_read_b128 v[102:105], v169 offset:2048
	ds_read_b128 v[192:195], v170 offset:22528
	ds_read_b128 v[196:199], v170 offset:24576
	ds_read_b128 v[200:203], v170 offset:26624
	ds_read_b128 v[204:207], v170 offset:28672
	ds_read_b128 v[208:211], v170 offset:30720
	s_waitcnt lgkmcnt(8)
	v_mfma_f32_16x16x32_bf16 v[56:59], v[98:101], v[180:183], v[56:59]
	s_andn2_b64 vcc, exec, s[54:55]
	s_mov_b64 s[54:55], 0
	s_waitcnt lgkmcnt(7)
	v_mfma_f32_16x16x32_bf16 v[52:55], v[98:101], v[184:187], v[52:55]
	s_waitcnt lgkmcnt(6)
	v_mfma_f32_16x16x32_bf16 v[48:51], v[98:101], v[188:191], v[48:51]
	s_waitcnt lgkmcnt(4)
	v_mfma_f32_16x16x32_bf16 v[44:47], v[98:101], v[192:195], v[44:47]
	s_waitcnt lgkmcnt(3)
	v_mfma_f32_16x16x32_bf16 v[40:43], v[98:101], v[196:199], v[40:43]
	s_waitcnt lgkmcnt(2)
	v_mfma_f32_16x16x32_bf16 v[36:39], v[98:101], v[200:203], v[36:39]
	s_waitcnt lgkmcnt(1)
	v_mfma_f32_16x16x32_bf16 v[32:35], v[98:101], v[204:207], v[32:35]
	s_waitcnt lgkmcnt(0)
	v_mfma_f32_16x16x32_bf16 v[28:31], v[98:101], v[208:211], v[28:31]
	ds_read_b128 v[98:101], v171
	v_mfma_f32_16x16x32_bf16 v[24:27], v[102:105], v[184:187], v[24:27]
	v_mfma_f32_16x16x32_bf16 v[20:23], v[102:105], v[188:191], v[20:23]
	v_mfma_f32_16x16x32_bf16 v[16:19], v[102:105], v[192:195], v[16:19]
	v_mfma_f32_16x16x32_bf16 v[12:15], v[102:105], v[196:199], v[12:15]
	v_mfma_f32_16x16x32_bf16 v[8:11], v[102:105], v[200:203], v[8:11]
	v_mfma_f32_16x16x32_bf16 v[4:7], v[102:105], v[204:207], v[4:7]
	v_mfma_f32_16x16x32_bf16 v[0:3], v[102:105], v[208:211], v[0:3]
	ds_read_b128 v[102:105], v171 offset:2048
	ds_read_b128 v[180:183], v172 offset:16384
	ds_read_b128 v[184:187], v172 offset:18432
	ds_read_b128 v[188:191], v172 offset:20480
	ds_read_b128 v[192:195], v172 offset:22528
	ds_read_b128 v[196:199], v172 offset:24576
	ds_read_b128 v[200:203], v172 offset:26624
	ds_read_b128 v[204:207], v172 offset:28672
	ds_read_b128 v[208:211], v172 offset:30720
	s_waitcnt lgkmcnt(7)
	v_mfma_f32_16x16x32_bf16 v[56:59], v[98:101], v[180:183], v[56:59]
	s_waitcnt lgkmcnt(0)
	s_barrier
	v_mfma_f32_16x16x32_bf16 v[52:55], v[98:101], v[184:187], v[52:55]
	v_mfma_f32_16x16x32_bf16 v[48:51], v[98:101], v[188:191], v[48:51]
	v_mfma_f32_16x16x32_bf16 v[44:47], v[98:101], v[192:195], v[44:47]
	v_mfma_f32_16x16x32_bf16 v[40:43], v[98:101], v[196:199], v[40:43]
	v_mfma_f32_16x16x32_bf16 v[36:39], v[98:101], v[200:203], v[36:39]
	v_mfma_f32_16x16x32_bf16 v[32:35], v[98:101], v[204:207], v[32:35]
	v_mfma_f32_16x16x32_bf16 v[28:31], v[98:101], v[208:211], v[28:31]
	v_mfma_f32_16x16x32_bf16 v[24:27], v[102:105], v[184:187], v[24:27]
	v_mfma_f32_16x16x32_bf16 v[20:23], v[102:105], v[188:191], v[20:23]
	v_mfma_f32_16x16x32_bf16 v[16:19], v[102:105], v[192:195], v[16:19]
	v_mfma_f32_16x16x32_bf16 v[12:15], v[102:105], v[196:199], v[12:15]
	v_mfma_f32_16x16x32_bf16 v[8:11], v[102:105], v[200:203], v[8:11]
	v_mfma_f32_16x16x32_bf16 v[4:7], v[102:105], v[204:207], v[4:7]
	v_mfma_f32_16x16x32_bf16 v[0:3], v[102:105], v[208:211], v[0:3]
	s_cbranch_vccz .LBB0_625
	v_mul_f32_e32 v63, v63, v87
	v_mul_f32_e32 v63, v63, v91
	v_add_f32_e32 v87, v97, v63
	v_sub_f32_e32 v91, v87, v97
	v_sub_f32_e32 v63, v63, v91
	v_add_f32_e32 v63, v96, v63
	v_add_f32_e32 v91, v87, v63
	v_add_f32_e32 v60, v94, v95
	v_sub_f32_e32 v87, v91, v87
	v_sub_f32_e32 v63, v63, v87
	v_add_f32_e32 v87, v60, v91
	v_sub_f32_e32 v61, v60, v94
	v_sub_f32_e32 v94, v87, v60
	v_sub_f32_e32 v61, v95, v61
	v_sub_f32_e32 v95, v87, v94
	v_sub_f32_e32 v60, v60, v95
	v_sub_f32_e32 v91, v91, v94
	v_add_f32_e32 v60, v91, v60
	v_add_f32_e32 v91, v61, v63
	v_sub_f32_e32 v94, v91, v61
	v_sub_f32_e32 v95, v91, v94
	v_sub_f32_e32 v61, v61, v95
	v_sub_f32_e32 v63, v63, v94
	v_add_f32_e32 v60, v91, v60
	v_add_f32_e32 v61, v63, v61
	v_add_f32_e32 v63, v87, v60
	v_sub_f32_e32 v87, v63, v87
	v_sub_f32_e32 v60, v60, v87
	v_add_f32_e32 v60, v61, v60
	v_add_f32_e32 v60, v63, v60
	v_cmp_nlt_f32_e32 vcc, 1.0, v62
	s_mov_b32 s31, 0x33800000
	s_mov_b64 s[56:57], 0
	v_cndmask_b32_e32 v60, v173, v60, vcc
	v_cmp_neq_f32_e32 vcc, 1.0, v62
	s_nop 1
	v_cndmask_b32_e32 v60, v174, v60, vcc
	v_cmp_gt_f32_e32 vcc, s31, v62
	s_ashr_i32 s31, s30, 31
	s_lshl_b64 s[54:55], s[30:31], 15
	v_cndmask_b32_e64 v87, v60, -v62, vcc
	v_mul_f32_e32 v60, v87, v110
	v_mul_f32_e32 v60, 0x3fb8aa3b, v60
	v_mul_f32_e64 v61, v118, -v87
	v_mul_f32_e64 v63, v119, -v87
	v_mul_f32_e64 v91, v120, -v87
	v_exp_f32_e32 v176, v60
	v_mul_f32_e32 v61, 0x3fb8aa3b, v61
	v_mul_f32_e32 v63, 0x3fb8aa3b, v63
	v_mul_f32_e32 v91, 0x3fb8aa3b, v91
	v_exp_f32_e32 v61, v61
	v_exp_f32_e32 v63, v63
	v_exp_f32_e32 v180, v91
	v_mul_f32_e64 v91, v121, -v87
	v_mul_f32_e32 v91, 0x3fb8aa3b, v91
	v_exp_f32_e32 v181, v91
	v_lshl_add_u64 v[94:95], v[66:67], 0, s[54:55]
	v_mul_f32_e32 v56, v176, v56
	v_mul_f32_e32 v57, v176, v57
	v_readlane_b32 s54, v247, 13
	v_mul_f32_e32 v56, v61, v56
	v_mul_f32_e32 v57, v63, v57
	v_readlane_b32 s55, v247, 14
	v_mul_f32_e32 v60, v87, v111
	v_cndmask_b32_e64 v91, v56, 0, s[6:7]
	v_cndmask_b32_e64 v97, 0, v57, s[54:55]
	v_pk_mul_f32 v[56:57], v[176:177], v[58:59] op_sel_hi:[0,1]
	v_readlane_b32 s54, v247, 17
	v_mul_f32_e32 v60, 0x3fb8aa3b, v60
	v_pk_mul_f32 v[56:57], v[180:181], v[56:57]
	v_readlane_b32 s55, v247, 18
	v_exp_f32_e32 v104, v60
	v_cndmask_b32_e64 v56, v56, 0, s[54:55]
	v_readlane_b32 s54, v247, 15
	v_readlane_b32 s55, v247, 16
	v_bfe_u32 v101, v56, 16, 1
	v_cndmask_b32_e64 v57, v57, 0, s[54:55]
	v_bfe_u32 v99, v57, 16, 1
	v_add3_u32 v101, v56, v101, s47
	v_add3_u32 v57, v57, v99, s47
	v_mul_f32_e32 v52, v104, v52
	v_readlane_b32 s54, v247, 21
	v_cvt_pk_bf16_f32 v56, v91, v97
	v_perm_b32 v57, v57, v101, s33
	v_add_u32_e32 v58, v122, v108
	v_mul_f32_e32 v52, v61, v52
	v_readlane_b32 s55, v247, 22
	ds_write_b64 v58, v[56:57] offset:32768
	v_mul_f32_e32 v53, v104, v53
	v_cndmask_b32_e64 v56, v52, 0, s[54:55]
	v_readlane_b32 s54, v247, 19
	v_mul_f32_e32 v53, v63, v53
	v_readlane_b32 s55, v247, 20
	v_mul_f32_e32 v60, v87, v112
	v_mul_f32_e32 v60, 0x3fb8aa3b, v60
	v_cndmask_b32_e64 v57, 0, v53, s[54:55]
	v_pk_mul_f32 v[52:53], v[104:105], v[54:55] op_sel_hi:[0,1]
	v_readlane_b32 s54, v247, 25
	v_pk_mul_f32 v[52:53], v[180:181], v[52:53]
	v_readlane_b32 s55, v247, 26
	v_exp_f32_e32 v102, v60
	v_cndmask_b32_e64 v52, v52, 0, s[54:55]
	v_readlane_b32 s54, v247, 23
	v_readlane_b32 s55, v247, 24
	v_bfe_u32 v59, v52, 16, 1
	v_cndmask_b32_e64 v53, v53, 0, s[54:55]
	v_bfe_u32 v58, v53, 16, 1
	v_add3_u32 v59, v52, v59, s47
	v_add3_u32 v53, v53, v58, s47
	v_mul_f32_e32 v48, v102, v48
	v_readlane_b32 s54, v247, 29
	v_cvt_pk_bf16_f32 v52, v56, v57
	v_perm_b32 v53, v53, v59, s33
	v_add_u32_e32 v54, v122, v123
	v_mul_f32_e32 v48, v61, v48
	v_readlane_b32 s55, v247, 30
	ds_write_b64 v54, v[52:53] offset:32768
	v_mul_f32_e32 v49, v102, v49
	v_cndmask_b32_e64 v52, v48, 0, s[54:55]
	v_readlane_b32 s54, v247, 27
	v_mul_f32_e32 v49, v63, v49
	v_readlane_b32 s55, v247, 28
	v_mul_f32_e32 v60, v87, v113
	v_mul_f32_e32 v60, 0x3fb8aa3b, v60
	v_cndmask_b32_e64 v53, 0, v49, s[54:55]
	v_pk_mul_f32 v[48:49], v[102:103], v[50:51] op_sel_hi:[0,1]
	v_readlane_b32 s54, v247, 33
	v_pk_mul_f32 v[48:49], v[180:181], v[48:49]
	v_readlane_b32 s55, v247, 34
	v_exp_f32_e32 v100, v60
	v_cndmask_b32_e64 v48, v48, 0, s[54:55]
	v_readlane_b32 s54, v247, 31
	v_readlane_b32 s55, v247, 32
	v_bfe_u32 v55, v48, 16, 1
	v_cndmask_b32_e64 v49, v49, 0, s[54:55]
	v_bfe_u32 v54, v49, 16, 1
	v_add3_u32 v55, v48, v55, s47
	v_add3_u32 v49, v49, v54, s47
	v_mul_f32_e32 v44, v100, v44
	v_readlane_b32 s54, v247, 37
	v_cvt_pk_bf16_f32 v48, v52, v53
	v_perm_b32 v49, v49, v55, s33
	v_add_u32_e32 v50, v122, v124
	v_mul_f32_e32 v44, v61, v44
	v_readlane_b32 s55, v247, 38
	ds_write_b64 v50, v[48:49] offset:32768
	v_mul_f32_e32 v45, v100, v45
	v_cndmask_b32_e64 v48, v44, 0, s[54:55]
	v_readlane_b32 s54, v247, 35
	v_mul_f32_e32 v45, v63, v45
	v_readlane_b32 s55, v247, 36
	v_mul_f32_e32 v60, v87, v114
	v_mul_f32_e32 v60, 0x3fb8aa3b, v60
	v_cndmask_b32_e64 v49, 0, v45, s[54:55]
	v_pk_mul_f32 v[44:45], v[100:101], v[46:47] op_sel_hi:[0,1]
	v_readlane_b32 s54, v247, 41
	v_pk_mul_f32 v[44:45], v[180:181], v[44:45]
	v_readlane_b32 s55, v247, 42
	v_exp_f32_e32 v98, v60
	v_cndmask_b32_e64 v44, v44, 0, s[54:55]
	v_readlane_b32 s54, v247, 39
	v_readlane_b32 s55, v247, 40
	v_bfe_u32 v51, v44, 16, 1
	v_cndmask_b32_e64 v45, v45, 0, s[54:55]
	v_bfe_u32 v50, v45, 16, 1
	v_add3_u32 v51, v44, v51, s47
	v_add3_u32 v45, v45, v50, s47
	v_mul_f32_e32 v40, v98, v40
	v_readlane_b32 s54, v247, 45
	v_cvt_pk_bf16_f32 v44, v48, v49
	v_perm_b32 v45, v45, v51, s33
	v_add_u32_e32 v46, v122, v125
	v_mul_f32_e32 v40, v61, v40
	v_readlane_b32 s55, v247, 46
	ds_write_b64 v46, v[44:45] offset:32768
	v_mul_f32_e32 v41, v98, v41
	v_cndmask_b32_e64 v44, v40, 0, s[54:55]
	v_readlane_b32 s54, v247, 43
	v_mul_f32_e32 v41, v63, v41
	v_readlane_b32 s55, v247, 44
	v_mul_f32_e32 v60, v87, v115
	v_mul_f32_e32 v60, 0x3fb8aa3b, v60
	v_cndmask_b32_e64 v45, 0, v41, s[54:55]
	v_pk_mul_f32 v[40:41], v[98:99], v[42:43] op_sel_hi:[0,1]
	v_readlane_b32 s54, v247, 49
	v_pk_mul_f32 v[40:41], v[180:181], v[40:41]
	v_readlane_b32 s55, v247, 50
	v_exp_f32_e32 v96, v60
	v_cndmask_b32_e64 v40, v40, 0, s[54:55]
	v_readlane_b32 s54, v247, 47
	v_readlane_b32 s55, v247, 48
	v_bfe_u32 v47, v40, 16, 1
	v_cndmask_b32_e64 v41, v41, 0, s[54:55]
	v_bfe_u32 v46, v41, 16, 1
	v_add3_u32 v47, v40, v47, s47
	v_add3_u32 v41, v41, v46, s47
	v_mul_f32_e32 v36, v96, v36
	v_readlane_b32 s54, v247, 53
	v_cvt_pk_bf16_f32 v40, v44, v45
	v_perm_b32 v41, v41, v47, s33
	v_add_u32_e32 v42, v122, v126
	v_mul_f32_e32 v36, v61, v36
	v_readlane_b32 s55, v247, 54
	ds_write_b64 v42, v[40:41] offset:32768
	v_mul_f32_e32 v37, v96, v37
	v_cndmask_b32_e64 v40, v36, 0, s[54:55]
	v_readlane_b32 s54, v247, 51
	v_mul_f32_e32 v37, v63, v37
	v_readlane_b32 s55, v247, 52
	v_mul_f32_e32 v60, v87, v116
	v_mul_f32_e32 v60, 0x3fb8aa3b, v60
	v_cndmask_b32_e64 v41, 0, v37, s[54:55]
	v_pk_mul_f32 v[36:37], v[96:97], v[38:39] op_sel_hi:[0,1]
	v_readlane_b32 s54, v247, 57
	v_pk_mul_f32 v[36:37], v[180:181], v[36:37]
	v_readlane_b32 s55, v247, 58
	v_exp_f32_e32 v62, v60
	v_cndmask_b32_e64 v36, v36, 0, s[54:55]
	v_readlane_b32 s54, v247, 55
	v_readlane_b32 s55, v247, 56
	v_bfe_u32 v43, v36, 16, 1
	v_cndmask_b32_e64 v37, v37, 0, s[54:55]
	v_bfe_u32 v42, v37, 16, 1
	v_add3_u32 v43, v36, v43, s47
	v_add3_u32 v37, v37, v42, s47
	v_mul_f32_e32 v32, v62, v32
	v_readlane_b32 s54, v247, 61
	v_cvt_pk_bf16_f32 v36, v40, v41
	v_perm_b32 v37, v37, v43, s33
	v_add_u32_e32 v38, v122, v127
	v_mul_f32_e32 v32, v61, v32
	v_readlane_b32 s55, v247, 62
	v_mul_f32_e32 v60, v87, v117
	ds_write_b64 v38, v[36:37] offset:32768
	v_mul_f32_e32 v33, v62, v33
	v_cndmask_b32_e64 v36, v32, 0, s[54:55]
	v_readlane_b32 s54, v247, 59
	v_mul_f32_e32 v60, 0x3fb8aa3b, v60
	v_mul_f32_e32 v33, v63, v33
	v_readlane_b32 s55, v247, 60
	v_exp_f32_e32 v60, v60
	v_pk_mul_f32 v[24:25], v[104:105], v[24:25] op_sel_hi:[0,1]
	v_cndmask_b32_e64 v37, 0, v33, s[54:55]
	v_pk_mul_f32 v[32:33], v[62:63], v[34:35] op_sel_hi:[0,1]
	v_readlane_b32 s54, v247, 63
	v_pk_mul_f32 v[32:33], v[180:181], v[32:33]
	v_readlane_b32 s55, v246, 0
	v_cndmask_b32_e64 v32, v32, 0, s[60:61]
	v_cndmask_b32_e64 v33, v33, 0, s[54:55]
	v_bfe_u32 v38, v33, 16, 1
	v_bfe_u32 v39, v32, 16, 1
	v_add3_u32 v39, v32, v39, s47
	v_add3_u32 v33, v33, v38, s47
	v_mul_f32_e32 v28, v60, v28
	v_mul_f32_e32 v29, v60, v29
	v_cvt_pk_bf16_f32 v32, v36, v37
	v_perm_b32 v33, v33, v39, s33
	v_add_u32_e32 v34, v122, v140
	v_mul_f32_e32 v28, v61, v28
	v_mul_f32_e32 v29, v63, v29
	ds_write_b64 v34, v[32:33] offset:32768
	v_cndmask_b32_e64 v32, v28, 0, s[64:65]
	v_cndmask_b32_e64 v33, 0, v29, s[62:63]
	v_pk_mul_f32 v[28:29], v[60:61], v[30:31] op_sel_hi:[0,1]
	v_pk_mul_f32 v[28:29], v[180:181], v[28:29]
	v_cndmask_b32_e64 v28, v28, 0, s[68:69]
	v_cndmask_b32_e64 v29, v29, 0, s[66:67]
	v_bfe_u32 v34, v29, 16, 1
	v_bfe_u32 v35, v28, 16, 1
	v_add3_u32 v35, v28, v35, s47
	v_add3_u32 v29, v29, v34, s47
	v_cvt_pk_bf16_f32 v28, v32, v33
	v_perm_b32 v29, v29, v35, s33
	v_add_u32_e32 v30, v122, v141
	ds_write_b64 v30, v[28:29] offset:32768
	v_mul_f32_e64 v28, v142, -v87
	v_mul_f32_e64 v29, v143, -v87
	v_mul_f32_e32 v28, 0x3fb8aa3b, v28
	v_mul_f32_e32 v29, 0x3fb8aa3b, v29
	v_exp_f32_e32 v28, v28
	v_exp_f32_e32 v29, v29
	v_mul_f32_e64 v30, v144, -v87
	v_mul_f32_e64 v31, v145, -v87
	v_mul_f32_e32 v30, 0x3fb8aa3b, v30
	v_mul_f32_e32 v31, 0x3fb8aa3b, v31
	v_exp_f32_e32 v30, v30
	v_exp_f32_e32 v31, v31
	v_add_u32_e32 v32, v146, v108
	v_pk_mul_f32 v[24:25], v[28:29], v[24:25]
	ds_write_b64 v32, v[178:179] offset:32768
	v_cndmask_b32_e64 v32, v24, 0, s[6:7]
	v_cndmask_b32_e64 v33, v25, 0, s[70:71]
	v_pk_mul_f32 v[24:25], v[104:105], v[26:27] op_sel_hi:[0,1]
	v_pk_mul_f32 v[24:25], v[30:31], v[24:25]
	v_cndmask_b32_e64 v24, v24, 0, s[74:75]
	v_cndmask_b32_e64 v25, v25, 0, s[72:73]
	v_pk_mul_f32 v[20:21], v[102:103], v[20:21] op_sel_hi:[0,1]
	v_cvt_pk_bf16_f32 v25, v24, v25
	v_cvt_pk_bf16_f32 v24, v32, v33
	v_add_u32_e32 v26, v146, v123
	v_pk_mul_f32 v[20:21], v[28:29], v[20:21]
	ds_write_b64 v26, v[24:25] offset:32768
	v_cndmask_b32_e64 v24, v20, 0, s[78:79]
	v_cndmask_b32_e64 v25, v21, 0, s[76:77]
	v_pk_mul_f32 v[20:21], v[102:103], v[22:23] op_sel_hi:[0,1]
	v_pk_mul_f32 v[20:21], v[30:31], v[20:21]
	v_cndmask_b32_e64 v20, v20, 0, s[82:83]
	v_cndmask_b32_e64 v21, v21, 0, s[80:81]
	v_pk_mul_f32 v[16:17], v[100:101], v[16:17] op_sel_hi:[0,1]
	v_cvt_pk_bf16_f32 v21, v20, v21
	v_cvt_pk_bf16_f32 v20, v24, v25
	v_add_u32_e32 v22, v146, v124
	v_pk_mul_f32 v[16:17], v[28:29], v[16:17]
	ds_write_b64 v22, v[20:21] offset:32768
	v_cndmask_b32_e64 v20, v16, 0, s[86:87]
	v_cndmask_b32_e64 v21, v17, 0, s[84:85]
	v_pk_mul_f32 v[16:17], v[100:101], v[18:19] op_sel_hi:[0,1]
	v_pk_mul_f32 v[16:17], v[30:31], v[16:17]
	v_cndmask_b32_e64 v16, v16, 0, s[90:91]
	v_cndmask_b32_e64 v17, v17, 0, s[88:89]
	v_pk_mul_f32 v[12:13], v[98:99], v[12:13] op_sel_hi:[0,1]
	v_cvt_pk_bf16_f32 v17, v16, v17
	v_cvt_pk_bf16_f32 v16, v20, v21
	v_add_u32_e32 v18, v146, v125
	v_pk_mul_f32 v[12:13], v[28:29], v[12:13]
	ds_write_b64 v18, v[16:17] offset:32768
	v_cndmask_b32_e64 v16, v12, 0, s[94:95]
	v_cndmask_b32_e64 v17, v13, 0, s[92:93]
	v_pk_mul_f32 v[12:13], v[98:99], v[14:15] op_sel_hi:[0,1]
	v_pk_mul_f32 v[12:13], v[30:31], v[12:13]
	v_cndmask_b32_e64 v12, v12, 0, s[0:1]
	v_cndmask_b32_e64 v13, v13, 0, s[96:97]
	v_pk_mul_f32 v[8:9], v[96:97], v[8:9] op_sel_hi:[0,1]
	v_cvt_pk_bf16_f32 v13, v12, v13
	v_cvt_pk_bf16_f32 v12, v16, v17
	v_add_u32_e32 v14, v146, v126
	v_pk_mul_f32 v[8:9], v[28:29], v[8:9]
	ds_write_b64 v14, v[12:13] offset:32768
	v_cndmask_b32_e64 v12, v8, 0, s[4:5]
	v_cndmask_b32_e64 v13, v9, 0, s[28:29]
	v_pk_mul_f32 v[8:9], v[96:97], v[10:11] op_sel_hi:[0,1]
	v_pk_mul_f32 v[8:9], v[30:31], v[8:9]
	v_cndmask_b32_e64 v8, v8, 0, s[10:11]
	v_cndmask_b32_e64 v9, v9, 0, s[8:9]
	v_pk_mul_f32 v[4:5], v[62:63], v[4:5] op_sel_hi:[0,1]
	v_cvt_pk_bf16_f32 v9, v8, v9
	v_cvt_pk_bf16_f32 v8, v12, v13
	v_add_u32_e32 v10, v146, v127
	v_pk_mul_f32 v[4:5], v[28:29], v[4:5]
	ds_write_b64 v10, v[8:9] offset:32768
	v_cndmask_b32_e64 v8, v4, 0, s[14:15]
	v_cndmask_b32_e64 v9, v5, 0, s[12:13]
	v_pk_mul_f32 v[4:5], v[62:63], v[6:7] op_sel_hi:[0,1]
	v_pk_mul_f32 v[4:5], v[30:31], v[4:5]
	v_cndmask_b32_e64 v4, v4, 0, s[18:19]
	v_cndmask_b32_e64 v5, v5, 0, s[16:17]
	v_pk_mul_f32 v[0:1], v[60:61], v[0:1] op_sel_hi:[0,1]
	v_cvt_pk_bf16_f32 v5, v4, v5
	v_cvt_pk_bf16_f32 v4, v8, v9
	v_add_u32_e32 v6, v146, v140
	v_pk_mul_f32 v[0:1], v[28:29], v[0:1]
	ds_write_b64 v6, v[4:5] offset:32768
	v_cndmask_b32_e64 v4, v0, 0, s[22:23]
	v_cndmask_b32_e64 v5, v1, 0, s[20:21]
	v_pk_mul_f32 v[0:1], v[60:61], v[2:3] op_sel_hi:[0,1]
	v_pk_mul_f32 v[0:1], v[30:31], v[0:1]
	v_cndmask_b32_e64 v0, v0, 0, s[26:27]
	v_cndmask_b32_e64 v1, v1, 0, s[24:25]
	v_cvt_pk_bf16_f32 v1, v0, v1
	v_cvt_pk_bf16_f32 v0, v4, v5
	v_add_u32_e32 v2, v146, v141
	v_mov_b32_e32 v32, 0
	ds_write_b64 v2, v[0:1] offset:32768
	v_mov_b32_e32 v33, v32
	v_mov_b32_e32 v34, v32
	v_mov_b32_e32 v35, v32
	v_mov_b32_e32 v36, v32
	v_mov_b32_e32 v37, v32
	v_mov_b32_e32 v38, v32
	v_mov_b32_e32 v39, v32
	v_mov_b32_e32 v40, v32
	v_mov_b32_e32 v41, v32
	v_mov_b32_e32 v42, v32
	v_mov_b32_e32 v43, v32
	v_mov_b32_e32 v44, v32
	v_mov_b32_e32 v45, v32
	v_mov_b32_e32 v46, v32
	v_mov_b32_e32 v47, v32
	v_mov_b32_e32 v48, v32
	v_mov_b32_e32 v49, v32
	v_mov_b32_e32 v50, v32
	v_mov_b32_e32 v51, v32
	v_mov_b32_e32 v52, v32
	v_mov_b32_e32 v53, v32
	v_mov_b32_e32 v54, v32
	v_mov_b32_e32 v55, v32
	v_mov_b32_e32 v56, v32
	v_mov_b32_e32 v57, v32
	v_mov_b32_e32 v58, v32
	v_mov_b32_e32 v59, v32
	v_mov_b32_e32 v60, v32
	v_mov_b32_e32 v61, v32
	v_mov_b32_e32 v62, v32
	v_mov_b32_e32 v63, v32
	v_mov_b32_e32 v0, v32
	v_mov_b32_e32 v1, v32
	v_mov_b32_e32 v2, v32
	v_mov_b32_e32 v3, v32
	v_mov_b32_e32 v8, v32
	v_mov_b32_e32 v9, v32
	v_mov_b32_e32 v10, v32
	v_mov_b32_e32 v11, v32
	v_mov_b32_e32 v12, v32
	v_mov_b32_e32 v13, v32
	v_mov_b32_e32 v14, v32
	v_mov_b32_e32 v15, v32
	v_mov_b32_e32 v16, v32
	v_mov_b32_e32 v17, v32
	v_mov_b32_e32 v18, v32
	v_mov_b32_e32 v19, v32
	v_mov_b32_e32 v20, v32
	v_mov_b32_e32 v21, v32
	v_mov_b32_e32 v22, v32
	v_mov_b32_e32 v23, v32
	v_mov_b32_e32 v24, v32
	v_mov_b32_e32 v25, v32
	v_mov_b32_e32 v26, v32
	v_mov_b32_e32 v27, v32
	v_mov_b32_e32 v28, v32
	v_mov_b32_e32 v29, v32
	v_mov_b32_e32 v30, v32
	v_mov_b32_e32 v31, v32
	v_mov_b32_e32 v4, v32
	v_mov_b32_e32 v5, v32
	v_mov_b32_e32 v6, v32
	v_mov_b32_e32 v7, v32
	s_mov_b64 s[54:55], -1

.LBB0_629:
	s_lshl_b32 s38, s31, 7
	v_lshl_add_u64 v[94:95], v[92:93], 0, s[38:39]
	v_readfirstlane_b32 s38, v165
	s_mov_b32 m0, s38
	s_mov_b64 s[54:55], 0x40000
	v_readfirstlane_b32 s38, v166
	global_load_lds_dwordx4 v[94:95], off
	v_lshl_add_u64 v[96:97], v[94:95], 0, s[54:55]
	s_mov_b32 m0, s38
	s_mov_b64 s[54:55], 0x80000
	v_readfirstlane_b32 s38, v167
	global_load_lds_dwordx4 v[96:97], off
	v_lshl_add_u64 v[96:97], v[94:95], 0, s[54:55]
	s_mov_b32 m0, s38
	s_mov_b64 s[54:55], 0xc0000
	v_readfirstlane_b32 s38, v168
	global_load_lds_dwordx4 v[96:97], off
	v_lshl_add_u64 v[94:95], v[94:95], 0, s[54:55]
	s_mov_b32 m0, s38
	s_lshl_b32 s31, s31, 14
	global_load_lds_dwordx4 v[94:95], off
	v_or_b32_e32 v87, s31, v106
	v_add_u32_e32 v87, v87, v109
	s_waitcnt vmcnt(0)
	s_waitcnt vmcnt(0) lgkmcnt(0)
	s_barrier
	ds_read_b128 v[94:97], v87 offset:32768
	ds_read_b128 v[102:105], v170 offset:16384
	ds_read_b128 v[180:183], v170 offset:18432
	ds_read_b128 v[184:187], v170 offset:20480
	ds_read_b128 v[98:101], v87 offset:34816
	ds_read_b128 v[188:191], v170 offset:22528
	ds_read_b128 v[192:195], v170 offset:24576
	ds_read_b128 v[196:199], v170 offset:26624
	ds_read_b128 v[200:203], v170 offset:28672
	ds_read_b128 v[204:207], v170 offset:30720
	v_or_b32_e32 v87, s31, v107
	v_add_u32_e32 v87, v87, v109
	s_waitcnt lgkmcnt(8)
	v_mfma_f32_16x16x32_bf16 v[32:35], v[94:97], v[102:105], v[32:35]
	s_mov_b32 s31, 1
	s_and_b64 vcc, exec, s[52:53]
	s_mov_b64 s[52:53], 0
	s_waitcnt lgkmcnt(7)
	v_mfma_f32_16x16x32_bf16 v[36:39], v[94:97], v[180:183], v[36:39]
	s_waitcnt lgkmcnt(6)
	v_mfma_f32_16x16x32_bf16 v[40:43], v[94:97], v[184:187], v[40:43]
	s_waitcnt lgkmcnt(4)
	v_mfma_f32_16x16x32_bf16 v[44:47], v[94:97], v[188:191], v[44:47]
	s_waitcnt lgkmcnt(3)
	v_mfma_f32_16x16x32_bf16 v[48:51], v[94:97], v[192:195], v[48:51]
	s_waitcnt lgkmcnt(2)
	v_mfma_f32_16x16x32_bf16 v[52:55], v[94:97], v[196:199], v[52:55]
	s_waitcnt lgkmcnt(1)
	v_mfma_f32_16x16x32_bf16 v[56:59], v[94:97], v[200:203], v[56:59]
	s_waitcnt lgkmcnt(0)
	v_mfma_f32_16x16x32_bf16 v[60:63], v[94:97], v[204:207], v[60:63]
	ds_read_b128 v[94:97], v87 offset:32768
	v_mfma_f32_16x16x32_bf16 v[0:3], v[98:101], v[102:105], v[0:3]
	v_mfma_f32_16x16x32_bf16 v[8:11], v[98:101], v[180:183], v[8:11]
	v_mfma_f32_16x16x32_bf16 v[12:15], v[98:101], v[184:187], v[12:15]
	v_mfma_f32_16x16x32_bf16 v[16:19], v[98:101], v[188:191], v[16:19]
	v_mfma_f32_16x16x32_bf16 v[20:23], v[98:101], v[192:195], v[20:23]
	v_mfma_f32_16x16x32_bf16 v[24:27], v[98:101], v[196:199], v[24:27]
	v_mfma_f32_16x16x32_bf16 v[28:31], v[98:101], v[200:203], v[28:31]
	v_mfma_f32_16x16x32_bf16 v[4:7], v[98:101], v[204:207], v[4:7]
	ds_read_b128 v[98:101], v87 offset:34816
	ds_read_b128 v[102:105], v172 offset:16384
	ds_read_b128 v[180:183], v172 offset:18432
	ds_read_b128 v[184:187], v172 offset:20480
	ds_read_b128 v[188:191], v172 offset:22528
	ds_read_b128 v[192:195], v172 offset:24576
	ds_read_b128 v[196:199], v172 offset:26624
	ds_read_b128 v[200:203], v172 offset:28672
	ds_read_b128 v[204:207], v172 offset:30720
	s_waitcnt lgkmcnt(7)
	v_mfma_f32_16x16x32_bf16 v[32:35], v[94:97], v[102:105], v[32:35]
	s_waitcnt lgkmcnt(0)
	s_barrier
	v_mfma_f32_16x16x32_bf16 v[36:39], v[94:97], v[180:183], v[36:39]
	v_mfma_f32_16x16x32_bf16 v[40:43], v[94:97], v[184:187], v[40:43]
	v_mfma_f32_16x16x32_bf16 v[44:47], v[94:97], v[188:191], v[44:47]
	v_mfma_f32_16x16x32_bf16 v[48:51], v[94:97], v[192:195], v[48:51]
	v_mfma_f32_16x16x32_bf16 v[52:55], v[94:97], v[196:199], v[52:55]
	v_mfma_f32_16x16x32_bf16 v[56:59], v[94:97], v[200:203], v[56:59]
	v_mfma_f32_16x16x32_bf16 v[60:63], v[94:97], v[204:207], v[60:63]
	v_mfma_f32_16x16x32_bf16 v[0:3], v[98:101], v[102:105], v[0:3]
	v_mfma_f32_16x16x32_bf16 v[8:11], v[98:101], v[180:183], v[8:11]
	v_mfma_f32_16x16x32_bf16 v[12:15], v[98:101], v[184:187], v[12:15]
	v_mfma_f32_16x16x32_bf16 v[16:19], v[98:101], v[188:191], v[16:19]
	v_mfma_f32_16x16x32_bf16 v[20:23], v[98:101], v[192:195], v[20:23]
	v_mfma_f32_16x16x32_bf16 v[24:27], v[98:101], v[196:199], v[24:27]
	v_mfma_f32_16x16x32_bf16 v[28:31], v[98:101], v[200:203], v[28:31]
	v_mfma_f32_16x16x32_bf16 v[4:7], v[98:101], v[204:207], v[4:7]
	s_cbranch_vccnz .LBB0_629
	v_and_b32_e32 v91, 64, v155
	v_xor_b32_e32 v87, 1, v155
	v_add_u32_e32 v92, 64, v91
	v_cmp_lt_i32_e32 vcc, v87, v92
	v_mov_b32_e32 v96, v56
	v_mov_b32_e32 v97, v60
	v_cndmask_b32_e32 v87, v155, v87, vcc
	v_lshlrev_b32_e32 v176, 2, v87
	v_xor_b32_e32 v87, 2, v155
	v_cmp_lt_i32_e32 vcc, v87, v92
	v_mov_b32_e32 v93, v44
	v_pk_mul_f32 v[98:99], v[96:97], v[96:97]
	v_cndmask_b32_e32 v87, v155, v87, vcc
	v_lshlrev_b32_e32 v175, 2, v87
	v_xor_b32_e32 v87, 4, v155
	v_cmp_lt_i32_e32 vcc, v87, v92
	v_mov_b32_e32 v96, v41
	v_mov_b32_e32 v97, v45
	v_cndmask_b32_e32 v87, v155, v87, vcc
	v_lshlrev_b32_e32 v91, 2, v87
	v_xor_b32_e32 v87, 8, v155
	v_cmp_lt_i32_e32 vcc, v87, v92
	v_mov_b32_e32 v92, v40
	v_pk_mul_f32 v[92:93], v[92:93], v[92:93]
	v_pk_mul_f32 v[100:101], v[96:97], v[96:97]
	v_pk_mul_f32 v[96:97], v[38:39], v[38:39]
	v_pk_mul_f32 v[102:103], v[36:37], v[36:37]
	v_mov_b32_e32 v94, v48
	v_mov_b32_e32 v95, v52
	v_pk_fma_f32 v[180:181], v[34:35], v[34:35], v[96:97]
	v_pk_fma_f32 v[102:103], v[32:33], v[32:33], v[102:103]
	v_mov_b32_e32 v96, v49
	v_mov_b32_e32 v97, v53
	v_mov_b32_e32 v210, v100
	v_mov_b32_e32 v211, v92
	v_pk_mul_f32 v[94:95], v[94:95], v[94:95]
	v_pk_mul_f32 v[182:183], v[96:97], v[96:97]
	v_pk_add_f32 v[102:103], v[102:103], v[210:211] op_sel:[1,0] op_sel_hi:[0,1]
	v_mov_b32_e32 v92, v101
	v_mov_b32_e32 v96, v57
	v_mov_b32_e32 v97, v61
	v_pk_add_f32 v[92:93], v[102:103], v[92:93]
	v_mov_b32_e32 v100, v182
	v_mov_b32_e32 v101, v94
	v_pk_mul_f32 v[184:185], v[96:97], v[96:97]
	v_pk_add_f32 v[92:93], v[92:93], v[100:101]
	v_mov_b32_e32 v94, v183
	v_pk_add_f32 v[92:93], v[92:93], v[94:95]
	v_mov_b32_e32 v94, v184
	v_mov_b32_e32 v95, v98
	v_pk_add_f32 v[92:93], v[92:93], v[94:95]
	v_mov_b32_e32 v98, v185
	v_pk_add_f32 v[92:93], v[92:93], v[98:99]
	ds_bpermute_b32 v95, v176, v93
	ds_bpermute_b32 v94, v176, v92
	v_mov_b32_e32 v96, v42
	v_mov_b32_e32 v97, v46
	v_pk_mul_f32 v[186:187], v[96:97], v[96:97]
	v_mov_b32_e32 v96, v50
	s_waitcnt lgkmcnt(0)
	v_pk_add_f32 v[92:93], v[92:93], v[94:95]
	ds_bpermute_b32 v95, v175, v93
	ds_bpermute_b32 v94, v175, v92
	v_mov_b32_e32 v97, v54
	v_pk_mul_f32 v[188:189], v[96:97], v[96:97]
	v_mov_b32_e32 v96, v58
	v_mov_b32_e32 v97, v62
	s_waitcnt lgkmcnt(0)
	v_pk_add_f32 v[92:93], v[92:93], v[94:95]
	ds_bpermute_b32 v185, v91, v93
	ds_bpermute_b32 v184, v91, v92
	v_pk_mul_f32 v[190:191], v[96:97], v[96:97]
	v_mov_b32_e32 v96, v43
	v_mov_b32_e32 v97, v47
	v_cndmask_b32_e32 v87, v155, v87, vcc
	v_pk_mul_f32 v[192:193], v[96:97], v[96:97]
	v_lshlrev_b32_e32 v87, 2, v87
	v_mov_b32_e32 v96, v51
	v_mov_b32_e32 v97, v55
	s_waitcnt lgkmcnt(0)
	v_pk_add_f32 v[92:93], v[92:93], v[184:185]
	v_mov_b32_e32 v212, v192
	v_mov_b32_e32 v213, v186
	v_pk_mul_f32 v[194:195], v[96:97], v[96:97]
	v_mov_b32_e32 v98, v14
	v_mov_b32_e32 v99, v18
	ds_bpermute_b32 v185, v87, v93
	ds_bpermute_b32 v184, v87, v92
	v_pk_add_f32 v[180:181], v[180:181], v[212:213] op_sel:[1,0] op_sel_hi:[0,1]
	v_mov_b32_e32 v186, v193
	v_mov_b32_e32 v96, v59
	v_mov_b32_e32 v97, v63
	v_pk_mul_f32 v[102:103], v[98:99], v[98:99]
	v_mov_b32_e32 v98, v22
	v_mov_b32_e32 v99, v26
	v_pk_add_f32 v[180:181], v[180:181], v[186:187]
	v_mov_b32_e32 v186, v194
	v_mov_b32_e32 v187, v188
	v_pk_mul_f32 v[196:197], v[96:97], v[96:97]
	v_pk_mul_f32 v[100:101], v[98:99], v[98:99]
	v_mov_b32_e32 v98, v30
	v_mov_b32_e32 v99, v6
	v_pk_add_f32 v[180:181], v[180:181], v[186:187]
	v_mov_b32_e32 v188, v195
	v_mov_b32_e32 v208, v29
	v_mov_b32_e32 v209, v5
	v_pk_mul_f32 v[94:95], v[98:99], v[98:99]
	v_mov_b32_e32 v98, v15
	v_mov_b32_e32 v99, v19
	v_pk_add_f32 v[180:181], v[180:181], v[188:189]
	v_mov_b32_e32 v186, v196
	v_mov_b32_e32 v187, v190
	v_pk_mul_f32 v[182:183], v[208:209], v[208:209]
	v_pk_mul_f32 v[208:209], v[98:99], v[98:99]
	v_mov_b32_e32 v98, v23
	v_mov_b32_e32 v99, v27
	s_mov_b32 s38, 0x358637bd
	v_pk_add_f32 v[180:181], v[180:181], v[186:187]
	v_mov_b32_e32 v190, v197
	v_pk_mul_f32 v[210:211], v[98:99], v[98:99]
	s_waitcnt lgkmcnt(0)
	v_pk_add_f32 v[98:99], v[92:93], v[184:185]
	v_mov_b64_e32 v[92:93], s[38:39]
	v_pk_add_f32 v[180:181], v[180:181], v[190:191]
	v_pk_fma_f32 v[184:185], v[98:99], s[46:47], v[92:93] op_sel_hi:[1,0,0]
	ds_bpermute_b32 v187, v176, v181
	ds_bpermute_b32 v186, v176, v180
	v_mul_f32_e32 v98, 0x4b800000, v185
	v_cmp_gt_f32_e32 vcc, s58, v185
	v_mov_b32_e32 v96, v12
	v_mov_b32_e32 v97, v16
	v_cndmask_b32_e32 v98, v185, v98, vcc
	v_rsq_f32_e32 v177, v98
	s_waitcnt lgkmcnt(0)
	v_pk_add_f32 v[180:181], v[180:181], v[186:187]
	ds_bpermute_b32 v187, v175, v181
	ds_bpermute_b32 v186, v175, v180
	v_mul_f32_e32 v185, 0x45800000, v177
	v_cndmask_b32_e32 v177, v177, v185, vcc
	v_mul_f32_e32 v214, v32, v177
	v_mul_f32_e32 v32, 0x4b800000, v184
	v_cmp_gt_f32_e32 vcc, s58, v184
	s_waitcnt lgkmcnt(0)
	v_pk_add_f32 v[180:181], v[180:181], v[186:187]
	ds_bpermute_b32 v185, v91, v181
	v_cndmask_b32_e32 v32, v184, v32, vcc
	v_rsq_f32_e32 v32, v32
	ds_bpermute_b32 v184, v91, v180
	v_mul_f32_e32 v215, v36, v177
	v_mul_f32_e32 v216, v40, v177
	v_mul_f32_e32 v36, 0x45800000, v32
	v_cndmask_b32_e32 v36, v32, v36, vcc
	v_mul_f32_e32 v44, v44, v177
	v_mul_f32_e32 v48, v48, v177
	v_mul_f32_e32 v52, v52, v177
	v_mul_f32_e32 v56, v56, v177
	v_mul_f32_e32 v60, v60, v177
	v_mul_f32_e32 v177, v33, v36
	s_waitcnt lgkmcnt(0)
	v_pk_add_f32 v[32:33], v[180:181], v[184:185]
	ds_bpermute_b32 v181, v87, v33
	ds_bpermute_b32 v180, v87, v32
	v_mul_f32_e32 v184, v37, v36
	v_pk_mul_f32 v[198:199], v[96:97], v[96:97]
	v_mov_b32_e32 v96, v20
	v_mov_b32_e32 v97, v24
	s_waitcnt lgkmcnt(0)
	v_pk_add_f32 v[32:33], v[32:33], v[180:181]
	v_pk_mul_f32 v[200:201], v[96:97], v[96:97]
	v_pk_fma_f32 v[32:33], v[32:33], s[46:47], v[92:93] op_sel_hi:[1,0,0]
	v_mov_b32_e32 v96, v28
	v_mul_f32_e32 v37, 0x4b800000, v33
	v_cmp_gt_f32_e32 vcc, s58, v33
	v_mov_b32_e32 v97, v4
	v_pk_mul_f32 v[104:105], v[96:97], v[96:97]
	v_cndmask_b32_e32 v33, v33, v37, vcc
	v_rsq_f32_e32 v33, v33
	v_mov_b32_e32 v96, v13
	v_mov_b32_e32 v97, v17
	v_pk_mul_f32 v[202:203], v[96:97], v[96:97]
	v_pk_mul_f32 v[204:205], v[8:9], v[8:9]
	v_mul_f32_e32 v185, v41, v36
	v_mul_f32_e32 v45, v45, v36
	v_mul_f32_e32 v49, v49, v36
	v_mul_f32_e32 v53, v53, v36
	v_mul_f32_e32 v57, v57, v36
	v_mul_f32_e32 v61, v61, v36
	v_mul_f32_e32 v36, 0x45800000, v33
	v_pk_fma_f32 v[204:205], v[0:1], v[0:1], v[204:205]
	v_mov_b32_e32 v206, v21
	v_mov_b32_e32 v207, v25
	v_cndmask_b32_e32 v180, v33, v36, vcc
	v_mov_b32_e32 v36, v202
	v_mov_b32_e32 v37, v198
	v_pk_mul_f32 v[206:207], v[206:207], v[206:207]
	v_pk_add_f32 v[36:37], v[204:205], v[36:37] op_sel:[1,0] op_sel_hi:[0,1]
	v_mov_b32_e32 v198, v203
	v_pk_add_f32 v[36:37], v[36:37], v[198:199]
	v_mov_b32_e32 v40, v206
	v_mov_b32_e32 v41, v200
	v_pk_add_f32 v[36:37], v[36:37], v[40:41]
	v_mov_b32_e32 v200, v207
	v_pk_add_f32 v[36:37], v[36:37], v[200:201]
	v_mov_b32_e32 v40, v182
	v_mov_b32_e32 v41, v104
	v_pk_add_f32 v[36:37], v[36:37], v[40:41]
	v_mov_b32_e32 v104, v183
	v_pk_add_f32 v[36:37], v[36:37], v[104:105]
	ds_bpermute_b32 v41, v176, v37
	ds_bpermute_b32 v40, v176, v36
	v_mul_f32_e32 v33, 0x4b800000, v32
	v_cmp_gt_f32_e32 vcc, s58, v32
	v_mul_f32_e32 v181, v34, v180
	v_mul_f32_e32 v186, v42, v180
	s_waitcnt lgkmcnt(0)
	v_pk_add_f32 v[36:37], v[36:37], v[40:41]
	ds_bpermute_b32 v41, v175, v37
	ds_bpermute_b32 v40, v175, v36
	v_cndmask_b32_e32 v32, v32, v33, vcc
	v_rsq_f32_e32 v34, v32
	v_pk_mul_f32 v[96:97], v[10:11], v[10:11]
	v_mul_f32_e32 v38, v38, v180
	s_waitcnt lgkmcnt(0)
	v_pk_add_f32 v[32:33], v[36:37], v[40:41]
	ds_bpermute_b32 v37, v91, v33
	ds_bpermute_b32 v36, v91, v32
	v_mul_f32_e32 v40, 0x45800000, v34
	v_cndmask_b32_e32 v42, v34, v40, vcc
	v_mul_f32_e32 v104, v35, v42
	v_pk_fma_f32 v[96:97], v[2:3], v[2:3], v[96:97]
	s_waitcnt lgkmcnt(0)
	v_pk_add_f32 v[32:33], v[32:33], v[36:37]
	ds_bpermute_b32 v35, v87, v33
	ds_bpermute_b32 v34, v87, v32
	v_mov_b32_e32 v36, v210
	v_mov_b32_e32 v37, v100
	v_mov_b32_e32 v100, v211
	v_mul_f32_e32 v39, v39, v42
	s_waitcnt lgkmcnt(0)
	v_pk_add_f32 v[32:33], v[32:33], v[34:35]
	v_mul_f32_e32 v105, v43, v42
	v_pk_fma_f32 v[40:41], v[32:33], s[46:47], v[92:93] op_sel_hi:[1,0,0]
	v_mul_f32_e32 v47, v47, v42
	v_mul_f32_e32 v32, 0x4b800000, v41
	v_cmp_gt_f32_e32 vcc, s58, v41
	v_mul_f32_e32 v51, v51, v42
	v_mul_f32_e32 v35, v55, v42
	v_cndmask_b32_e32 v32, v41, v32, vcc
	v_rsq_f32_e32 v32, v32
	v_mul_f32_e32 v41, v59, v42
	v_mul_f32_e32 v55, v63, v42
	v_add_u32_e32 v63, 0x400, v150
	v_mul_f32_e32 v33, 0x45800000, v32
	v_cndmask_b32_e32 v59, v32, v33, vcc
	v_mov_b32_e32 v32, v208
	v_mov_b32_e32 v33, v102
	v_pk_add_f32 v[32:33], v[96:97], v[32:33] op_sel:[1,0] op_sel_hi:[0,1]
	v_mov_b32_e32 v102, v209
	v_pk_add_f32 v[32:33], v[32:33], v[102:103]
	s_lshl_b32 s38, s59, 1
	v_pk_add_f32 v[32:33], v[32:33], v[36:37]
	v_mul_f32_e32 v46, v46, v180
	v_pk_add_f32 v[42:43], v[32:33], v[100:101]
	v_lshl_add_u64 v[32:33], s[34:35], 0, v[68:69]
	v_lshlrev_b64 v[32:33], 12, v[32:33]
	v_lshl_add_u64 v[32:33], s[36:37], 0, v[32:33]
	v_mul_f32_e32 v50, v50, v180
	v_mul_f32_e32 v54, v54, v180
	v_mul_f32_e32 v58, v58, v180
	v_mul_f32_e32 v62, v62, v180
	ds_write2_b32 v150, v214, v215 offset1:16
	ds_write2_b32 v150, v177, v184 offset0:128 offset1:144
	ds_write2_b32 v63, v181, v38 offset1:16
	ds_write2_b32 v63, v104, v39 offset0:128 offset1:144
	ds_write2_b32 v150, v216, v44 offset0:32 offset1:48
	ds_write2_b32 v150, v185, v45 offset0:160 offset1:176
	ds_write2_b32 v63, v186, v46 offset0:32 offset1:48
	ds_write2_b32 v63, v105, v47 offset0:160 offset1:176
	ds_write2_b32 v150, v48, v52 offset0:64 offset1:80
	ds_write2_b32 v150, v49, v53 offset0:192 offset1:208
	ds_write2_b32 v63, v50, v54 offset0:64 offset1:80
	ds_write2_b32 v63, v51, v35 offset0:192 offset1:208
	ds_write2st64_b32 v151, v56, v57 offset1:2
	ds_write2st64_b32 v151, v58, v41 offset0:4 offset1:6
	ds_write2st64_b32 v154, v60, v61 offset1:2
	ds_write2st64_b32 v154, v62, v55 offset0:4 offset1:6
	v_lshl_add_u64 v[32:33], v[32:33], 0, s[38:39]
	v_lshl_add_u64 v[32:33], v[32:33], 0, v[64:65]
	global_load_dwordx4 v[36:39], v[32:33], off offset:2048
	v_mov_b32_e32 v98, v31
	v_mov_b32_e32 v99, v7
	v_pk_mul_f32 v[98:99], v[98:99], v[98:99]
	v_mov_b32_e32 v45, v94
	v_mov_b32_e32 v44, v98
	v_pk_add_f32 v[42:43], v[42:43], v[44:45]
	v_mov_b32_e32 v94, v99
	v_pk_add_f32 v[42:43], v[42:43], v[94:95]
	ds_bpermute_b32 v45, v176, v43
	ds_bpermute_b32 v44, v176, v42
	v_mul_f32_e32 v34, v0, v59
	v_mul_f32_e32 v0, v12, v59
	v_mul_f32_e32 v12, 0x4b800000, v40
	v_cmp_gt_f32_e32 vcc, s58, v40
	s_waitcnt lgkmcnt(0)
	v_pk_add_f32 v[42:43], v[42:43], v[44:45]
	ds_bpermute_b32 v45, v175, v43
	ds_bpermute_b32 v44, v175, v42
	v_cndmask_b32_e32 v12, v40, v12, vcc
	v_rsq_f32_e32 v12, v12
	v_mul_f32_e32 v48, v4, v59
	v_mul_f32_e32 v46, v20, v59
	s_waitcnt lgkmcnt(0)
	v_pk_add_f32 v[40:41], v[42:43], v[44:45]
	ds_bpermute_b32 v43, v91, v41
	ds_bpermute_b32 v42, v91, v40
	v_mul_f32_e32 v4, 0x45800000, v12
	v_cndmask_b32_e32 v4, v12, v4, vcc
	v_mul_f32_e32 v49, v13, v4
	v_mul_f32_e32 v35, v16, v59
	s_waitcnt lgkmcnt(0)
	v_pk_add_f32 v[40:41], v[40:41], v[42:43]
	ds_bpermute_b32 v43, v87, v41
	ds_bpermute_b32 v42, v87, v40
	v_mul_f32_e32 v50, v17, v4
	v_lshl_add_u64 v[16:17], s[34:35], 0, v[70:71]
	v_mul_f32_e32 v1, v1, v4
	v_mul_f32_e32 v9, v9, v4
	s_waitcnt lgkmcnt(0)
	v_pk_add_f32 v[12:13], v[40:41], v[42:43]
	v_mul_f32_e32 v51, v21, v4
	v_pk_fma_f32 v[12:13], v[12:13], s[46:47], v[92:93] op_sel_hi:[1,0,0]
	v_lshlrev_b64 v[16:17], 12, v[16:17]
	v_mul_f32_e32 v20, 0x4b800000, v13
	v_cmp_gt_f32_e32 vcc, s58, v13
	v_mul_f32_e32 v52, v25, v4
	v_mul_f32_e32 v29, v29, v4
	v_cndmask_b32_e32 v13, v13, v20, vcc
	v_rsq_f32_e32 v13, v13
	v_mul_f32_e32 v53, v5, v4
	v_lshl_add_u64 v[16:17], s[36:37], 0, v[16:17]
	v_lshl_add_u64 v[16:17], v[16:17], 0, s[38:39]
	v_mul_f32_e32 v4, 0x45800000, v13
	v_cndmask_b32_e32 v4, v13, v4, vcc
	v_mul_f32_e32 v54, v2, v4
	v_mul_f32_e32 v2, 0x4b800000, v12
	v_cmp_gt_f32_e32 vcc, s58, v12
	v_lshl_add_u64 v[44:45], v[16:17], 0, v[64:65]
	global_load_dwordx4 v[40:43], v[44:45], off offset:2048
	v_cndmask_b32_e32 v2, v12, v2, vcc
	v_rsq_f32_e32 v2, v2
	v_mul_f32_e32 v8, v8, v59
	v_mul_f32_e32 v47, v24, v59
	v_mul_f32_e32 v28, v28, v59
	v_mul_f32_e32 v55, v10, v4
	v_mul_f32_e32 v56, v14, v4
	v_mul_f32_e32 v57, v18, v4
	v_mul_f32_e32 v58, v22, v4
	v_mul_f32_e32 v26, v26, v4
	v_mul_f32_e32 v30, v30, v4
	v_mul_f32_e32 v59, v6, v4
	v_mul_f32_e32 v4, 0x45800000, v2
	v_cndmask_b32_e32 v6, v2, v4, vcc
	v_mul_f32_e32 v60, v3, v6
	v_lshl_add_u64 v[2:3], s[34:35], 0, v[72:73]
	v_lshlrev_b64 v[2:3], 12, v[2:3]
	v_lshl_add_u64 v[2:3], s[36:37], 0, v[2:3]
	v_lshl_add_u64 v[2:3], v[2:3], 0, s[38:39]
	v_mul_f32_e32 v61, v11, v6
	v_mul_f32_e32 v91, v23, v6
	v_lshl_add_u64 v[22:23], v[2:3], 0, v[64:65]
	ds_read_b128 v[10:13], v149
	global_load_dwordx4 v[2:5], v[22:23], off offset:2048
	v_mul_f32_e32 v62, v15, v6
	v_mul_f32_e32 v87, v19, v6
	v_mul_f32_e32 v27, v27, v6
	v_mul_f32_e32 v31, v31, v6
	v_mul_f32_e32 v92, v7, v6
	s_waitcnt vmcnt(2)
	v_and_b32_e32 v7, 0xffff0000, v36
	v_lshlrev_b32_e32 v6, 16, v36
	ds_read_b128 v[14:17], v149 offset:16
	s_waitcnt lgkmcnt(1)
	v_pk_mul_f32 v[6:7], v[10:11], v[6:7]
	v_and_b32_e32 v11, 0xffff0000, v37
	v_bfe_u32 v24, v7, 16, 1
	v_bfe_u32 v25, v6, 16, 1
	v_add3_u32 v25, v6, v25, s47
	v_add3_u32 v24, v7, v24, s47
	v_lshl_add_u64 v[6:7], s[34:35], 0, v[74:75]
	v_lshlrev_b32_e32 v10, 16, v37
	v_lshlrev_b64 v[6:7], 12, v[6:7]
	v_pk_mul_f32 v[10:11], v[12:13], v[10:11]
	v_and_b32_e32 v13, 0xffff0000, v38
	v_lshlrev_b32_e32 v12, 16, v38
	v_lshl_add_u64 v[6:7], s[36:37], 0, v[6:7]
	s_waitcnt lgkmcnt(0)
	v_pk_mul_f32 v[12:13], v[14:15], v[12:13]
	v_lshl_add_u64 v[6:7], v[6:7], 0, s[38:39]
	v_bfe_u32 v18, v13, 16, 1
	v_bfe_u32 v19, v12, 16, 1
	v_bfe_u32 v20, v11, 16, 1
	v_bfe_u32 v21, v10, 16, 1
	v_lshl_add_u64 v[6:7], v[6:7], 0, v[64:65]
	v_add3_u32 v21, v10, v21, s47
	v_add3_u32 v20, v11, v20, s47
	v_add3_u32 v19, v12, v19, s47
	v_add3_u32 v18, v13, v18, s47
	global_load_dwordx4 v[10:13], v[6:7], off offset:2048
	v_and_b32_e32 v15, 0xffff0000, v39
	v_lshlrev_b32_e32 v14, 16, v39
	v_pk_mul_f32 v[14:15], v[16:17], v[14:15]
	s_add_i32 s30, s30, s3
	v_cvt_pk_bf16_f32 v17, v14, v15
	v_perm_b32 v16, v18, v19, s33
	v_perm_b32 v15, v20, v21, s33
	ds_read_b128 v[18:21], v157
	v_perm_b32 v14, v24, v25, s33
	global_store_dwordx4 v[32:33], v[14:17], off offset:2048
	ds_read_b128 v[14:17], v157 offset:16
	s_cmpk_lt_i32 s30, 0x400
	s_waitcnt vmcnt(3)
	v_and_b32_e32 v25, 0xffff0000, v40
	v_lshlrev_b32_e32 v24, 16, v40
	s_waitcnt lgkmcnt(1)
	v_pk_mul_f32 v[18:19], v[18:19], v[24:25]
	v_and_b32_e32 v25, 0xffff0000, v41
	v_lshlrev_b32_e32 v24, 16, v41
	v_pk_mul_f32 v[20:21], v[20:21], v[24:25]
	v_and_b32_e32 v25, 0xffff0000, v42
	v_lshlrev_b32_e32 v24, 16, v42
	s_waitcnt lgkmcnt(0)
	v_pk_mul_f32 v[14:15], v[14:15], v[24:25]
	v_and_b32_e32 v25, 0xffff0000, v43
	v_lshlrev_b32_e32 v24, 16, v43
	v_pk_mul_f32 v[16:17], v[16:17], v[24:25]
	v_cvt_pk_bf16_f32 v17, v16, v17
	v_cvt_pk_bf16_f32 v16, v14, v15
	v_cvt_pk_bf16_f32 v15, v20, v21
	v_cvt_pk_bf16_f32 v14, v18, v19
	ds_read_b128 v[18:21], v158
	global_store_dwordx4 v[44:45], v[14:17], off offset:2048
	ds_read_b128 v[14:17], v158 offset:16
	s_waitcnt vmcnt(3)
	v_and_b32_e32 v25, 0xffff0000, v2
	v_lshlrev_b32_e32 v24, 16, v2
	s_waitcnt lgkmcnt(1)
	v_pk_mul_f32 v[18:19], v[18:19], v[24:25]
	v_and_b32_e32 v25, 0xffff0000, v3
	v_lshlrev_b32_e32 v24, 16, v3
	v_pk_mul_f32 v[2:3], v[20:21], v[24:25]
	v_and_b32_e32 v21, 0xffff0000, v4
	v_lshlrev_b32_e32 v20, 16, v4
	s_waitcnt lgkmcnt(0)
	v_pk_mul_f32 v[14:15], v[14:15], v[20:21]
	v_and_b32_e32 v21, 0xffff0000, v5
	v_lshlrev_b32_e32 v20, 16, v5
	v_pk_mul_f32 v[4:5], v[16:17], v[20:21]
	v_cvt_pk_bf16_f32 v5, v4, v5
	v_cvt_pk_bf16_f32 v4, v14, v15
	ds_read_b128 v[14:17], v159
	v_cvt_pk_bf16_f32 v3, v2, v3
	v_cvt_pk_bf16_f32 v2, v18, v19
	global_store_dwordx4 v[22:23], v[2:5], off offset:2048
	ds_read_b128 v[2:5], v159 offset:16
	s_waitcnt vmcnt(3)
	v_and_b32_e32 v19, 0xffff0000, v10
	v_lshlrev_b32_e32 v18, 16, v10
	s_waitcnt lgkmcnt(1)
	v_pk_mul_f32 v[14:15], v[14:15], v[18:19]
	v_and_b32_e32 v19, 0xffff0000, v11
	v_lshlrev_b32_e32 v18, 16, v11
	v_pk_mul_f32 v[10:11], v[16:17], v[18:19]
	v_and_b32_e32 v17, 0xffff0000, v12
	v_lshlrev_b32_e32 v16, 16, v12
	s_waitcnt lgkmcnt(0)
	v_pk_mul_f32 v[2:3], v[2:3], v[16:17]
	v_and_b32_e32 v17, 0xffff0000, v13
	v_lshlrev_b32_e32 v16, 16, v13
	v_pk_mul_f32 v[4:5], v[4:5], v[16:17]
	v_cvt_pk_bf16_f32 v5, v4, v5
	v_cvt_pk_bf16_f32 v4, v2, v3
	v_cvt_pk_bf16_f32 v3, v10, v11
	v_cvt_pk_bf16_f32 v2, v14, v15
	global_store_dwordx4 v[6:7], v[2:5], off offset:2048
	ds_write2_b32 v150, v34, v8 offset1:16
	ds_write2_b32 v150, v1, v9 offset0:128 offset1:144
	ds_write2_b32 v63, v54, v55 offset1:16
	ds_write2_b32 v63, v60, v61 offset0:128 offset1:144
	ds_write2_b32 v150, v0, v35 offset0:32 offset1:48
	ds_write2_b32 v150, v49, v50 offset0:160 offset1:176
	ds_write2_b32 v63, v56, v57 offset0:32 offset1:48
	ds_write2_b32 v63, v62, v87 offset0:160 offset1:176
	ds_write2_b32 v150, v46, v47 offset0:64 offset1:80
	ds_write2_b32 v150, v51, v52 offset0:192 offset1:208
	ds_write2_b32 v63, v58, v26 offset0:64 offset1:80
	ds_write2_b32 v63, v91, v27 offset0:192 offset1:208
	ds_write2st64_b32 v151, v28, v29 offset1:2
	ds_write2st64_b32 v151, v30, v31 offset0:4 offset1:6
	ds_write2st64_b32 v154, v48, v53 offset1:2
	ds_write2st64_b32 v154, v59, v92 offset0:4 offset1:6
	v_lshl_add_u64 v[0:1], s[34:35], 0, v[76:77]
	v_lshlrev_b64 v[0:1], 12, v[0:1]
	v_lshl_add_u64 v[0:1], s[36:37], 0, v[0:1]
	v_lshl_add_u64 v[0:1], v[0:1], 0, s[38:39]
	v_lshl_add_u64 v[20:21], v[0:1], 0, v[64:65]
	global_load_dwordx4 v[0:3], v[20:21], off offset:2048
	v_lshl_add_u64 v[4:5], s[34:35], 0, v[78:79]
	v_lshlrev_b64 v[4:5], 12, v[4:5]
	v_lshl_add_u64 v[4:5], s[36:37], 0, v[4:5]
	v_lshl_add_u64 v[4:5], v[4:5], 0, s[38:39]
	v_lshl_add_u64 v[22:23], v[4:5], 0, v[64:65]
	global_load_dwordx4 v[4:7], v[22:23], off offset:2048
	v_lshl_add_u64 v[8:9], s[34:35], 0, v[80:81]
	v_lshlrev_b64 v[8:9], 12, v[8:9]
	v_lshl_add_u64 v[8:9], s[36:37], 0, v[8:9]
	v_lshl_add_u64 v[8:9], v[8:9], 0, s[38:39]
	v_lshl_add_u64 v[24:25], v[8:9], 0, v[64:65]
	global_load_dwordx4 v[8:11], v[24:25], off offset:2048
	ds_read_b128 v[12:15], v149
	ds_read_b128 v[16:19], v149 offset:16
	s_waitcnt vmcnt(2)
	v_and_b32_e32 v27, 0xffff0000, v0
	v_lshlrev_b32_e32 v26, 16, v0
	s_waitcnt lgkmcnt(1)
	v_pk_mul_f32 v[12:13], v[12:13], v[26:27]
	v_and_b32_e32 v27, 0xffff0000, v1
	v_lshlrev_b32_e32 v26, 16, v1
	v_pk_mul_f32 v[0:1], v[14:15], v[26:27]
	v_bfe_u32 v28, v13, 16, 1
	v_bfe_u32 v26, v1, 16, 1
	v_bfe_u32 v27, v0, 16, 1
	v_bfe_u32 v29, v12, 16, 1
	v_add3_u32 v12, v12, v29, s47
	v_add3_u32 v28, v13, v28, s47
	v_add3_u32 v13, v0, v27, s47
	v_add3_u32 v29, v1, v26, s47
	v_lshl_add_u64 v[0:1], s[34:35], 0, v[82:83]
	v_lshlrev_b64 v[0:1], 12, v[0:1]
	v_and_b32_e32 v15, 0xffff0000, v2
	v_lshlrev_b32_e32 v14, 16, v2
	v_lshl_add_u64 v[0:1], s[36:37], 0, v[0:1]
	s_waitcnt lgkmcnt(0)
	v_pk_mul_f32 v[14:15], v[16:17], v[14:15]
	v_lshl_add_u64 v[0:1], v[0:1], 0, s[38:39]
	v_and_b32_e32 v17, 0xffff0000, v3
	v_lshlrev_b32_e32 v16, 16, v3
	v_lshl_add_u64 v[26:27], v[0:1], 0, v[64:65]
	global_load_dwordx4 v[0:3], v[26:27], off offset:2048
	v_pk_mul_f32 v[16:17], v[18:19], v[16:17]
	v_cvt_pk_bf16_f32 v14, v14, v15
	v_bfe_u32 v18, v17, 16, 1
	v_bfe_u32 v19, v16, 16, 1
	v_add3_u32 v15, v16, v19, s47
	v_add3_u32 v16, v17, v18, s47
	v_perm_b32 v15, v16, v15, s33
	ds_read_b128 v[16:19], v157
	v_perm_b32 v13, v29, v13, s33
	v_perm_b32 v12, v28, v12, s33
	global_store_dwordx4 v[20:21], v[12:15], off offset:2048
	ds_read_b128 v[12:15], v157 offset:16
	s_waitcnt vmcnt(3)
	v_and_b32_e32 v21, 0xffff0000, v4
	v_lshlrev_b32_e32 v20, 16, v4
	s_waitcnt lgkmcnt(1)
	v_pk_mul_f32 v[16:17], v[16:17], v[20:21]
	v_and_b32_e32 v21, 0xffff0000, v5
	v_lshlrev_b32_e32 v20, 16, v5
	v_pk_mul_f32 v[4:5], v[18:19], v[20:21]
	v_and_b32_e32 v19, 0xffff0000, v6
	v_lshlrev_b32_e32 v18, 16, v6
	s_waitcnt lgkmcnt(0)
	v_pk_mul_f32 v[12:13], v[12:13], v[18:19]
	v_and_b32_e32 v19, 0xffff0000, v7
	v_lshlrev_b32_e32 v18, 16, v7
	v_pk_mul_f32 v[6:7], v[14:15], v[18:19]
	v_cvt_pk_bf16_f32 v7, v6, v7
	v_cvt_pk_bf16_f32 v6, v12, v13
	ds_read_b128 v[12:15], v158
	v_cvt_pk_bf16_f32 v5, v4, v5
	v_cvt_pk_bf16_f32 v4, v16, v17
	global_store_dwordx4 v[22:23], v[4:7], off offset:2048
	ds_read_b128 v[4:7], v158 offset:16
	s_waitcnt vmcnt(3)
	v_and_b32_e32 v17, 0xffff0000, v8
	v_lshlrev_b32_e32 v16, 16, v8
	s_waitcnt lgkmcnt(1)
	v_pk_mul_f32 v[12:13], v[12:13], v[16:17]
	v_and_b32_e32 v17, 0xffff0000, v9
	v_lshlrev_b32_e32 v16, 16, v9
	v_pk_mul_f32 v[8:9], v[14:15], v[16:17]
	v_and_b32_e32 v15, 0xffff0000, v10
	v_lshlrev_b32_e32 v14, 16, v10
	s_waitcnt lgkmcnt(0)
	v_pk_mul_f32 v[4:5], v[4:5], v[14:15]
	v_and_b32_e32 v15, 0xffff0000, v11
	v_lshlrev_b32_e32 v14, 16, v11
	v_pk_mul_f32 v[6:7], v[6:7], v[14:15]
	v_cvt_pk_bf16_f32 v7, v6, v7
	v_cvt_pk_bf16_f32 v6, v4, v5
	v_cvt_pk_bf16_f32 v5, v8, v9
	ds_read_b128 v[8:11], v159
	v_cvt_pk_bf16_f32 v4, v12, v13
	global_store_dwordx4 v[24:25], v[4:7], off offset:2048
	ds_read_b128 v[4:7], v159 offset:16
	s_waitcnt vmcnt(3)
	v_and_b32_e32 v13, 0xffff0000, v0
	v_lshlrev_b32_e32 v12, 16, v0
	s_waitcnt lgkmcnt(1)
	v_pk_mul_f32 v[8:9], v[8:9], v[12:13]
	v_and_b32_e32 v13, 0xffff0000, v1
	v_lshlrev_b32_e32 v12, 16, v1
	v_pk_mul_f32 v[0:1], v[10:11], v[12:13]
	v_and_b32_e32 v11, 0xffff0000, v2
	v_lshlrev_b32_e32 v10, 16, v2
	s_waitcnt lgkmcnt(0)
	v_pk_mul_f32 v[4:5], v[4:5], v[10:11]
	v_and_b32_e32 v11, 0xffff0000, v3
	v_lshlrev_b32_e32 v10, 16, v3
	v_pk_mul_f32 v[2:3], v[6:7], v[10:11]
	v_cvt_pk_bf16_f32 v3, v2, v3
	v_cvt_pk_bf16_f32 v2, v4, v5
	v_cvt_pk_bf16_f32 v1, v0, v1
	v_cvt_pk_bf16_f32 v0, v8, v9
	global_store_dwordx4 v[26:27], v[0:3], off offset:2048
	s_cbranch_scc1 .LBB0_624
	v_readlane_b32 s96, v247, 7
	v_readlane_b32 s54, v247, 5
	v_readlane_b32 s97, v247, 8
	v_readlane_b32 s55, v247, 6
